# fused pass-1 step trimmed: two accumulators per dot (one negate-add instead of three adds), v operand loaded with d16_hi into a zeroed register (no shift), s_nop before the MFMA burst dropped
# baseline (speedup 1.0000x reference)
; #define NEXT_ITEM() (MIX ? (int)__builtin_amdgcn_readfirstlane(lane == 0 ? __hip_atomic_fetch_add(qctr, 1u, __ATOMIC_RELAXED, __HIP_MEMORY_SCOPE_AGENT) : 0u) : item + (int)gridDim.x * 8)
; #define SB __builtin_amdgcn_sched_barrier(0)
; #define MKR(ptr) __builtin_amdgcn_make_buffer_rsrc((void*)(ptr), 0, 0x7fffffff, 0x00027000)
; #define LD1(set, s) { const int e_ = min((int)(s), LC - 1) * (int)stp; const unsigned s4_ = ob4 + (unsigned)(e_ * 4), s2_ = ob2 + (unsigned)(e_ * 2); set.w = LDX(rW, s4_); set.a = LDX(rA, s4_); set.b = LDX(rB, s4_); \
;             set.kw = __builtin_amdgcn_raw_buffer_load_b64(rK, lo8, s2_, 0); set.v = __builtin_amdgcn_raw_buffer_load_b16(rV, lo2, s2_, 0); }
; #define TOUCH1(set) asm volatile("" :: "v"(set.w), "v"(set.a), "v"(set.b), "v"(set.kw), "v"(set.v))
; #define ST1(set) { DERIVE_BK(set); float sd[4]; ScanK<0>::dot(S, set.a, sd); ScanK<0>::updS(S, set, -((sd[0] + sd[1]) + (sd[2] + sd[3])), __uint_as_float(set.v << 16)); }
; #define TOUCH1(set) asm volatile("" :: "v"(set.w), "v"(set.a), "v"(set.b))
; template <bool MIX> __device__ __forceinline__ void scan_pass1(const Params& p, int d, float* ldsf) {
;     ...
;     for (int item = MIX ? NEXT_ITEM() : (int)(blockIdx.x * 8 + wid); item < 2 * NS; item = NEXT_ITEM()) {
;         const bool isP = item >= NS; const int idx = isP ? item - NS : item;
;         const int bh = idx / (NC - 1), c = idx - bh * (NC - 1), b = bh >> 4, h = bh & 15;
;         const int t0 = d ? (SEQ - 1 - c * LC) : c * LC;
;         const size_t off0 = ((size_t)(b * SEQ + t0)) * RW + h * 64; const long stp = d ? -(long)RW : (long)RW;
;         const unsigned ob4 = (unsigned)(off0 * 4), ob2 = (unsigned)(off0 * 2);
;         const f32x4 ka4 = *(const f32x4*)(p.k_a + h * 64 + (lane & 15) * 4), c04 = 1.0f - ka4;
;         float S[64]; int ln = lane; asm volatile("" : "+v"(ln));
;     ...
;         const __amdgpu_buffer_rsrc_t rW = MKR(Wd), rA = MKR(A), rB = MKR(Bd), rK = MKR(KB), rV = MKR(V);
;         if (!isP) {
; #pragma unroll
;             for (int i = 0; i < 64; ++i) S[i] = 0.f;
;     ...
;             In1 i0, i1; LD1(i0, 0);
; #pragma unroll 1
;             for (int s = 0; s < LC; s += 2) { TOUCH1(i0); SB; LD1(i1, s + 1); SB; ST1(i0); TOUCH1(i1); SB; LD1(i0, s + 2); SB; ST1(i1); }
;     ...
;         } else {
; #pragma unroll
;             for (int i = 0; i < 64; ++i) S[i] = (ln == i) ? 1.f : 0.f;
.Lmy_p1d0_item:
	s_cmpk_gt_i32 s0, 0x7df
	s_cbranch_scc1 .Lmy_p1d0_end
	s_mul_i32 s86, s0, 2081
	s_lshr_b32 s86, s86, 17
	s_mul_i32 s7, s86, 63
	s_sub_u32 s85, s0, s7
	s_and_b32 s87, s86, 15
	s_lshr_b32 s6, s86, 4
	s_lshl_b32 s6, s6, 14
	s_lshl_b32 s7, s85, 8
	s_add_u32 s6, s6, s7
	s_lshl_b32 s6, s6, 10
	s_lshl_b32 s7, s87, 6
	s_add_u32 s84, s6, s7
	s_lshl_b32 s72, s84, 2
	s_lshl_b32 s76, s84, 1
	s_lshl_b32 s6, s86, 6
	s_add_u32 s6, s6, s85
	s_lshl_b32 s6, s6, 14
	s_add_u32 s7, s6, 0x15800000
	s_add_u32 s90, s56, s7
	s_addc_u32 s91, s57, 0
	s_add_u32 s7, s6, 0x13800000
	s_add_u32 s92, s56, s7
	s_addc_u32 s93, s57, 0
	s_lshl_b32 s8, s87, 8
	s_add_u32 s4, s42, s8
	s_addc_u32 s5, s43, 0
	v_and_b32_e32 v129, 15, v254
	v_lshlrev_b32_e32 v130, 4, v129
	global_load_dwordx4 v[216:219], v130, s[4:5]
	v_mov_b32_e32 v174, 0
	v_mov_b32_e32 v190, 0
	v_mov_b32_e32 v206, 0
	buffer_load_dwordx4 v[160:163], v235, s[64:67], s72 offen
	buffer_load_dwordx4 v[164:167], v250, s[64:67], s72 offen
	buffer_load_dwordx4 v[168:171], v251, s[64:67], s72 offen
	buffer_load_dwordx2 v[172:173], v252, s[64:67], s76 offen
	buffer_load_short_d16_hi v174, v253, s[64:67], s76 offen
	s_add_u32 s72, s72, 0x1000
	s_add_u32 s76, s76, 0x800
	buffer_load_dwordx4 v[176:179], v235, s[64:67], s72 offen
	buffer_load_dwordx4 v[180:183], v250, s[64:67], s72 offen
	buffer_load_dwordx4 v[184:187], v251, s[64:67], s72 offen
	buffer_load_dwordx2 v[188:189], v252, s[64:67], s76 offen
	buffer_load_short_d16_hi v190, v253, s[64:67], s76 offen
	s_add_u32 s72, s72, 0x1000
	s_add_u32 s76, s76, 0x800
	v_and_b32_e32 v128, 63, v254
	v_mov_b32_e32 v129, 1.0
	v_mov_b32_e32 v0, 0
	v_mov_b32_e32 v1, 0
	v_mov_b32_e32 v2, 0
	v_mov_b32_e32 v3, 0
	v_mov_b32_e32 v4, 0
	v_mov_b32_e32 v5, 0
	v_mov_b32_e32 v6, 0
	v_mov_b32_e32 v7, 0
	v_mov_b32_e32 v8, 0
	v_mov_b32_e32 v9, 0
	v_mov_b32_e32 v10, 0
	v_mov_b32_e32 v11, 0
	v_mov_b32_e32 v12, 0
	v_mov_b32_e32 v13, 0
	v_mov_b32_e32 v14, 0
	v_mov_b32_e32 v15, 0
	v_mov_b32_e32 v16, 0
	v_mov_b32_e32 v17, 0
	v_mov_b32_e32 v18, 0
	v_mov_b32_e32 v19, 0
	v_mov_b32_e32 v20, 0
	v_mov_b32_e32 v21, 0
	v_mov_b32_e32 v22, 0
	v_mov_b32_e32 v23, 0
	v_mov_b32_e32 v24, 0
	v_mov_b32_e32 v25, 0
	v_mov_b32_e32 v26, 0
	v_mov_b32_e32 v27, 0
	v_mov_b32_e32 v28, 0
	v_mov_b32_e32 v29, 0
	v_mov_b32_e32 v30, 0
	v_mov_b32_e32 v31, 0
	v_mov_b32_e32 v32, 0
	v_mov_b32_e32 v33, 0
	v_mov_b32_e32 v34, 0
	v_mov_b32_e32 v35, 0
	v_mov_b32_e32 v36, 0
	v_mov_b32_e32 v37, 0
	v_mov_b32_e32 v38, 0
	v_mov_b32_e32 v39, 0
	v_mov_b32_e32 v40, 0
	v_mov_b32_e32 v41, 0
	v_mov_b32_e32 v42, 0
	v_mov_b32_e32 v43, 0
	v_mov_b32_e32 v44, 0
	v_mov_b32_e32 v45, 0
	v_mov_b32_e32 v46, 0
	v_mov_b32_e32 v47, 0
	v_mov_b32_e32 v48, 0
	v_mov_b32_e32 v49, 0
	v_mov_b32_e32 v50, 0
	v_mov_b32_e32 v51, 0
	v_mov_b32_e32 v52, 0
	v_mov_b32_e32 v53, 0
	v_mov_b32_e32 v54, 0
	v_mov_b32_e32 v55, 0
	v_mov_b32_e32 v56, 0
	v_mov_b32_e32 v57, 0
	v_mov_b32_e32 v58, 0
	v_mov_b32_e32 v59, 0
	v_mov_b32_e32 v60, 0
	v_mov_b32_e32 v61, 0
	v_mov_b32_e32 v62, 0
	v_mov_b32_e32 v63, 0
	v_cmp_eq_u32_e32 vcc, 0, v128
	s_nop 1
	v_cndmask_b32_e32 v64, 0, v129, vcc
	v_cmp_eq_u32_e32 vcc, 1, v128
	s_nop 1
	v_cndmask_b32_e32 v65, 0, v129, vcc
	v_cmp_eq_u32_e32 vcc, 2, v128
	s_nop 1
	v_cndmask_b32_e32 v66, 0, v129, vcc
	v_cmp_eq_u32_e32 vcc, 3, v128
	s_nop 1
	v_cndmask_b32_e32 v67, 0, v129, vcc
	v_cmp_eq_u32_e32 vcc, 4, v128
	s_nop 1
	v_cndmask_b32_e32 v68, 0, v129, vcc
	v_cmp_eq_u32_e32 vcc, 5, v128
	s_nop 1
	v_cndmask_b32_e32 v69, 0, v129, vcc
	v_cmp_eq_u32_e32 vcc, 6, v128
	s_nop 1
	v_cndmask_b32_e32 v70, 0, v129, vcc
	v_cmp_eq_u32_e32 vcc, 7, v128
	s_nop 1
	v_cndmask_b32_e32 v71, 0, v129, vcc
	v_cmp_eq_u32_e32 vcc, 8, v128
	s_nop 1
	v_cndmask_b32_e32 v72, 0, v129, vcc
	v_cmp_eq_u32_e32 vcc, 9, v128
	s_nop 1
	v_cndmask_b32_e32 v73, 0, v129, vcc
	v_cmp_eq_u32_e32 vcc, 10, v128
	s_nop 1
	v_cndmask_b32_e32 v74, 0, v129, vcc
	v_cmp_eq_u32_e32 vcc, 11, v128
	s_nop 1
	v_cndmask_b32_e32 v75, 0, v129, vcc
	v_cmp_eq_u32_e32 vcc, 12, v128
	s_nop 1
	v_cndmask_b32_e32 v76, 0, v129, vcc
	v_cmp_eq_u32_e32 vcc, 13, v128
	s_nop 1
	v_cndmask_b32_e32 v77, 0, v129, vcc
	v_cmp_eq_u32_e32 vcc, 14, v128
	s_nop 1
	v_cndmask_b32_e32 v78, 0, v129, vcc
; template <bool MIX> __device__ __forceinline__ void scan_pass1(const Params& p, int d, float* ldsf) {
;     ...
;         const f32x4 ka4 = *(const f32x4*)(p.k_a + h * 64 + (lane & 15) * 4), c04 = 1.0f - ka4;
;     ...
; #pragma unroll
;             for (int i = 0; i < 64; ++i) S[i] = (ln == i) ? 1.f : 0.f;
	v_cmp_eq_u32_e32 vcc, 15, v128
	s_nop 1
	v_cndmask_b32_e32 v79, 0, v129, vcc
	v_cmp_eq_u32_e32 vcc, 16, v128
	s_nop 1
	v_cndmask_b32_e32 v80, 0, v129, vcc
	v_cmp_eq_u32_e32 vcc, 17, v128
	s_nop 1
	v_cndmask_b32_e32 v81, 0, v129, vcc
	v_cmp_eq_u32_e32 vcc, 18, v128
	s_nop 1
	v_cndmask_b32_e32 v82, 0, v129, vcc
	v_cmp_eq_u32_e32 vcc, 19, v128
	s_nop 1
	v_cndmask_b32_e32 v83, 0, v129, vcc
	v_cmp_eq_u32_e32 vcc, 20, v128
	s_nop 1
	v_cndmask_b32_e32 v84, 0, v129, vcc
	v_cmp_eq_u32_e32 vcc, 21, v128
	s_nop 1
	v_cndmask_b32_e32 v85, 0, v129, vcc
	v_cmp_eq_u32_e32 vcc, 22, v128
	s_nop 1
	v_cndmask_b32_e32 v86, 0, v129, vcc
	v_cmp_eq_u32_e32 vcc, 23, v128
	s_nop 1
	v_cndmask_b32_e32 v87, 0, v129, vcc
	v_cmp_eq_u32_e32 vcc, 24, v128
	s_nop 1
	v_cndmask_b32_e32 v88, 0, v129, vcc
	v_cmp_eq_u32_e32 vcc, 25, v128
	s_nop 1
	v_cndmask_b32_e32 v89, 0, v129, vcc
	v_cmp_eq_u32_e32 vcc, 26, v128
	s_nop 1
	v_cndmask_b32_e32 v90, 0, v129, vcc
	v_cmp_eq_u32_e32 vcc, 27, v128
	s_nop 1
	v_cndmask_b32_e32 v91, 0, v129, vcc
	v_cmp_eq_u32_e32 vcc, 28, v128
	s_nop 1
	v_cndmask_b32_e32 v92, 0, v129, vcc
	v_cmp_eq_u32_e32 vcc, 29, v128
	s_nop 1
	v_cndmask_b32_e32 v93, 0, v129, vcc
	v_cmp_eq_u32_e32 vcc, 30, v128
	s_nop 1
	v_cndmask_b32_e32 v94, 0, v129, vcc
	v_cmp_eq_u32_e32 vcc, 31, v128
	s_nop 1
	v_cndmask_b32_e32 v95, 0, v129, vcc
	v_cmp_eq_u32_e32 vcc, 32, v128
	s_nop 1
	v_cndmask_b32_e32 v96, 0, v129, vcc
	v_cmp_eq_u32_e32 vcc, 33, v128
	s_nop 1
	v_cndmask_b32_e32 v97, 0, v129, vcc
	v_cmp_eq_u32_e32 vcc, 34, v128
	s_nop 1
	v_cndmask_b32_e32 v98, 0, v129, vcc
	v_cmp_eq_u32_e32 vcc, 35, v128
	s_nop 1
	v_cndmask_b32_e32 v99, 0, v129, vcc
	v_cmp_eq_u32_e32 vcc, 36, v128
	s_nop 1
	v_cndmask_b32_e32 v100, 0, v129, vcc
	v_cmp_eq_u32_e32 vcc, 37, v128
	s_nop 1
	v_cndmask_b32_e32 v101, 0, v129, vcc
	v_cmp_eq_u32_e32 vcc, 38, v128
	s_nop 1
	v_cndmask_b32_e32 v102, 0, v129, vcc
	v_cmp_eq_u32_e32 vcc, 39, v128
	s_nop 1
	v_cndmask_b32_e32 v103, 0, v129, vcc
	v_cmp_eq_u32_e32 vcc, 40, v128
	s_nop 1
	v_cndmask_b32_e32 v104, 0, v129, vcc
	v_cmp_eq_u32_e32 vcc, 41, v128
	s_nop 1
	v_cndmask_b32_e32 v105, 0, v129, vcc
	v_cmp_eq_u32_e32 vcc, 42, v128
	s_nop 1
	v_cndmask_b32_e32 v106, 0, v129, vcc
	v_cmp_eq_u32_e32 vcc, 43, v128
	s_nop 1
	v_cndmask_b32_e32 v107, 0, v129, vcc
	v_cmp_eq_u32_e32 vcc, 44, v128
	s_nop 1
	v_cndmask_b32_e32 v108, 0, v129, vcc
	v_cmp_eq_u32_e32 vcc, 45, v128
	s_nop 1
	v_cndmask_b32_e32 v109, 0, v129, vcc
	v_cmp_eq_u32_e32 vcc, 46, v128
	s_nop 1
	v_cndmask_b32_e32 v110, 0, v129, vcc
	v_cmp_eq_u32_e32 vcc, 47, v128
	s_nop 1
	v_cndmask_b32_e32 v111, 0, v129, vcc
	v_cmp_eq_u32_e32 vcc, 48, v128
	s_nop 1
	v_cndmask_b32_e32 v112, 0, v129, vcc
	v_cmp_eq_u32_e32 vcc, 49, v128
	s_nop 1
	v_cndmask_b32_e32 v113, 0, v129, vcc
	v_cmp_eq_u32_e32 vcc, 50, v128
	s_nop 1
	v_cndmask_b32_e32 v114, 0, v129, vcc
	v_cmp_eq_u32_e32 vcc, 51, v128
	s_nop 1
	v_cndmask_b32_e32 v115, 0, v129, vcc
	v_cmp_eq_u32_e32 vcc, 52, v128
	s_nop 1
	v_cndmask_b32_e32 v116, 0, v129, vcc
	v_cmp_eq_u32_e32 vcc, 53, v128
	s_nop 1
	v_cndmask_b32_e32 v117, 0, v129, vcc
	v_cmp_eq_u32_e32 vcc, 54, v128
	s_nop 1
	v_cndmask_b32_e32 v118, 0, v129, vcc
	v_cmp_eq_u32_e32 vcc, 55, v128
	s_nop 1
	v_cndmask_b32_e32 v119, 0, v129, vcc
	v_cmp_eq_u32_e32 vcc, 56, v128
	s_nop 1
	v_cndmask_b32_e32 v120, 0, v129, vcc
	v_cmp_eq_u32_e32 vcc, 57, v128
	s_nop 1
	v_cndmask_b32_e32 v121, 0, v129, vcc
	v_cmp_eq_u32_e32 vcc, 58, v128
	s_nop 1
	v_cndmask_b32_e32 v122, 0, v129, vcc
	v_cmp_eq_u32_e32 vcc, 59, v128
	s_nop 1
	v_cndmask_b32_e32 v123, 0, v129, vcc
	v_cmp_eq_u32_e32 vcc, 60, v128
	s_nop 1
	v_cndmask_b32_e32 v124, 0, v129, vcc
	v_cmp_eq_u32_e32 vcc, 61, v128
	s_nop 1
	v_cndmask_b32_e32 v125, 0, v129, vcc
	v_cmp_eq_u32_e32 vcc, 62, v128
	s_nop 1
	v_cndmask_b32_e32 v126, 0, v129, vcc
	v_cmp_eq_u32_e32 vcc, 63, v128
	s_nop 1
	v_cndmask_b32_e32 v127, 0, v129, vcc
	s_waitcnt vmcnt(0)
	v_sub_f32_e32 v220, 1.0, v216
	v_sub_f32_e32 v221, 1.0, v217
	v_sub_f32_e32 v222, 1.0, v218
	v_sub_f32_e32 v223, 1.0, v219
	v_mov_b32_e32 v236, 1.0
	v_mov_b32_e32 v237, 1.0
	v_mov_b32_e32 v238, 1.0
	v_mov_b32_e32 v239, 1.0
	s_movk_i32 s83, 85
	s_movk_i32 s9, 11
	s_branch .Lmy_p1d0_loop

; #define SB __builtin_amdgcn_sched_barrier(0)
; #define LD1(set, s) { const int e_ = min((int)(s), LC - 1) * (int)stp; const unsigned s4_ = ob4 + (unsigned)(e_ * 4), s2_ = ob2 + (unsigned)(e_ * 2); set.w = LDX(rW, s4_); set.a = LDX(rA, s4_); set.b = LDX(rB, s4_); \
;             set.kw = __builtin_amdgcn_raw_buffer_load_b64(rK, lo8, s2_, 0); set.v = __builtin_amdgcn_raw_buffer_load_b16(rV, lo2, s2_, 0); }
; #define TOUCH1(set) asm volatile("" :: "v"(set.w), "v"(set.a), "v"(set.b), "v"(set.kw), "v"(set.v))
; #define ST1(set) { DERIVE_BK(set); float sd[4]; ScanK<0>::dot(S, set.a, sd); ScanK<0>::updS(S, set, -((sd[0] + sd[1]) + (sd[2] + sd[3])), __uint_as_float(set.v << 16)); }
; #define LD1(set, s) { const int e_ = min((int)(s), LC - 1) * (int)stp; const unsigned s4_ = ob4 + (unsigned)(e_ * 4); set.w = LDX(rW, s4_); set.a = LDX(rA, s4_); set.b = LDX(rB, s4_); }
; #define TOUCH1(set) asm volatile("" :: "v"(set.w), "v"(set.a), "v"(set.b))
; #define ST1(set) { DERIVE_B(set); float sd[4]; ScanK<0>::dot(S, set.a, sd); ScanK<0>::updP(S, set, -((sd[0] + sd[1]) + (sd[2] + sd[3]))); }
; template <bool MIX> __device__ __forceinline__ void scan_pass1(const Params& p, int d, float* ldsf) {
;     ...
;             In1 i0, i1; LD1(i0, 0);
; #pragma unroll 1
;             for (int s = 0; s < LC; s += 2) { TOUCH1(i0); SB; LD1(i1, s + 1); SB; ST1(i0); TOUCH1(i1); SB; LD1(i0, s + 2); SB; ST1(i1); }
.Lmy_p1d0_loop:
	s_waitcnt vmcnt(5)
	buffer_load_dwordx4 v[192:195], v235, s[64:67], s72 offen
	buffer_load_dwordx4 v[196:199], v250, s[64:67], s72 offen
	buffer_load_dwordx4 v[200:203], v251, s[64:67], s72 offen
	buffer_load_dwordx2 v[204:205], v252, s[64:67], s76 offen
	buffer_load_short_d16_hi v206, v253, s[64:67], s76 offen
	s_add_u32 s72, s72, 0x1000
	s_add_u32 s76, s76, 0x800
	v_pk_mul_f32 v[244:245], v[164:165], v[236:237]
	v_pk_mul_f32 v[246:247], v[166:167], v[238:239]
	v_pk_mul_f32 v[236:237], v[236:237], v[160:161]
	v_pk_mul_f32 v[238:239], v[238:239], v[162:163]
	v_pk_fma_f32 v[228:229], v[168:169], v[216:217], v[220:221]
	v_pk_fma_f32 v[230:231], v[170:171], v[218:219], v[222:223]
	v_pk_mul_f32 v[208:209], v[164:165], v[168:169]
	v_pk_mul_f32 v[210:211], v[166:167], v[170:171]
	v_rcp_f32_e32 v240, v236
	v_rcp_f32_e32 v241, v237
	v_rcp_f32_e32 v242, v238
	v_rcp_f32_e32 v243, v239
	v_lshlrev_b32_e32 v212, 16, v172
	v_and_b32_e32 v213, 0xffff0000, v172
	v_lshlrev_b32_e32 v214, 16, v173
	v_and_b32_e32 v215, 0xffff0000, v173
	v_pk_mul_f32 v[212:213], v[212:213], v[228:229]
	v_pk_mul_f32 v[214:215], v[214:215], v[230:231]
	v_pk_mul_f32 v[208:209], v[208:209], v[240:241]
	v_pk_mul_f32 v[210:211], v[210:211], v[242:243]
	v_pk_mul_f32 v[212:213], v[212:213], v[240:241]
	v_pk_mul_f32 v[214:215], v[214:215], v[242:243]
	ds_write2_b32 v248, v208, v209 offset0:0 offset1:16
	ds_write2_b32 v248, v210, v211 offset0:32 offset1:48
	ds_write2_b32 v248, v212, v213 offset0:64 offset1:80
	ds_write2_b32 v248, v214, v215 offset0:96 offset1:112
	ds_read_b128 v[128:131], v249 offset:0
	ds_read_b128 v[132:135], v249 offset:16
	ds_read_b128 v[136:139], v249 offset:32
	ds_read_b128 v[140:143], v249 offset:48
	ds_read_b128 v[144:147], v249 offset:256
	ds_read_b128 v[148:151], v249 offset:272
	ds_read_b128 v[152:155], v249 offset:288
	ds_read_b128 v[156:159], v249 offset:304
	v_mul_f32_dpp v224, v244, v0 row_newbcast:0 row_mask:0xf bank_mask:0xf
	v_mul_f32_dpp v225, v245, v1 row_newbcast:0 row_mask:0xf bank_mask:0xf
	v_fmac_f32_dpp v224, v246, v2 row_newbcast:0 row_mask:0xf bank_mask:0xf
	v_fmac_f32_dpp v225, v247, v3 row_newbcast:0 row_mask:0xf bank_mask:0xf
	v_fmac_f32_dpp v224, v244, v4 row_newbcast:1 row_mask:0xf bank_mask:0xf
	v_fmac_f32_dpp v225, v245, v5 row_newbcast:1 row_mask:0xf bank_mask:0xf
	v_fmac_f32_dpp v224, v246, v6 row_newbcast:1 row_mask:0xf bank_mask:0xf
	v_fmac_f32_dpp v225, v247, v7 row_newbcast:1 row_mask:0xf bank_mask:0xf
	v_fmac_f32_dpp v224, v244, v8 row_newbcast:2 row_mask:0xf bank_mask:0xf
	v_fmac_f32_dpp v225, v245, v9 row_newbcast:2 row_mask:0xf bank_mask:0xf
	v_fmac_f32_dpp v224, v246, v10 row_newbcast:2 row_mask:0xf bank_mask:0xf
	v_fmac_f32_dpp v225, v247, v11 row_newbcast:2 row_mask:0xf bank_mask:0xf
	v_fmac_f32_dpp v224, v244, v12 row_newbcast:3 row_mask:0xf bank_mask:0xf
	v_fmac_f32_dpp v225, v245, v13 row_newbcast:3 row_mask:0xf bank_mask:0xf
	v_fmac_f32_dpp v224, v246, v14 row_newbcast:3 row_mask:0xf bank_mask:0xf
	v_fmac_f32_dpp v225, v247, v15 row_newbcast:3 row_mask:0xf bank_mask:0xf
	v_fmac_f32_dpp v224, v244, v16 row_newbcast:4 row_mask:0xf bank_mask:0xf
	v_fmac_f32_dpp v225, v245, v17 row_newbcast:4 row_mask:0xf bank_mask:0xf
	v_fmac_f32_dpp v224, v246, v18 row_newbcast:4 row_mask:0xf bank_mask:0xf
	v_fmac_f32_dpp v225, v247, v19 row_newbcast:4 row_mask:0xf bank_mask:0xf
	v_fmac_f32_dpp v224, v244, v20 row_newbcast:5 row_mask:0xf bank_mask:0xf
	v_fmac_f32_dpp v225, v245, v21 row_newbcast:5 row_mask:0xf bank_mask:0xf
	v_fmac_f32_dpp v224, v246, v22 row_newbcast:5 row_mask:0xf bank_mask:0xf
	v_fmac_f32_dpp v225, v247, v23 row_newbcast:5 row_mask:0xf bank_mask:0xf
	v_fmac_f32_dpp v224, v244, v24 row_newbcast:6 row_mask:0xf bank_mask:0xf
	v_fmac_f32_dpp v225, v245, v25 row_newbcast:6 row_mask:0xf bank_mask:0xf
	v_fmac_f32_dpp v224, v246, v26 row_newbcast:6 row_mask:0xf bank_mask:0xf
	v_fmac_f32_dpp v225, v247, v27 row_newbcast:6 row_mask:0xf bank_mask:0xf
	v_fmac_f32_dpp v224, v244, v28 row_newbcast:7 row_mask:0xf bank_mask:0xf
	v_fmac_f32_dpp v225, v245, v29 row_newbcast:7 row_mask:0xf bank_mask:0xf
	v_fmac_f32_dpp v224, v246, v30 row_newbcast:7 row_mask:0xf bank_mask:0xf
	v_fmac_f32_dpp v225, v247, v31 row_newbcast:7 row_mask:0xf bank_mask:0xf
	v_fmac_f32_dpp v224, v244, v32 row_newbcast:8 row_mask:0xf bank_mask:0xf
	v_fmac_f32_dpp v225, v245, v33 row_newbcast:8 row_mask:0xf bank_mask:0xf
	v_fmac_f32_dpp v224, v246, v34 row_newbcast:8 row_mask:0xf bank_mask:0xf
	v_fmac_f32_dpp v225, v247, v35 row_newbcast:8 row_mask:0xf bank_mask:0xf
	v_fmac_f32_dpp v224, v244, v36 row_newbcast:9 row_mask:0xf bank_mask:0xf
	v_fmac_f32_dpp v225, v245, v37 row_newbcast:9 row_mask:0xf bank_mask:0xf
	v_fmac_f32_dpp v224, v246, v38 row_newbcast:9 row_mask:0xf bank_mask:0xf
	v_fmac_f32_dpp v225, v247, v39 row_newbcast:9 row_mask:0xf bank_mask:0xf
	v_fmac_f32_dpp v224, v244, v40 row_newbcast:10 row_mask:0xf bank_mask:0xf
	v_fmac_f32_dpp v225, v245, v41 row_newbcast:10 row_mask:0xf bank_mask:0xf
	v_fmac_f32_dpp v224, v246, v42 row_newbcast:10 row_mask:0xf bank_mask:0xf
	v_fmac_f32_dpp v225, v247, v43 row_newbcast:10 row_mask:0xf bank_mask:0xf
	v_fmac_f32_dpp v224, v244, v44 row_newbcast:11 row_mask:0xf bank_mask:0xf
	v_fmac_f32_dpp v225, v245, v45 row_newbcast:11 row_mask:0xf bank_mask:0xf
	v_fmac_f32_dpp v224, v246, v46 row_newbcast:11 row_mask:0xf bank_mask:0xf
	v_fmac_f32_dpp v225, v247, v47 row_newbcast:11 row_mask:0xf bank_mask:0xf
	v_fmac_f32_dpp v224, v244, v48 row_newbcast:12 row_mask:0xf bank_mask:0xf
	v_fmac_f32_dpp v225, v245, v49 row_newbcast:12 row_mask:0xf bank_mask:0xf
	v_fmac_f32_dpp v224, v246, v50 row_newbcast:12 row_mask:0xf bank_mask:0xf
;     static __device__ __forceinline__ void dot(const float (&S)[64], const f32x4& a, float (&s)[4]) {
;         if constexpr (K == 0) {
;             asm volatile("v_mul_f32_dpp %0, %4, %8 row_newbcast:%16" DPPM "v_mul_f32_dpp %1, %5, %9 row_newbcast:%16" DPPM "v_mul_f32_dpp %2, %6, %10 row_newbcast:%16" DPPM "v_mul_f32_dpp %3, %7, %11 row_newbcast:%16" DPPM
;                          "v_fmac_f32_dpp %0, %4, %12 row_newbcast:%17" DPPM "v_fmac_f32_dpp %1, %5, %13 row_newbcast:%17" DPPM "v_fmac_f32_dpp %2, %6, %14 row_newbcast:%17" DPPM "v_fmac_f32_dpp %3, %7, %15 row_newbcast:%17" DPPM
;                          : "=&v"(s[0]), "=&v"(s[1]), "=&v"(s[2]), "=&v"(s[3])
;                          : "v"(a[0]), "v"(a[1]), "v"(a[2]), "v"(a[3]), "v"(S[K]), "v"(S[K + 1]), "v"(S[K + 2]), "v"(S[K + 3]), "v"(S[K + 4]), "v"(S[K + 5]), "v"(S[K + 6]), "v"(S[K + 7]), "n"(N0), "n"(N1));
;         } else
;         asm volatile("v_fmac_f32_dpp %0, %4, %8 row_newbcast:%16" DPPM "v_fmac_f32_dpp %1, %5, %9 row_newbcast:%16" DPPM "v_fmac_f32_dpp %2, %6, %10 row_newbcast:%16" DPPM "v_fmac_f32_dpp %3, %7, %11 row_newbcast:%16" DPPM
;                      "v_fmac_f32_dpp %0, %4, %12 row_newbcast:%17" DPPM "v_fmac_f32_dpp %1, %5, %13 row_newbcast:%17" DPPM "v_fmac_f32_dpp %2, %6, %14 row_newbcast:%17" DPPM "v_fmac_f32_dpp %3, %7, %15 row_newbcast:%17" DPPM
;                      : "+v"(s[0]), "+v"(s[1]), "+v"(s[2]), "+v"(s[3])
;                      : "v"(a[0]), "v"(a[1]), "v"(a[2]), "v"(a[3]), "v"(S[K]), "v"(S[K + 1]), "v"(S[K + 2]), "v"(S[K + 3]), "v"(S[K + 4]), "v"(S[K + 5]), "v"(S[K + 6]), "v"(S[K + 7]), "n"(N0), "n"(N1));
;         if constexpr (K + 8 < 64) ScanK<K + 8>::dot(S, a, s);
	v_fmac_f32_dpp v225, v247, v51 row_newbcast:12 row_mask:0xf bank_mask:0xf
	v_fmac_f32_dpp v224, v244, v52 row_newbcast:13 row_mask:0xf bank_mask:0xf
	v_fmac_f32_dpp v225, v245, v53 row_newbcast:13 row_mask:0xf bank_mask:0xf
	v_fmac_f32_dpp v224, v246, v54 row_newbcast:13 row_mask:0xf bank_mask:0xf
	v_fmac_f32_dpp v225, v247, v55 row_newbcast:13 row_mask:0xf bank_mask:0xf
	v_fmac_f32_dpp v224, v244, v56 row_newbcast:14 row_mask:0xf bank_mask:0xf
	v_fmac_f32_dpp v225, v245, v57 row_newbcast:14 row_mask:0xf bank_mask:0xf
	v_fmac_f32_dpp v224, v246, v58 row_newbcast:14 row_mask:0xf bank_mask:0xf
	v_fmac_f32_dpp v225, v247, v59 row_newbcast:14 row_mask:0xf bank_mask:0xf
	v_fmac_f32_dpp v224, v244, v60 row_newbcast:15 row_mask:0xf bank_mask:0xf
	v_fmac_f32_dpp v225, v245, v61 row_newbcast:15 row_mask:0xf bank_mask:0xf
	v_fmac_f32_dpp v224, v246, v62 row_newbcast:15 row_mask:0xf bank_mask:0xf
	v_fmac_f32_dpp v225, v247, v63 row_newbcast:15 row_mask:0xf bank_mask:0xf
	v_mul_f32_dpp v228, v244, v64 row_newbcast:0 row_mask:0xf bank_mask:0xf
	v_mul_f32_dpp v229, v245, v65 row_newbcast:0 row_mask:0xf bank_mask:0xf
	v_fmac_f32_dpp v228, v246, v66 row_newbcast:0 row_mask:0xf bank_mask:0xf
	v_fmac_f32_dpp v229, v247, v67 row_newbcast:0 row_mask:0xf bank_mask:0xf
	v_fmac_f32_dpp v228, v244, v68 row_newbcast:1 row_mask:0xf bank_mask:0xf
	v_fmac_f32_dpp v229, v245, v69 row_newbcast:1 row_mask:0xf bank_mask:0xf
	v_fmac_f32_dpp v228, v246, v70 row_newbcast:1 row_mask:0xf bank_mask:0xf
	v_fmac_f32_dpp v229, v247, v71 row_newbcast:1 row_mask:0xf bank_mask:0xf
	v_fmac_f32_dpp v228, v244, v72 row_newbcast:2 row_mask:0xf bank_mask:0xf
	v_fmac_f32_dpp v229, v245, v73 row_newbcast:2 row_mask:0xf bank_mask:0xf
	v_fmac_f32_dpp v228, v246, v74 row_newbcast:2 row_mask:0xf bank_mask:0xf
	v_fmac_f32_dpp v229, v247, v75 row_newbcast:2 row_mask:0xf bank_mask:0xf
	v_fmac_f32_dpp v228, v244, v76 row_newbcast:3 row_mask:0xf bank_mask:0xf
	v_fmac_f32_dpp v229, v245, v77 row_newbcast:3 row_mask:0xf bank_mask:0xf
	v_fmac_f32_dpp v228, v246, v78 row_newbcast:3 row_mask:0xf bank_mask:0xf
	v_fmac_f32_dpp v229, v247, v79 row_newbcast:3 row_mask:0xf bank_mask:0xf
	v_fmac_f32_dpp v228, v244, v80 row_newbcast:4 row_mask:0xf bank_mask:0xf
	v_fmac_f32_dpp v229, v245, v81 row_newbcast:4 row_mask:0xf bank_mask:0xf
	v_fmac_f32_dpp v228, v246, v82 row_newbcast:4 row_mask:0xf bank_mask:0xf
	v_fmac_f32_dpp v229, v247, v83 row_newbcast:4 row_mask:0xf bank_mask:0xf
	v_fmac_f32_dpp v228, v244, v84 row_newbcast:5 row_mask:0xf bank_mask:0xf
	v_fmac_f32_dpp v229, v245, v85 row_newbcast:5 row_mask:0xf bank_mask:0xf
	v_fmac_f32_dpp v228, v246, v86 row_newbcast:5 row_mask:0xf bank_mask:0xf
	v_fmac_f32_dpp v229, v247, v87 row_newbcast:5 row_mask:0xf bank_mask:0xf
	v_fmac_f32_dpp v228, v244, v88 row_newbcast:6 row_mask:0xf bank_mask:0xf
	v_fmac_f32_dpp v229, v245, v89 row_newbcast:6 row_mask:0xf bank_mask:0xf
	v_fmac_f32_dpp v228, v246, v90 row_newbcast:6 row_mask:0xf bank_mask:0xf
	v_fmac_f32_dpp v229, v247, v91 row_newbcast:6 row_mask:0xf bank_mask:0xf
	v_fmac_f32_dpp v228, v244, v92 row_newbcast:7 row_mask:0xf bank_mask:0xf
	v_fmac_f32_dpp v229, v245, v93 row_newbcast:7 row_mask:0xf bank_mask:0xf
	v_fmac_f32_dpp v228, v246, v94 row_newbcast:7 row_mask:0xf bank_mask:0xf
	v_fmac_f32_dpp v229, v247, v95 row_newbcast:7 row_mask:0xf bank_mask:0xf
	v_fmac_f32_dpp v228, v244, v96 row_newbcast:8 row_mask:0xf bank_mask:0xf
	v_fmac_f32_dpp v229, v245, v97 row_newbcast:8 row_mask:0xf bank_mask:0xf
	v_fmac_f32_dpp v228, v246, v98 row_newbcast:8 row_mask:0xf bank_mask:0xf
	v_fmac_f32_dpp v229, v247, v99 row_newbcast:8 row_mask:0xf bank_mask:0xf
	v_fmac_f32_dpp v228, v244, v100 row_newbcast:9 row_mask:0xf bank_mask:0xf
	v_fmac_f32_dpp v229, v245, v101 row_newbcast:9 row_mask:0xf bank_mask:0xf
	v_fmac_f32_dpp v228, v246, v102 row_newbcast:9 row_mask:0xf bank_mask:0xf
	v_fmac_f32_dpp v229, v247, v103 row_newbcast:9 row_mask:0xf bank_mask:0xf
	v_fmac_f32_dpp v228, v244, v104 row_newbcast:10 row_mask:0xf bank_mask:0xf
	v_fmac_f32_dpp v229, v245, v105 row_newbcast:10 row_mask:0xf bank_mask:0xf
	v_fmac_f32_dpp v228, v246, v106 row_newbcast:10 row_mask:0xf bank_mask:0xf
	v_fmac_f32_dpp v229, v247, v107 row_newbcast:10 row_mask:0xf bank_mask:0xf
	v_fmac_f32_dpp v228, v244, v108 row_newbcast:11 row_mask:0xf bank_mask:0xf
	v_fmac_f32_dpp v229, v245, v109 row_newbcast:11 row_mask:0xf bank_mask:0xf
	v_fmac_f32_dpp v228, v246, v110 row_newbcast:11 row_mask:0xf bank_mask:0xf
	v_fmac_f32_dpp v229, v247, v111 row_newbcast:11 row_mask:0xf bank_mask:0xf
	v_fmac_f32_dpp v228, v244, v112 row_newbcast:12 row_mask:0xf bank_mask:0xf
	v_fmac_f32_dpp v229, v245, v113 row_newbcast:12 row_mask:0xf bank_mask:0xf
	v_fmac_f32_dpp v228, v246, v114 row_newbcast:12 row_mask:0xf bank_mask:0xf
	v_fmac_f32_dpp v229, v247, v115 row_newbcast:12 row_mask:0xf bank_mask:0xf
	v_fmac_f32_dpp v228, v244, v116 row_newbcast:13 row_mask:0xf bank_mask:0xf
	v_fmac_f32_dpp v229, v245, v117 row_newbcast:13 row_mask:0xf bank_mask:0xf
	v_fmac_f32_dpp v228, v246, v118 row_newbcast:13 row_mask:0xf bank_mask:0xf
	v_fmac_f32_dpp v229, v247, v119 row_newbcast:13 row_mask:0xf bank_mask:0xf
	v_fmac_f32_dpp v228, v244, v120 row_newbcast:14 row_mask:0xf bank_mask:0xf
	v_fmac_f32_dpp v229, v245, v121 row_newbcast:14 row_mask:0xf bank_mask:0xf
	v_fmac_f32_dpp v228, v246, v122 row_newbcast:14 row_mask:0xf bank_mask:0xf
	v_fmac_f32_dpp v229, v247, v123 row_newbcast:14 row_mask:0xf bank_mask:0xf
	v_fmac_f32_dpp v228, v244, v124 row_newbcast:15 row_mask:0xf bank_mask:0xf
	v_fmac_f32_dpp v229, v245, v125 row_newbcast:15 row_mask:0xf bank_mask:0xf
	v_fmac_f32_dpp v228, v246, v126 row_newbcast:15 row_mask:0xf bank_mask:0xf
	v_fmac_f32_dpp v229, v247, v127 row_newbcast:15 row_mask:0xf bank_mask:0xf
	v_sub_f32_e64 v232, -v224, v225
	v_sub_f32_e64 v233, -v228, v229
	s_waitcnt lgkmcnt(0)
;     static __device__ __forceinline__ void updS(float (&S)[64], const In1& in, float sa, float vv) {
;         float t0, t1, t2, t3;
;         asm volatile("v_mul_f32_dpp %0, %8, %21 row_newbcast:%22" DPPM "v_mul_f32_dpp %1, %9, %21 row_newbcast:%22" DPPM "v_mul_f32_dpp %2, %10, %21 row_newbcast:%22" DPPM "v_mul_f32_dpp %3, %11, %21 row_newbcast:%22" DPPM
;                      "v_fmac_f32_dpp %0, %12, %4 row_newbcast:%22" DPPM "v_fmac_f32_dpp %1, %13, %5 row_newbcast:%22" DPPM "v_fmac_f32_dpp %2, %14, %6 row_newbcast:%22" DPPM "v_fmac_f32_dpp %3, %15, %7 row_newbcast:%22" DPPM
;                      "v_fmac_f32_dpp %0, %16, %20 row_newbcast:%22" DPPM "v_fmac_f32_dpp %1, %17, %20 row_newbcast:%22" DPPM "v_fmac_f32_dpp %2, %18, %20 row_newbcast:%22" DPPM "v_fmac_f32_dpp %3, %19, %20 row_newbcast:%22" DPPM
;                      : "=&v"(t0), "=&v"(t1), "=&v"(t2), "=&v"(t3)
;                      : "v"(S[K]), "v"(S[K + 1]), "v"(S[K + 2]), "v"(S[K + 3]), "v"(in.kd[0]), "v"(in.kd[1]), "v"(in.kd[2]), "v"(in.kd[3]), "v"(in.w[0]), "v"(in.w[1]), "v"(in.w[2]), "v"(in.w[3]),
;                        "v"(in.b[0]), "v"(in.b[1]), "v"(in.b[2]), "v"(in.b[3]), "v"(sa), "v"(vv), "n"(N0));
;         S[K] = t0; S[K + 1] = t1; S[K + 2] = t2; S[K + 3] = t3;
;         if constexpr (K + 4 < 64) ScanK<K + 4>::updS(S, in, sa, vv);
;     }
;     static __device__ __forceinline__ void updP(float (&P)[64], const In1& in, float sa) {
;         float u0, u1, u2, u3;
;         asm volatile("v_mul_f32_dpp %0, %8, %4 row_newbcast:%17" DPPM "v_mul_f32_dpp %1, %9, %5 row_newbcast:%17" DPPM "v_mul_f32_dpp %2, %10, %6 row_newbcast:%17" DPPM "v_mul_f32_dpp %3, %11, %7 row_newbcast:%17" DPPM
;                      "v_fmac_f32_dpp %0, %12, %16 row_newbcast:%17" DPPM "v_fmac_f32_dpp %1, %13, %16 row_newbcast:%17" DPPM "v_fmac_f32_dpp %2, %14, %16 row_newbcast:%17" DPPM "v_fmac_f32_dpp %3, %15, %16 row_newbcast:%17" DPPM
;                      : "=&v"(u0), "=&v"(u1), "=&v"(u2), "=&v"(u3)
;                      : "v"(P[K]), "v"(P[K + 1]), "v"(P[K + 2]), "v"(P[K + 3]), "v"(in.w[0]), "v"(in.w[1]), "v"(in.w[2]), "v"(in.w[3]), "v"(in.b[0]), "v"(in.b[1]), "v"(in.b[2]), "v"(in.b[3]), "v"(sa), "n"(N0));
;         P[K] = u0; P[K + 1] = u1; P[K + 2] = u2; P[K + 3] = u3;
;         if constexpr (K + 4 < 64) ScanK<K + 4>::updP(P, in, sa);
;     }
	v_mfma_f32_4x4x1_16b_f32 v[0:3], v128, v232, v[0:3]
	v_mfma_f32_4x4x1_16b_f32 v[4:7], v129, v232, v[4:7]
	v_mfma_f32_4x4x1_16b_f32 v[8:11], v130, v232, v[8:11]
	v_mfma_f32_4x4x1_16b_f32 v[12:15], v131, v232, v[12:15]
	v_mfma_f32_4x4x1_16b_f32 v[16:19], v132, v232, v[16:19]
	v_mfma_f32_4x4x1_16b_f32 v[20:23], v133, v232, v[20:23]
	v_mfma_f32_4x4x1_16b_f32 v[24:27], v134, v232, v[24:27]
	v_mfma_f32_4x4x1_16b_f32 v[28:31], v135, v232, v[28:31]
	v_mfma_f32_4x4x1_16b_f32 v[32:35], v136, v232, v[32:35]
	v_mfma_f32_4x4x1_16b_f32 v[36:39], v137, v232, v[36:39]
	v_mfma_f32_4x4x1_16b_f32 v[40:43], v138, v232, v[40:43]
	v_mfma_f32_4x4x1_16b_f32 v[44:47], v139, v232, v[44:47]
	v_mfma_f32_4x4x1_16b_f32 v[48:51], v140, v232, v[48:51]
	v_mfma_f32_4x4x1_16b_f32 v[52:55], v141, v232, v[52:55]
	v_mfma_f32_4x4x1_16b_f32 v[56:59], v142, v232, v[56:59]
	v_mfma_f32_4x4x1_16b_f32 v[60:63], v143, v232, v[60:63]
	v_mfma_f32_4x4x1_16b_f32 v[0:3], v144, v174, v[0:3]
	v_mfma_f32_4x4x1_16b_f32 v[4:7], v145, v174, v[4:7]
	v_mfma_f32_4x4x1_16b_f32 v[8:11], v146, v174, v[8:11]
	v_mfma_f32_4x4x1_16b_f32 v[12:15], v147, v174, v[12:15]
	v_mfma_f32_4x4x1_16b_f32 v[16:19], v148, v174, v[16:19]
	v_mfma_f32_4x4x1_16b_f32 v[20:23], v149, v174, v[20:23]
	v_mfma_f32_4x4x1_16b_f32 v[24:27], v150, v174, v[24:27]
	v_mfma_f32_4x4x1_16b_f32 v[28:31], v151, v174, v[28:31]
	v_mfma_f32_4x4x1_16b_f32 v[32:35], v152, v174, v[32:35]
	v_mfma_f32_4x4x1_16b_f32 v[36:39], v153, v174, v[36:39]
	v_mfma_f32_4x4x1_16b_f32 v[40:43], v154, v174, v[40:43]
	v_mfma_f32_4x4x1_16b_f32 v[44:47], v155, v174, v[44:47]
	v_mfma_f32_4x4x1_16b_f32 v[48:51], v156, v174, v[48:51]
	v_mfma_f32_4x4x1_16b_f32 v[52:55], v157, v174, v[52:55]
	v_mfma_f32_4x4x1_16b_f32 v[56:59], v158, v174, v[56:59]
	v_mfma_f32_4x4x1_16b_f32 v[60:63], v159, v174, v[60:63]
	v_mfma_f32_4x4x1_16b_f32 v[64:67], v128, v233, v[64:67]
	v_mfma_f32_4x4x1_16b_f32 v[68:71], v129, v233, v[68:71]
	v_mfma_f32_4x4x1_16b_f32 v[72:75], v130, v233, v[72:75]
	v_mfma_f32_4x4x1_16b_f32 v[76:79], v131, v233, v[76:79]
	v_mfma_f32_4x4x1_16b_f32 v[80:83], v132, v233, v[80:83]
	v_mfma_f32_4x4x1_16b_f32 v[84:87], v133, v233, v[84:87]
	v_mfma_f32_4x4x1_16b_f32 v[88:91], v134, v233, v[88:91]
	v_mfma_f32_4x4x1_16b_f32 v[92:95], v135, v233, v[92:95]
	v_mfma_f32_4x4x1_16b_f32 v[96:99], v136, v233, v[96:99]
	v_mfma_f32_4x4x1_16b_f32 v[100:103], v137, v233, v[100:103]
	v_mfma_f32_4x4x1_16b_f32 v[104:107], v138, v233, v[104:107]
	v_mfma_f32_4x4x1_16b_f32 v[108:111], v139, v233, v[108:111]
	v_mfma_f32_4x4x1_16b_f32 v[112:115], v140, v233, v[112:115]
	v_mfma_f32_4x4x1_16b_f32 v[116:119], v141, v233, v[116:119]
	v_mfma_f32_4x4x1_16b_f32 v[120:123], v142, v233, v[120:123]
	v_mfma_f32_4x4x1_16b_f32 v[124:127], v143, v233, v[124:127]
	s_waitcnt vmcnt(5)
	buffer_load_dwordx4 v[160:163], v235, s[64:67], s72 offen
	buffer_load_dwordx4 v[164:167], v250, s[64:67], s72 offen
	buffer_load_dwordx4 v[168:171], v251, s[64:67], s72 offen
	buffer_load_dwordx2 v[172:173], v252, s[64:67], s76 offen
	buffer_load_short_d16_hi v174, v253, s[64:67], s76 offen
	s_add_u32 s72, s72, 0x1000
	s_add_u32 s76, s76, 0x800
	v_pk_mul_f32 v[244:245], v[180:181], v[236:237]
	v_pk_mul_f32 v[246:247], v[182:183], v[238:239]
	v_pk_mul_f32 v[236:237], v[236:237], v[176:177]
	v_pk_mul_f32 v[238:239], v[238:239], v[178:179]
	v_pk_fma_f32 v[228:229], v[184:185], v[216:217], v[220:221]
	v_pk_fma_f32 v[230:231], v[186:187], v[218:219], v[222:223]
	v_pk_mul_f32 v[208:209], v[180:181], v[184:185]
	v_pk_mul_f32 v[210:211], v[182:183], v[186:187]
	v_rcp_f32_e32 v240, v236
	v_rcp_f32_e32 v241, v237
	v_rcp_f32_e32 v242, v238
	v_rcp_f32_e32 v243, v239
	v_lshlrev_b32_e32 v212, 16, v188
	v_and_b32_e32 v213, 0xffff0000, v188
	v_lshlrev_b32_e32 v214, 16, v189
	v_and_b32_e32 v215, 0xffff0000, v189
	v_pk_mul_f32 v[212:213], v[212:213], v[228:229]
	v_pk_mul_f32 v[214:215], v[214:215], v[230:231]
	v_pk_mul_f32 v[208:209], v[208:209], v[240:241]
	v_pk_mul_f32 v[210:211], v[210:211], v[242:243]
	v_pk_mul_f32 v[212:213], v[212:213], v[240:241]
	v_pk_mul_f32 v[214:215], v[214:215], v[242:243]
	ds_write2_b32 v248, v208, v209 offset0:0 offset1:16
	ds_write2_b32 v248, v210, v211 offset0:32 offset1:48
	ds_write2_b32 v248, v212, v213 offset0:64 offset1:80
	ds_write2_b32 v248, v214, v215 offset0:96 offset1:112
	ds_read_b128 v[128:131], v249 offset:0
	ds_read_b128 v[132:135], v249 offset:16
	ds_read_b128 v[136:139], v249 offset:32
	ds_read_b128 v[140:143], v249 offset:48
	ds_read_b128 v[144:147], v249 offset:256
	ds_read_b128 v[148:151], v249 offset:272
	ds_read_b128 v[152:155], v249 offset:288
	ds_read_b128 v[156:159], v249 offset:304
	v_mul_f32_dpp v224, v244, v0 row_newbcast:0 row_mask:0xf bank_mask:0xf
	v_mul_f32_dpp v225, v245, v1 row_newbcast:0 row_mask:0xf bank_mask:0xf
	v_fmac_f32_dpp v224, v246, v2 row_newbcast:0 row_mask:0xf bank_mask:0xf
	v_fmac_f32_dpp v225, v247, v3 row_newbcast:0 row_mask:0xf bank_mask:0xf
	v_fmac_f32_dpp v224, v244, v4 row_newbcast:1 row_mask:0xf bank_mask:0xf
	v_fmac_f32_dpp v225, v245, v5 row_newbcast:1 row_mask:0xf bank_mask:0xf
	v_fmac_f32_dpp v224, v246, v6 row_newbcast:1 row_mask:0xf bank_mask:0xf
	v_fmac_f32_dpp v225, v247, v7 row_newbcast:1 row_mask:0xf bank_mask:0xf
	v_fmac_f32_dpp v224, v244, v8 row_newbcast:2 row_mask:0xf bank_mask:0xf
	v_fmac_f32_dpp v225, v245, v9 row_newbcast:2 row_mask:0xf bank_mask:0xf
	v_fmac_f32_dpp v224, v246, v10 row_newbcast:2 row_mask:0xf bank_mask:0xf
	v_fmac_f32_dpp v225, v247, v11 row_newbcast:2 row_mask:0xf bank_mask:0xf
	v_fmac_f32_dpp v224, v244, v12 row_newbcast:3 row_mask:0xf bank_mask:0xf
	v_fmac_f32_dpp v225, v245, v13 row_newbcast:3 row_mask:0xf bank_mask:0xf
;     static __device__ __forceinline__ void dot(const float (&S)[64], const f32x4& a, float (&s)[4]) {
;         if constexpr (K == 0) {
;             asm volatile("v_mul_f32_dpp %0, %4, %8 row_newbcast:%16" DPPM "v_mul_f32_dpp %1, %5, %9 row_newbcast:%16" DPPM "v_mul_f32_dpp %2, %6, %10 row_newbcast:%16" DPPM "v_mul_f32_dpp %3, %7, %11 row_newbcast:%16" DPPM
;                          "v_fmac_f32_dpp %0, %4, %12 row_newbcast:%17" DPPM "v_fmac_f32_dpp %1, %5, %13 row_newbcast:%17" DPPM "v_fmac_f32_dpp %2, %6, %14 row_newbcast:%17" DPPM "v_fmac_f32_dpp %3, %7, %15 row_newbcast:%17" DPPM
;                          : "=&v"(s[0]), "=&v"(s[1]), "=&v"(s[2]), "=&v"(s[3])
;                          : "v"(a[0]), "v"(a[1]), "v"(a[2]), "v"(a[3]), "v"(S[K]), "v"(S[K + 1]), "v"(S[K + 2]), "v"(S[K + 3]), "v"(S[K + 4]), "v"(S[K + 5]), "v"(S[K + 6]), "v"(S[K + 7]), "n"(N0), "n"(N1));
;         } else
;         asm volatile("v_fmac_f32_dpp %0, %4, %8 row_newbcast:%16" DPPM "v_fmac_f32_dpp %1, %5, %9 row_newbcast:%16" DPPM "v_fmac_f32_dpp %2, %6, %10 row_newbcast:%16" DPPM "v_fmac_f32_dpp %3, %7, %11 row_newbcast:%16" DPPM
;                      "v_fmac_f32_dpp %0, %4, %12 row_newbcast:%17" DPPM "v_fmac_f32_dpp %1, %5, %13 row_newbcast:%17" DPPM "v_fmac_f32_dpp %2, %6, %14 row_newbcast:%17" DPPM "v_fmac_f32_dpp %3, %7, %15 row_newbcast:%17" DPPM
;                      : "+v"(s[0]), "+v"(s[1]), "+v"(s[2]), "+v"(s[3])
;                      : "v"(a[0]), "v"(a[1]), "v"(a[2]), "v"(a[3]), "v"(S[K]), "v"(S[K + 1]), "v"(S[K + 2]), "v"(S[K + 3]), "v"(S[K + 4]), "v"(S[K + 5]), "v"(S[K + 6]), "v"(S[K + 7]), "n"(N0), "n"(N1));
;         if constexpr (K + 8 < 64) ScanK<K + 8>::dot(S, a, s);
	v_fmac_f32_dpp v224, v246, v14 row_newbcast:3 row_mask:0xf bank_mask:0xf
	v_fmac_f32_dpp v225, v247, v15 row_newbcast:3 row_mask:0xf bank_mask:0xf
	v_fmac_f32_dpp v224, v244, v16 row_newbcast:4 row_mask:0xf bank_mask:0xf
	v_fmac_f32_dpp v225, v245, v17 row_newbcast:4 row_mask:0xf bank_mask:0xf
	v_fmac_f32_dpp v224, v246, v18 row_newbcast:4 row_mask:0xf bank_mask:0xf
	v_fmac_f32_dpp v225, v247, v19 row_newbcast:4 row_mask:0xf bank_mask:0xf
	v_fmac_f32_dpp v224, v244, v20 row_newbcast:5 row_mask:0xf bank_mask:0xf
	v_fmac_f32_dpp v225, v245, v21 row_newbcast:5 row_mask:0xf bank_mask:0xf
	v_fmac_f32_dpp v224, v246, v22 row_newbcast:5 row_mask:0xf bank_mask:0xf
	v_fmac_f32_dpp v225, v247, v23 row_newbcast:5 row_mask:0xf bank_mask:0xf
	v_fmac_f32_dpp v224, v244, v24 row_newbcast:6 row_mask:0xf bank_mask:0xf
	v_fmac_f32_dpp v225, v245, v25 row_newbcast:6 row_mask:0xf bank_mask:0xf
	v_fmac_f32_dpp v224, v246, v26 row_newbcast:6 row_mask:0xf bank_mask:0xf
	v_fmac_f32_dpp v225, v247, v27 row_newbcast:6 row_mask:0xf bank_mask:0xf
	v_fmac_f32_dpp v224, v244, v28 row_newbcast:7 row_mask:0xf bank_mask:0xf
	v_fmac_f32_dpp v225, v245, v29 row_newbcast:7 row_mask:0xf bank_mask:0xf
	v_fmac_f32_dpp v224, v246, v30 row_newbcast:7 row_mask:0xf bank_mask:0xf
	v_fmac_f32_dpp v225, v247, v31 row_newbcast:7 row_mask:0xf bank_mask:0xf
	v_fmac_f32_dpp v224, v244, v32 row_newbcast:8 row_mask:0xf bank_mask:0xf
	v_fmac_f32_dpp v225, v245, v33 row_newbcast:8 row_mask:0xf bank_mask:0xf
	v_fmac_f32_dpp v224, v246, v34 row_newbcast:8 row_mask:0xf bank_mask:0xf
	v_fmac_f32_dpp v225, v247, v35 row_newbcast:8 row_mask:0xf bank_mask:0xf
	v_fmac_f32_dpp v224, v244, v36 row_newbcast:9 row_mask:0xf bank_mask:0xf
	v_fmac_f32_dpp v225, v245, v37 row_newbcast:9 row_mask:0xf bank_mask:0xf
	v_fmac_f32_dpp v224, v246, v38 row_newbcast:9 row_mask:0xf bank_mask:0xf
	v_fmac_f32_dpp v225, v247, v39 row_newbcast:9 row_mask:0xf bank_mask:0xf
	v_fmac_f32_dpp v224, v244, v40 row_newbcast:10 row_mask:0xf bank_mask:0xf
	v_fmac_f32_dpp v225, v245, v41 row_newbcast:10 row_mask:0xf bank_mask:0xf
	v_fmac_f32_dpp v224, v246, v42 row_newbcast:10 row_mask:0xf bank_mask:0xf
	v_fmac_f32_dpp v225, v247, v43 row_newbcast:10 row_mask:0xf bank_mask:0xf
	v_fmac_f32_dpp v224, v244, v44 row_newbcast:11 row_mask:0xf bank_mask:0xf
	v_fmac_f32_dpp v225, v245, v45 row_newbcast:11 row_mask:0xf bank_mask:0xf
	v_fmac_f32_dpp v224, v246, v46 row_newbcast:11 row_mask:0xf bank_mask:0xf
	v_fmac_f32_dpp v225, v247, v47 row_newbcast:11 row_mask:0xf bank_mask:0xf
	v_fmac_f32_dpp v224, v244, v48 row_newbcast:12 row_mask:0xf bank_mask:0xf
	v_fmac_f32_dpp v225, v245, v49 row_newbcast:12 row_mask:0xf bank_mask:0xf
	v_fmac_f32_dpp v224, v246, v50 row_newbcast:12 row_mask:0xf bank_mask:0xf
	v_fmac_f32_dpp v225, v247, v51 row_newbcast:12 row_mask:0xf bank_mask:0xf
	v_fmac_f32_dpp v224, v244, v52 row_newbcast:13 row_mask:0xf bank_mask:0xf
	v_fmac_f32_dpp v225, v245, v53 row_newbcast:13 row_mask:0xf bank_mask:0xf
	v_fmac_f32_dpp v224, v246, v54 row_newbcast:13 row_mask:0xf bank_mask:0xf
	v_fmac_f32_dpp v225, v247, v55 row_newbcast:13 row_mask:0xf bank_mask:0xf
	v_fmac_f32_dpp v224, v244, v56 row_newbcast:14 row_mask:0xf bank_mask:0xf
	v_fmac_f32_dpp v225, v245, v57 row_newbcast:14 row_mask:0xf bank_mask:0xf
	v_fmac_f32_dpp v224, v246, v58 row_newbcast:14 row_mask:0xf bank_mask:0xf
	v_fmac_f32_dpp v225, v247, v59 row_newbcast:14 row_mask:0xf bank_mask:0xf
	v_fmac_f32_dpp v224, v244, v60 row_newbcast:15 row_mask:0xf bank_mask:0xf
	v_fmac_f32_dpp v225, v245, v61 row_newbcast:15 row_mask:0xf bank_mask:0xf
	v_fmac_f32_dpp v224, v246, v62 row_newbcast:15 row_mask:0xf bank_mask:0xf
	v_fmac_f32_dpp v225, v247, v63 row_newbcast:15 row_mask:0xf bank_mask:0xf
	v_mul_f32_dpp v228, v244, v64 row_newbcast:0 row_mask:0xf bank_mask:0xf
	v_mul_f32_dpp v229, v245, v65 row_newbcast:0 row_mask:0xf bank_mask:0xf
	v_fmac_f32_dpp v228, v246, v66 row_newbcast:0 row_mask:0xf bank_mask:0xf
	v_fmac_f32_dpp v229, v247, v67 row_newbcast:0 row_mask:0xf bank_mask:0xf
	v_fmac_f32_dpp v228, v244, v68 row_newbcast:1 row_mask:0xf bank_mask:0xf
	v_fmac_f32_dpp v229, v245, v69 row_newbcast:1 row_mask:0xf bank_mask:0xf
	v_fmac_f32_dpp v228, v246, v70 row_newbcast:1 row_mask:0xf bank_mask:0xf
	v_fmac_f32_dpp v229, v247, v71 row_newbcast:1 row_mask:0xf bank_mask:0xf
	v_fmac_f32_dpp v228, v244, v72 row_newbcast:2 row_mask:0xf bank_mask:0xf
	v_fmac_f32_dpp v229, v245, v73 row_newbcast:2 row_mask:0xf bank_mask:0xf
	v_fmac_f32_dpp v228, v246, v74 row_newbcast:2 row_mask:0xf bank_mask:0xf
	v_fmac_f32_dpp v229, v247, v75 row_newbcast:2 row_mask:0xf bank_mask:0xf
	v_fmac_f32_dpp v228, v244, v76 row_newbcast:3 row_mask:0xf bank_mask:0xf
	v_fmac_f32_dpp v229, v245, v77 row_newbcast:3 row_mask:0xf bank_mask:0xf
	v_fmac_f32_dpp v228, v246, v78 row_newbcast:3 row_mask:0xf bank_mask:0xf
	v_fmac_f32_dpp v229, v247, v79 row_newbcast:3 row_mask:0xf bank_mask:0xf
	v_fmac_f32_dpp v228, v244, v80 row_newbcast:4 row_mask:0xf bank_mask:0xf
	v_fmac_f32_dpp v229, v245, v81 row_newbcast:4 row_mask:0xf bank_mask:0xf
	v_fmac_f32_dpp v228, v246, v82 row_newbcast:4 row_mask:0xf bank_mask:0xf
	v_fmac_f32_dpp v229, v247, v83 row_newbcast:4 row_mask:0xf bank_mask:0xf
	v_fmac_f32_dpp v228, v244, v84 row_newbcast:5 row_mask:0xf bank_mask:0xf
	v_fmac_f32_dpp v229, v245, v85 row_newbcast:5 row_mask:0xf bank_mask:0xf
	v_fmac_f32_dpp v228, v246, v86 row_newbcast:5 row_mask:0xf bank_mask:0xf
	v_fmac_f32_dpp v229, v247, v87 row_newbcast:5 row_mask:0xf bank_mask:0xf
	v_fmac_f32_dpp v228, v244, v88 row_newbcast:6 row_mask:0xf bank_mask:0xf
	v_fmac_f32_dpp v229, v245, v89 row_newbcast:6 row_mask:0xf bank_mask:0xf
;     static __device__ __forceinline__ void dot(const float (&S)[64], const f32x4& a, float (&s)[4]) {
;         if constexpr (K == 0) {
;             asm volatile("v_mul_f32_dpp %0, %4, %8 row_newbcast:%16" DPPM "v_mul_f32_dpp %1, %5, %9 row_newbcast:%16" DPPM "v_mul_f32_dpp %2, %6, %10 row_newbcast:%16" DPPM "v_mul_f32_dpp %3, %7, %11 row_newbcast:%16" DPPM
;                          "v_fmac_f32_dpp %0, %4, %12 row_newbcast:%17" DPPM "v_fmac_f32_dpp %1, %5, %13 row_newbcast:%17" DPPM "v_fmac_f32_dpp %2, %6, %14 row_newbcast:%17" DPPM "v_fmac_f32_dpp %3, %7, %15 row_newbcast:%17" DPPM
;                          : "=&v"(s[0]), "=&v"(s[1]), "=&v"(s[2]), "=&v"(s[3])
;                          : "v"(a[0]), "v"(a[1]), "v"(a[2]), "v"(a[3]), "v"(S[K]), "v"(S[K + 1]), "v"(S[K + 2]), "v"(S[K + 3]), "v"(S[K + 4]), "v"(S[K + 5]), "v"(S[K + 6]), "v"(S[K + 7]), "n"(N0), "n"(N1));
;         } else
;         asm volatile("v_fmac_f32_dpp %0, %4, %8 row_newbcast:%16" DPPM "v_fmac_f32_dpp %1, %5, %9 row_newbcast:%16" DPPM "v_fmac_f32_dpp %2, %6, %10 row_newbcast:%16" DPPM "v_fmac_f32_dpp %3, %7, %11 row_newbcast:%16" DPPM
;                      "v_fmac_f32_dpp %0, %4, %12 row_newbcast:%17" DPPM "v_fmac_f32_dpp %1, %5, %13 row_newbcast:%17" DPPM "v_fmac_f32_dpp %2, %6, %14 row_newbcast:%17" DPPM "v_fmac_f32_dpp %3, %7, %15 row_newbcast:%17" DPPM
;                      : "+v"(s[0]), "+v"(s[1]), "+v"(s[2]), "+v"(s[3])
;                      : "v"(a[0]), "v"(a[1]), "v"(a[2]), "v"(a[3]), "v"(S[K]), "v"(S[K + 1]), "v"(S[K + 2]), "v"(S[K + 3]), "v"(S[K + 4]), "v"(S[K + 5]), "v"(S[K + 6]), "v"(S[K + 7]), "n"(N0), "n"(N1));
;         if constexpr (K + 8 < 64) ScanK<K + 8>::dot(S, a, s);
;     static __device__ __forceinline__ void updS(float (&S)[64], const In1& in, float sa, float vv) {
;         float t0, t1, t2, t3;
;         asm volatile("v_mul_f32_dpp %0, %8, %21 row_newbcast:%22" DPPM "v_mul_f32_dpp %1, %9, %21 row_newbcast:%22" DPPM "v_mul_f32_dpp %2, %10, %21 row_newbcast:%22" DPPM "v_mul_f32_dpp %3, %11, %21 row_newbcast:%22" DPPM
;                      "v_fmac_f32_dpp %0, %12, %4 row_newbcast:%22" DPPM "v_fmac_f32_dpp %1, %13, %5 row_newbcast:%22" DPPM "v_fmac_f32_dpp %2, %14, %6 row_newbcast:%22" DPPM "v_fmac_f32_dpp %3, %15, %7 row_newbcast:%22" DPPM
	v_fmac_f32_dpp v228, v246, v90 row_newbcast:6 row_mask:0xf bank_mask:0xf
	v_fmac_f32_dpp v229, v247, v91 row_newbcast:6 row_mask:0xf bank_mask:0xf
	v_fmac_f32_dpp v228, v244, v92 row_newbcast:7 row_mask:0xf bank_mask:0xf
	v_fmac_f32_dpp v229, v245, v93 row_newbcast:7 row_mask:0xf bank_mask:0xf
	v_fmac_f32_dpp v228, v246, v94 row_newbcast:7 row_mask:0xf bank_mask:0xf
	v_fmac_f32_dpp v229, v247, v95 row_newbcast:7 row_mask:0xf bank_mask:0xf
	v_fmac_f32_dpp v228, v244, v96 row_newbcast:8 row_mask:0xf bank_mask:0xf
	v_fmac_f32_dpp v229, v245, v97 row_newbcast:8 row_mask:0xf bank_mask:0xf
	v_fmac_f32_dpp v228, v246, v98 row_newbcast:8 row_mask:0xf bank_mask:0xf
	v_fmac_f32_dpp v229, v247, v99 row_newbcast:8 row_mask:0xf bank_mask:0xf
	v_fmac_f32_dpp v228, v244, v100 row_newbcast:9 row_mask:0xf bank_mask:0xf
	v_fmac_f32_dpp v229, v245, v101 row_newbcast:9 row_mask:0xf bank_mask:0xf
	v_fmac_f32_dpp v228, v246, v102 row_newbcast:9 row_mask:0xf bank_mask:0xf
	v_fmac_f32_dpp v229, v247, v103 row_newbcast:9 row_mask:0xf bank_mask:0xf
	v_fmac_f32_dpp v228, v244, v104 row_newbcast:10 row_mask:0xf bank_mask:0xf
	v_fmac_f32_dpp v229, v245, v105 row_newbcast:10 row_mask:0xf bank_mask:0xf
	v_fmac_f32_dpp v228, v246, v106 row_newbcast:10 row_mask:0xf bank_mask:0xf
	v_fmac_f32_dpp v229, v247, v107 row_newbcast:10 row_mask:0xf bank_mask:0xf
	v_fmac_f32_dpp v228, v244, v108 row_newbcast:11 row_mask:0xf bank_mask:0xf
	v_fmac_f32_dpp v229, v245, v109 row_newbcast:11 row_mask:0xf bank_mask:0xf
	v_fmac_f32_dpp v228, v246, v110 row_newbcast:11 row_mask:0xf bank_mask:0xf
	v_fmac_f32_dpp v229, v247, v111 row_newbcast:11 row_mask:0xf bank_mask:0xf
	v_fmac_f32_dpp v228, v244, v112 row_newbcast:12 row_mask:0xf bank_mask:0xf
	v_fmac_f32_dpp v229, v245, v113 row_newbcast:12 row_mask:0xf bank_mask:0xf
	v_fmac_f32_dpp v228, v246, v114 row_newbcast:12 row_mask:0xf bank_mask:0xf
	v_fmac_f32_dpp v229, v247, v115 row_newbcast:12 row_mask:0xf bank_mask:0xf
	v_fmac_f32_dpp v228, v244, v116 row_newbcast:13 row_mask:0xf bank_mask:0xf
	v_fmac_f32_dpp v229, v245, v117 row_newbcast:13 row_mask:0xf bank_mask:0xf
	v_fmac_f32_dpp v228, v246, v118 row_newbcast:13 row_mask:0xf bank_mask:0xf
	v_fmac_f32_dpp v229, v247, v119 row_newbcast:13 row_mask:0xf bank_mask:0xf
	v_fmac_f32_dpp v228, v244, v120 row_newbcast:14 row_mask:0xf bank_mask:0xf
	v_fmac_f32_dpp v229, v245, v121 row_newbcast:14 row_mask:0xf bank_mask:0xf
	v_fmac_f32_dpp v228, v246, v122 row_newbcast:14 row_mask:0xf bank_mask:0xf
	v_fmac_f32_dpp v229, v247, v123 row_newbcast:14 row_mask:0xf bank_mask:0xf
	v_fmac_f32_dpp v228, v244, v124 row_newbcast:15 row_mask:0xf bank_mask:0xf
	v_fmac_f32_dpp v229, v245, v125 row_newbcast:15 row_mask:0xf bank_mask:0xf
	v_fmac_f32_dpp v228, v246, v126 row_newbcast:15 row_mask:0xf bank_mask:0xf
	v_fmac_f32_dpp v229, v247, v127 row_newbcast:15 row_mask:0xf bank_mask:0xf
	v_sub_f32_e64 v232, -v224, v225
	v_sub_f32_e64 v233, -v228, v229
	s_waitcnt lgkmcnt(0)
	v_mfma_f32_4x4x1_16b_f32 v[0:3], v128, v232, v[0:3]
	v_mfma_f32_4x4x1_16b_f32 v[4:7], v129, v232, v[4:7]
	v_mfma_f32_4x4x1_16b_f32 v[8:11], v130, v232, v[8:11]
	v_mfma_f32_4x4x1_16b_f32 v[12:15], v131, v232, v[12:15]
	v_mfma_f32_4x4x1_16b_f32 v[16:19], v132, v232, v[16:19]
	v_mfma_f32_4x4x1_16b_f32 v[20:23], v133, v232, v[20:23]
	v_mfma_f32_4x4x1_16b_f32 v[24:27], v134, v232, v[24:27]
	v_mfma_f32_4x4x1_16b_f32 v[28:31], v135, v232, v[28:31]
	v_mfma_f32_4x4x1_16b_f32 v[32:35], v136, v232, v[32:35]
	v_mfma_f32_4x4x1_16b_f32 v[36:39], v137, v232, v[36:39]
	v_mfma_f32_4x4x1_16b_f32 v[40:43], v138, v232, v[40:43]
	v_mfma_f32_4x4x1_16b_f32 v[44:47], v139, v232, v[44:47]
	v_mfma_f32_4x4x1_16b_f32 v[48:51], v140, v232, v[48:51]
	v_mfma_f32_4x4x1_16b_f32 v[52:55], v141, v232, v[52:55]
	v_mfma_f32_4x4x1_16b_f32 v[56:59], v142, v232, v[56:59]
	v_mfma_f32_4x4x1_16b_f32 v[60:63], v143, v232, v[60:63]
	v_mfma_f32_4x4x1_16b_f32 v[0:3], v144, v190, v[0:3]
	v_mfma_f32_4x4x1_16b_f32 v[4:7], v145, v190, v[4:7]
	v_mfma_f32_4x4x1_16b_f32 v[8:11], v146, v190, v[8:11]
	v_mfma_f32_4x4x1_16b_f32 v[12:15], v147, v190, v[12:15]
	v_mfma_f32_4x4x1_16b_f32 v[16:19], v148, v190, v[16:19]
	v_mfma_f32_4x4x1_16b_f32 v[20:23], v149, v190, v[20:23]
	v_mfma_f32_4x4x1_16b_f32 v[24:27], v150, v190, v[24:27]
	v_mfma_f32_4x4x1_16b_f32 v[28:31], v151, v190, v[28:31]
	v_mfma_f32_4x4x1_16b_f32 v[32:35], v152, v190, v[32:35]
	v_mfma_f32_4x4x1_16b_f32 v[36:39], v153, v190, v[36:39]
	v_mfma_f32_4x4x1_16b_f32 v[40:43], v154, v190, v[40:43]
	v_mfma_f32_4x4x1_16b_f32 v[44:47], v155, v190, v[44:47]
	v_mfma_f32_4x4x1_16b_f32 v[48:51], v156, v190, v[48:51]
	v_mfma_f32_4x4x1_16b_f32 v[52:55], v157, v190, v[52:55]
	v_mfma_f32_4x4x1_16b_f32 v[56:59], v158, v190, v[56:59]
	v_mfma_f32_4x4x1_16b_f32 v[60:63], v159, v190, v[60:63]
	v_mfma_f32_4x4x1_16b_f32 v[64:67], v128, v233, v[64:67]
	v_mfma_f32_4x4x1_16b_f32 v[68:71], v129, v233, v[68:71]
	v_mfma_f32_4x4x1_16b_f32 v[72:75], v130, v233, v[72:75]
	v_mfma_f32_4x4x1_16b_f32 v[76:79], v131, v233, v[76:79]
	v_mfma_f32_4x4x1_16b_f32 v[80:83], v132, v233, v[80:83]
	v_mfma_f32_4x4x1_16b_f32 v[84:87], v133, v233, v[84:87]
	v_mfma_f32_4x4x1_16b_f32 v[88:91], v134, v233, v[88:91]
	v_mfma_f32_4x4x1_16b_f32 v[92:95], v135, v233, v[92:95]
	v_mfma_f32_4x4x1_16b_f32 v[96:99], v136, v233, v[96:99]
	v_mfma_f32_4x4x1_16b_f32 v[100:103], v137, v233, v[100:103]
	v_mfma_f32_4x4x1_16b_f32 v[104:107], v138, v233, v[104:107]
	v_mfma_f32_4x4x1_16b_f32 v[108:111], v139, v233, v[108:111]
	v_mfma_f32_4x4x1_16b_f32 v[112:115], v140, v233, v[112:115]
	v_mfma_f32_4x4x1_16b_f32 v[116:119], v141, v233, v[116:119]
	v_mfma_f32_4x4x1_16b_f32 v[120:123], v142, v233, v[120:123]
	v_mfma_f32_4x4x1_16b_f32 v[124:127], v143, v233, v[124:127]
	s_waitcnt vmcnt(5)
	buffer_load_dwordx4 v[176:179], v235, s[64:67], s72 offen
	buffer_load_dwordx4 v[180:183], v250, s[64:67], s72 offen
	buffer_load_dwordx4 v[184:187], v251, s[64:67], s72 offen
	buffer_load_dwordx2 v[188:189], v252, s[64:67], s76 offen
	buffer_load_short_d16_hi v190, v253, s[64:67], s76 offen
	s_add_u32 s72, s72, 0x1000
	s_add_u32 s76, s76, 0x800
	v_pk_mul_f32 v[244:245], v[196:197], v[236:237]
	v_pk_mul_f32 v[246:247], v[198:199], v[238:239]
	v_pk_mul_f32 v[236:237], v[236:237], v[192:193]
	v_pk_mul_f32 v[238:239], v[238:239], v[194:195]
	v_pk_fma_f32 v[228:229], v[200:201], v[216:217], v[220:221]
	v_pk_fma_f32 v[230:231], v[202:203], v[218:219], v[222:223]
	v_pk_mul_f32 v[208:209], v[196:197], v[200:201]
	v_pk_mul_f32 v[210:211], v[198:199], v[202:203]
	v_rcp_f32_e32 v240, v236
	v_rcp_f32_e32 v241, v237
	v_rcp_f32_e32 v242, v238
	v_rcp_f32_e32 v243, v239
	v_lshlrev_b32_e32 v212, 16, v204
	v_and_b32_e32 v213, 0xffff0000, v204
	v_lshlrev_b32_e32 v214, 16, v205
	v_and_b32_e32 v215, 0xffff0000, v205
	v_pk_mul_f32 v[212:213], v[212:213], v[228:229]
	v_pk_mul_f32 v[214:215], v[214:215], v[230:231]
	v_pk_mul_f32 v[208:209], v[208:209], v[240:241]
	v_pk_mul_f32 v[210:211], v[210:211], v[242:243]
	v_pk_mul_f32 v[212:213], v[212:213], v[240:241]
	v_pk_mul_f32 v[214:215], v[214:215], v[242:243]
	ds_write2_b32 v248, v208, v209 offset0:0 offset1:16
	ds_write2_b32 v248, v210, v211 offset0:32 offset1:48
	ds_write2_b32 v248, v212, v213 offset0:64 offset1:80
	ds_write2_b32 v248, v214, v215 offset0:96 offset1:112
	ds_read_b128 v[128:131], v249 offset:0
	ds_read_b128 v[132:135], v249 offset:16
	ds_read_b128 v[136:139], v249 offset:32
	ds_read_b128 v[140:143], v249 offset:48
	ds_read_b128 v[144:147], v249 offset:256
	ds_read_b128 v[148:151], v249 offset:272
	ds_read_b128 v[152:155], v249 offset:288
	ds_read_b128 v[156:159], v249 offset:304
	v_mul_f32_dpp v224, v244, v0 row_newbcast:0 row_mask:0xf bank_mask:0xf
	v_mul_f32_dpp v225, v245, v1 row_newbcast:0 row_mask:0xf bank_mask:0xf
	v_fmac_f32_dpp v224, v246, v2 row_newbcast:0 row_mask:0xf bank_mask:0xf
	v_fmac_f32_dpp v225, v247, v3 row_newbcast:0 row_mask:0xf bank_mask:0xf
	v_fmac_f32_dpp v224, v244, v4 row_newbcast:1 row_mask:0xf bank_mask:0xf
	v_fmac_f32_dpp v225, v245, v5 row_newbcast:1 row_mask:0xf bank_mask:0xf
	v_fmac_f32_dpp v224, v246, v6 row_newbcast:1 row_mask:0xf bank_mask:0xf
	v_fmac_f32_dpp v225, v247, v7 row_newbcast:1 row_mask:0xf bank_mask:0xf
	v_fmac_f32_dpp v224, v244, v8 row_newbcast:2 row_mask:0xf bank_mask:0xf
	v_fmac_f32_dpp v225, v245, v9 row_newbcast:2 row_mask:0xf bank_mask:0xf
	v_fmac_f32_dpp v224, v246, v10 row_newbcast:2 row_mask:0xf bank_mask:0xf
	v_fmac_f32_dpp v225, v247, v11 row_newbcast:2 row_mask:0xf bank_mask:0xf
	v_fmac_f32_dpp v224, v244, v12 row_newbcast:3 row_mask:0xf bank_mask:0xf
	v_fmac_f32_dpp v225, v245, v13 row_newbcast:3 row_mask:0xf bank_mask:0xf
	v_fmac_f32_dpp v224, v246, v14 row_newbcast:3 row_mask:0xf bank_mask:0xf
	v_fmac_f32_dpp v225, v247, v15 row_newbcast:3 row_mask:0xf bank_mask:0xf
	v_fmac_f32_dpp v224, v244, v16 row_newbcast:4 row_mask:0xf bank_mask:0xf
	v_fmac_f32_dpp v225, v245, v17 row_newbcast:4 row_mask:0xf bank_mask:0xf
	v_fmac_f32_dpp v224, v246, v18 row_newbcast:4 row_mask:0xf bank_mask:0xf
	v_fmac_f32_dpp v225, v247, v19 row_newbcast:4 row_mask:0xf bank_mask:0xf
	v_fmac_f32_dpp v224, v244, v20 row_newbcast:5 row_mask:0xf bank_mask:0xf
	v_fmac_f32_dpp v225, v245, v21 row_newbcast:5 row_mask:0xf bank_mask:0xf
	v_fmac_f32_dpp v224, v246, v22 row_newbcast:5 row_mask:0xf bank_mask:0xf
	v_fmac_f32_dpp v225, v247, v23 row_newbcast:5 row_mask:0xf bank_mask:0xf
	v_fmac_f32_dpp v224, v244, v24 row_newbcast:6 row_mask:0xf bank_mask:0xf
	v_fmac_f32_dpp v225, v245, v25 row_newbcast:6 row_mask:0xf bank_mask:0xf
	v_fmac_f32_dpp v224, v246, v26 row_newbcast:6 row_mask:0xf bank_mask:0xf
	v_fmac_f32_dpp v225, v247, v27 row_newbcast:6 row_mask:0xf bank_mask:0xf
	v_fmac_f32_dpp v224, v244, v28 row_newbcast:7 row_mask:0xf bank_mask:0xf
	v_fmac_f32_dpp v225, v245, v29 row_newbcast:7 row_mask:0xf bank_mask:0xf
	v_fmac_f32_dpp v224, v246, v30 row_newbcast:7 row_mask:0xf bank_mask:0xf
	v_fmac_f32_dpp v225, v247, v31 row_newbcast:7 row_mask:0xf bank_mask:0xf
	v_fmac_f32_dpp v224, v244, v32 row_newbcast:8 row_mask:0xf bank_mask:0xf
	v_fmac_f32_dpp v225, v245, v33 row_newbcast:8 row_mask:0xf bank_mask:0xf
	v_fmac_f32_dpp v224, v246, v34 row_newbcast:8 row_mask:0xf bank_mask:0xf
	v_fmac_f32_dpp v225, v247, v35 row_newbcast:8 row_mask:0xf bank_mask:0xf
	v_fmac_f32_dpp v224, v244, v36 row_newbcast:9 row_mask:0xf bank_mask:0xf
	v_fmac_f32_dpp v225, v245, v37 row_newbcast:9 row_mask:0xf bank_mask:0xf
	v_fmac_f32_dpp v224, v246, v38 row_newbcast:9 row_mask:0xf bank_mask:0xf
	v_fmac_f32_dpp v225, v247, v39 row_newbcast:9 row_mask:0xf bank_mask:0xf
	v_fmac_f32_dpp v224, v244, v40 row_newbcast:10 row_mask:0xf bank_mask:0xf
	v_fmac_f32_dpp v225, v245, v41 row_newbcast:10 row_mask:0xf bank_mask:0xf
	v_fmac_f32_dpp v224, v246, v42 row_newbcast:10 row_mask:0xf bank_mask:0xf
	v_fmac_f32_dpp v225, v247, v43 row_newbcast:10 row_mask:0xf bank_mask:0xf
	v_fmac_f32_dpp v224, v244, v44 row_newbcast:11 row_mask:0xf bank_mask:0xf
	v_fmac_f32_dpp v225, v245, v45 row_newbcast:11 row_mask:0xf bank_mask:0xf
	v_fmac_f32_dpp v224, v246, v46 row_newbcast:11 row_mask:0xf bank_mask:0xf
	v_fmac_f32_dpp v225, v247, v47 row_newbcast:11 row_mask:0xf bank_mask:0xf
	v_fmac_f32_dpp v224, v244, v48 row_newbcast:12 row_mask:0xf bank_mask:0xf
	v_fmac_f32_dpp v225, v245, v49 row_newbcast:12 row_mask:0xf bank_mask:0xf
	v_fmac_f32_dpp v224, v246, v50 row_newbcast:12 row_mask:0xf bank_mask:0xf
;     static __device__ __forceinline__ void dot(const float (&S)[64], const f32x4& a, float (&s)[4]) {
;         if constexpr (K == 0) {
;             asm volatile("v_mul_f32_dpp %0, %4, %8 row_newbcast:%16" DPPM "v_mul_f32_dpp %1, %5, %9 row_newbcast:%16" DPPM "v_mul_f32_dpp %2, %6, %10 row_newbcast:%16" DPPM "v_mul_f32_dpp %3, %7, %11 row_newbcast:%16" DPPM
;                          "v_fmac_f32_dpp %0, %4, %12 row_newbcast:%17" DPPM "v_fmac_f32_dpp %1, %5, %13 row_newbcast:%17" DPPM "v_fmac_f32_dpp %2, %6, %14 row_newbcast:%17" DPPM "v_fmac_f32_dpp %3, %7, %15 row_newbcast:%17" DPPM
;                          : "=&v"(s[0]), "=&v"(s[1]), "=&v"(s[2]), "=&v"(s[3])
;                          : "v"(a[0]), "v"(a[1]), "v"(a[2]), "v"(a[3]), "v"(S[K]), "v"(S[K + 1]), "v"(S[K + 2]), "v"(S[K + 3]), "v"(S[K + 4]), "v"(S[K + 5]), "v"(S[K + 6]), "v"(S[K + 7]), "n"(N0), "n"(N1));
;         } else
;         asm volatile("v_fmac_f32_dpp %0, %4, %8 row_newbcast:%16" DPPM "v_fmac_f32_dpp %1, %5, %9 row_newbcast:%16" DPPM "v_fmac_f32_dpp %2, %6, %10 row_newbcast:%16" DPPM "v_fmac_f32_dpp %3, %7, %11 row_newbcast:%16" DPPM
;                      "v_fmac_f32_dpp %0, %4, %12 row_newbcast:%17" DPPM "v_fmac_f32_dpp %1, %5, %13 row_newbcast:%17" DPPM "v_fmac_f32_dpp %2, %6, %14 row_newbcast:%17" DPPM "v_fmac_f32_dpp %3, %7, %15 row_newbcast:%17" DPPM
;                      : "+v"(s[0]), "+v"(s[1]), "+v"(s[2]), "+v"(s[3])
;                      : "v"(a[0]), "v"(a[1]), "v"(a[2]), "v"(a[3]), "v"(S[K]), "v"(S[K + 1]), "v"(S[K + 2]), "v"(S[K + 3]), "v"(S[K + 4]), "v"(S[K + 5]), "v"(S[K + 6]), "v"(S[K + 7]), "n"(N0), "n"(N1));
;         if constexpr (K + 8 < 64) ScanK<K + 8>::dot(S, a, s);
	v_fmac_f32_dpp v225, v247, v51 row_newbcast:12 row_mask:0xf bank_mask:0xf
	v_fmac_f32_dpp v224, v244, v52 row_newbcast:13 row_mask:0xf bank_mask:0xf
	v_fmac_f32_dpp v225, v245, v53 row_newbcast:13 row_mask:0xf bank_mask:0xf
	v_fmac_f32_dpp v224, v246, v54 row_newbcast:13 row_mask:0xf bank_mask:0xf
	v_fmac_f32_dpp v225, v247, v55 row_newbcast:13 row_mask:0xf bank_mask:0xf
	v_fmac_f32_dpp v224, v244, v56 row_newbcast:14 row_mask:0xf bank_mask:0xf
	v_fmac_f32_dpp v225, v245, v57 row_newbcast:14 row_mask:0xf bank_mask:0xf
	v_fmac_f32_dpp v224, v246, v58 row_newbcast:14 row_mask:0xf bank_mask:0xf
	v_fmac_f32_dpp v225, v247, v59 row_newbcast:14 row_mask:0xf bank_mask:0xf
	v_fmac_f32_dpp v224, v244, v60 row_newbcast:15 row_mask:0xf bank_mask:0xf
	v_fmac_f32_dpp v225, v245, v61 row_newbcast:15 row_mask:0xf bank_mask:0xf
	v_fmac_f32_dpp v224, v246, v62 row_newbcast:15 row_mask:0xf bank_mask:0xf
	v_fmac_f32_dpp v225, v247, v63 row_newbcast:15 row_mask:0xf bank_mask:0xf
	v_mul_f32_dpp v228, v244, v64 row_newbcast:0 row_mask:0xf bank_mask:0xf
	v_mul_f32_dpp v229, v245, v65 row_newbcast:0 row_mask:0xf bank_mask:0xf
	v_fmac_f32_dpp v228, v246, v66 row_newbcast:0 row_mask:0xf bank_mask:0xf
	v_fmac_f32_dpp v229, v247, v67 row_newbcast:0 row_mask:0xf bank_mask:0xf
	v_fmac_f32_dpp v228, v244, v68 row_newbcast:1 row_mask:0xf bank_mask:0xf
	v_fmac_f32_dpp v229, v245, v69 row_newbcast:1 row_mask:0xf bank_mask:0xf
	v_fmac_f32_dpp v228, v246, v70 row_newbcast:1 row_mask:0xf bank_mask:0xf
	v_fmac_f32_dpp v229, v247, v71 row_newbcast:1 row_mask:0xf bank_mask:0xf
	v_fmac_f32_dpp v228, v244, v72 row_newbcast:2 row_mask:0xf bank_mask:0xf
	v_fmac_f32_dpp v229, v245, v73 row_newbcast:2 row_mask:0xf bank_mask:0xf
	v_fmac_f32_dpp v228, v246, v74 row_newbcast:2 row_mask:0xf bank_mask:0xf
	v_fmac_f32_dpp v229, v247, v75 row_newbcast:2 row_mask:0xf bank_mask:0xf
	v_fmac_f32_dpp v228, v244, v76 row_newbcast:3 row_mask:0xf bank_mask:0xf
	v_fmac_f32_dpp v229, v245, v77 row_newbcast:3 row_mask:0xf bank_mask:0xf
	v_fmac_f32_dpp v228, v246, v78 row_newbcast:3 row_mask:0xf bank_mask:0xf
	v_fmac_f32_dpp v229, v247, v79 row_newbcast:3 row_mask:0xf bank_mask:0xf
	v_fmac_f32_dpp v228, v244, v80 row_newbcast:4 row_mask:0xf bank_mask:0xf
	v_fmac_f32_dpp v229, v245, v81 row_newbcast:4 row_mask:0xf bank_mask:0xf
	v_fmac_f32_dpp v228, v246, v82 row_newbcast:4 row_mask:0xf bank_mask:0xf
	v_fmac_f32_dpp v229, v247, v83 row_newbcast:4 row_mask:0xf bank_mask:0xf
	v_fmac_f32_dpp v228, v244, v84 row_newbcast:5 row_mask:0xf bank_mask:0xf
	v_fmac_f32_dpp v229, v245, v85 row_newbcast:5 row_mask:0xf bank_mask:0xf
	v_fmac_f32_dpp v228, v246, v86 row_newbcast:5 row_mask:0xf bank_mask:0xf
	v_fmac_f32_dpp v229, v247, v87 row_newbcast:5 row_mask:0xf bank_mask:0xf
	v_fmac_f32_dpp v228, v244, v88 row_newbcast:6 row_mask:0xf bank_mask:0xf
	v_fmac_f32_dpp v229, v245, v89 row_newbcast:6 row_mask:0xf bank_mask:0xf
	v_fmac_f32_dpp v228, v246, v90 row_newbcast:6 row_mask:0xf bank_mask:0xf
	v_fmac_f32_dpp v229, v247, v91 row_newbcast:6 row_mask:0xf bank_mask:0xf
	v_fmac_f32_dpp v228, v244, v92 row_newbcast:7 row_mask:0xf bank_mask:0xf
	v_fmac_f32_dpp v229, v245, v93 row_newbcast:7 row_mask:0xf bank_mask:0xf
	v_fmac_f32_dpp v228, v246, v94 row_newbcast:7 row_mask:0xf bank_mask:0xf
	v_fmac_f32_dpp v229, v247, v95 row_newbcast:7 row_mask:0xf bank_mask:0xf
	v_fmac_f32_dpp v228, v244, v96 row_newbcast:8 row_mask:0xf bank_mask:0xf
	v_fmac_f32_dpp v229, v245, v97 row_newbcast:8 row_mask:0xf bank_mask:0xf
	v_fmac_f32_dpp v228, v246, v98 row_newbcast:8 row_mask:0xf bank_mask:0xf
	v_fmac_f32_dpp v229, v247, v99 row_newbcast:8 row_mask:0xf bank_mask:0xf
	v_fmac_f32_dpp v228, v244, v100 row_newbcast:9 row_mask:0xf bank_mask:0xf
	v_fmac_f32_dpp v229, v245, v101 row_newbcast:9 row_mask:0xf bank_mask:0xf
	v_fmac_f32_dpp v228, v246, v102 row_newbcast:9 row_mask:0xf bank_mask:0xf
	v_fmac_f32_dpp v229, v247, v103 row_newbcast:9 row_mask:0xf bank_mask:0xf
	v_fmac_f32_dpp v228, v244, v104 row_newbcast:10 row_mask:0xf bank_mask:0xf
	v_fmac_f32_dpp v229, v245, v105 row_newbcast:10 row_mask:0xf bank_mask:0xf
	v_fmac_f32_dpp v228, v246, v106 row_newbcast:10 row_mask:0xf bank_mask:0xf
	v_fmac_f32_dpp v229, v247, v107 row_newbcast:10 row_mask:0xf bank_mask:0xf
	v_fmac_f32_dpp v228, v244, v108 row_newbcast:11 row_mask:0xf bank_mask:0xf
	v_fmac_f32_dpp v229, v245, v109 row_newbcast:11 row_mask:0xf bank_mask:0xf
	v_fmac_f32_dpp v228, v246, v110 row_newbcast:11 row_mask:0xf bank_mask:0xf
	v_fmac_f32_dpp v229, v247, v111 row_newbcast:11 row_mask:0xf bank_mask:0xf
	v_fmac_f32_dpp v228, v244, v112 row_newbcast:12 row_mask:0xf bank_mask:0xf
	v_fmac_f32_dpp v229, v245, v113 row_newbcast:12 row_mask:0xf bank_mask:0xf
	v_fmac_f32_dpp v228, v246, v114 row_newbcast:12 row_mask:0xf bank_mask:0xf
	v_fmac_f32_dpp v229, v247, v115 row_newbcast:12 row_mask:0xf bank_mask:0xf
	v_fmac_f32_dpp v228, v244, v116 row_newbcast:13 row_mask:0xf bank_mask:0xf
	v_fmac_f32_dpp v229, v245, v117 row_newbcast:13 row_mask:0xf bank_mask:0xf
	v_fmac_f32_dpp v228, v246, v118 row_newbcast:13 row_mask:0xf bank_mask:0xf
	v_fmac_f32_dpp v229, v247, v119 row_newbcast:13 row_mask:0xf bank_mask:0xf
	v_fmac_f32_dpp v228, v244, v120 row_newbcast:14 row_mask:0xf bank_mask:0xf
	v_fmac_f32_dpp v229, v245, v121 row_newbcast:14 row_mask:0xf bank_mask:0xf
	v_fmac_f32_dpp v228, v246, v122 row_newbcast:14 row_mask:0xf bank_mask:0xf
	v_fmac_f32_dpp v229, v247, v123 row_newbcast:14 row_mask:0xf bank_mask:0xf
	v_fmac_f32_dpp v228, v244, v124 row_newbcast:15 row_mask:0xf bank_mask:0xf
	v_fmac_f32_dpp v229, v245, v125 row_newbcast:15 row_mask:0xf bank_mask:0xf
	v_fmac_f32_dpp v228, v246, v126 row_newbcast:15 row_mask:0xf bank_mask:0xf
	v_fmac_f32_dpp v229, v247, v127 row_newbcast:15 row_mask:0xf bank_mask:0xf
	v_sub_f32_e64 v232, -v224, v225
	v_sub_f32_e64 v233, -v228, v229
	s_waitcnt lgkmcnt(0)
;     static __device__ __forceinline__ void updS(float (&S)[64], const In1& in, float sa, float vv) {
;         float t0, t1, t2, t3;
;         asm volatile("v_mul_f32_dpp %0, %8, %21 row_newbcast:%22" DPPM "v_mul_f32_dpp %1, %9, %21 row_newbcast:%22" DPPM "v_mul_f32_dpp %2, %10, %21 row_newbcast:%22" DPPM "v_mul_f32_dpp %3, %11, %21 row_newbcast:%22" DPPM
;                      "v_fmac_f32_dpp %0, %12, %4 row_newbcast:%22" DPPM "v_fmac_f32_dpp %1, %13, %5 row_newbcast:%22" DPPM "v_fmac_f32_dpp %2, %14, %6 row_newbcast:%22" DPPM "v_fmac_f32_dpp %3, %15, %7 row_newbcast:%22" DPPM
;                      "v_fmac_f32_dpp %0, %16, %20 row_newbcast:%22" DPPM "v_fmac_f32_dpp %1, %17, %20 row_newbcast:%22" DPPM "v_fmac_f32_dpp %2, %18, %20 row_newbcast:%22" DPPM "v_fmac_f32_dpp %3, %19, %20 row_newbcast:%22" DPPM
;                      : "=&v"(t0), "=&v"(t1), "=&v"(t2), "=&v"(t3)
;                      : "v"(S[K]), "v"(S[K + 1]), "v"(S[K + 2]), "v"(S[K + 3]), "v"(in.kd[0]), "v"(in.kd[1]), "v"(in.kd[2]), "v"(in.kd[3]), "v"(in.w[0]), "v"(in.w[1]), "v"(in.w[2]), "v"(in.w[3]),
;                        "v"(in.b[0]), "v"(in.b[1]), "v"(in.b[2]), "v"(in.b[3]), "v"(sa), "v"(vv), "n"(N0));
;         S[K] = t0; S[K + 1] = t1; S[K + 2] = t2; S[K + 3] = t3;
;         if constexpr (K + 4 < 64) ScanK<K + 4>::updS(S, in, sa, vv);
;     }
;     static __device__ __forceinline__ void updP(float (&P)[64], const In1& in, float sa) {
;         float u0, u1, u2, u3;
;         asm volatile("v_mul_f32_dpp %0, %8, %4 row_newbcast:%17" DPPM "v_mul_f32_dpp %1, %9, %5 row_newbcast:%17" DPPM "v_mul_f32_dpp %2, %10, %6 row_newbcast:%17" DPPM "v_mul_f32_dpp %3, %11, %7 row_newbcast:%17" DPPM
;                      "v_fmac_f32_dpp %0, %12, %16 row_newbcast:%17" DPPM "v_fmac_f32_dpp %1, %13, %16 row_newbcast:%17" DPPM "v_fmac_f32_dpp %2, %14, %16 row_newbcast:%17" DPPM "v_fmac_f32_dpp %3, %15, %16 row_newbcast:%17" DPPM
;                      : "=&v"(u0), "=&v"(u1), "=&v"(u2), "=&v"(u3)
;                      : "v"(P[K]), "v"(P[K + 1]), "v"(P[K + 2]), "v"(P[K + 3]), "v"(in.w[0]), "v"(in.w[1]), "v"(in.w[2]), "v"(in.w[3]), "v"(in.b[0]), "v"(in.b[1]), "v"(in.b[2]), "v"(in.b[3]), "v"(sa), "n"(N0));
;         P[K] = u0; P[K + 1] = u1; P[K + 2] = u2; P[K + 3] = u3;
;         if constexpr (K + 4 < 64) ScanK<K + 4>::updP(P, in, sa);
;     }
	v_mfma_f32_4x4x1_16b_f32 v[0:3], v128, v232, v[0:3]
	v_mfma_f32_4x4x1_16b_f32 v[4:7], v129, v232, v[4:7]
	v_mfma_f32_4x4x1_16b_f32 v[8:11], v130, v232, v[8:11]
	v_mfma_f32_4x4x1_16b_f32 v[12:15], v131, v232, v[12:15]
	v_mfma_f32_4x4x1_16b_f32 v[16:19], v132, v232, v[16:19]
	v_mfma_f32_4x4x1_16b_f32 v[20:23], v133, v232, v[20:23]
	v_mfma_f32_4x4x1_16b_f32 v[24:27], v134, v232, v[24:27]
	v_mfma_f32_4x4x1_16b_f32 v[28:31], v135, v232, v[28:31]
	v_mfma_f32_4x4x1_16b_f32 v[32:35], v136, v232, v[32:35]
	v_mfma_f32_4x4x1_16b_f32 v[36:39], v137, v232, v[36:39]
	v_mfma_f32_4x4x1_16b_f32 v[40:43], v138, v232, v[40:43]
	v_mfma_f32_4x4x1_16b_f32 v[44:47], v139, v232, v[44:47]
	v_mfma_f32_4x4x1_16b_f32 v[48:51], v140, v232, v[48:51]
	v_mfma_f32_4x4x1_16b_f32 v[52:55], v141, v232, v[52:55]
	v_mfma_f32_4x4x1_16b_f32 v[56:59], v142, v232, v[56:59]
	v_mfma_f32_4x4x1_16b_f32 v[60:63], v143, v232, v[60:63]
	v_mfma_f32_4x4x1_16b_f32 v[0:3], v144, v206, v[0:3]
	v_mfma_f32_4x4x1_16b_f32 v[4:7], v145, v206, v[4:7]
	v_mfma_f32_4x4x1_16b_f32 v[8:11], v146, v206, v[8:11]
	v_mfma_f32_4x4x1_16b_f32 v[12:15], v147, v206, v[12:15]
	v_mfma_f32_4x4x1_16b_f32 v[16:19], v148, v206, v[16:19]
	v_mfma_f32_4x4x1_16b_f32 v[20:23], v149, v206, v[20:23]
	v_mfma_f32_4x4x1_16b_f32 v[24:27], v150, v206, v[24:27]
	v_mfma_f32_4x4x1_16b_f32 v[28:31], v151, v206, v[28:31]
	v_mfma_f32_4x4x1_16b_f32 v[32:35], v152, v206, v[32:35]
	v_mfma_f32_4x4x1_16b_f32 v[36:39], v153, v206, v[36:39]
	v_mfma_f32_4x4x1_16b_f32 v[40:43], v154, v206, v[40:43]
	v_mfma_f32_4x4x1_16b_f32 v[44:47], v155, v206, v[44:47]
	v_mfma_f32_4x4x1_16b_f32 v[48:51], v156, v206, v[48:51]
	v_mfma_f32_4x4x1_16b_f32 v[52:55], v157, v206, v[52:55]
	v_mfma_f32_4x4x1_16b_f32 v[56:59], v158, v206, v[56:59]
	v_mfma_f32_4x4x1_16b_f32 v[60:63], v159, v206, v[60:63]
	v_mfma_f32_4x4x1_16b_f32 v[64:67], v128, v233, v[64:67]
	v_mfma_f32_4x4x1_16b_f32 v[68:71], v129, v233, v[68:71]
	v_mfma_f32_4x4x1_16b_f32 v[72:75], v130, v233, v[72:75]
	v_mfma_f32_4x4x1_16b_f32 v[76:79], v131, v233, v[76:79]
	v_mfma_f32_4x4x1_16b_f32 v[80:83], v132, v233, v[80:83]
	v_mfma_f32_4x4x1_16b_f32 v[84:87], v133, v233, v[84:87]
	v_mfma_f32_4x4x1_16b_f32 v[88:91], v134, v233, v[88:91]
	v_mfma_f32_4x4x1_16b_f32 v[92:95], v135, v233, v[92:95]
	v_mfma_f32_4x4x1_16b_f32 v[96:99], v136, v233, v[96:99]
	v_mfma_f32_4x4x1_16b_f32 v[100:103], v137, v233, v[100:103]
	v_mfma_f32_4x4x1_16b_f32 v[104:107], v138, v233, v[104:107]
	v_mfma_f32_4x4x1_16b_f32 v[108:111], v139, v233, v[108:111]
	v_mfma_f32_4x4x1_16b_f32 v[112:115], v140, v233, v[112:115]
	v_mfma_f32_4x4x1_16b_f32 v[116:119], v141, v233, v[116:119]
	v_mfma_f32_4x4x1_16b_f32 v[120:123], v142, v233, v[120:123]
	v_mfma_f32_4x4x1_16b_f32 v[124:127], v143, v233, v[124:127]
	s_sub_u32 s83, s83, 1
	s_cmp_eq_u32 s83, 0
	s_cbranch_scc1 .Lmy_p1d0_ldone
	s_sub_u32 s9, s9, 1
	s_cmp_eq_u32 s9, 0
	s_cbranch_scc1 .Lmy_p1d0_renorm
	s_branch .Lmy_p1d0_loop
.Lmy_p1d0_ldone:
	s_waitcnt vmcnt(5)
	buffer_load_dwordx4 v[192:195], v235, s[64:67], s72 offen
	buffer_load_dwordx4 v[196:199], v250, s[64:67], s72 offen
	buffer_load_dwordx4 v[200:203], v251, s[64:67], s72 offen
	buffer_load_dwordx2 v[204:205], v252, s[64:67], s76 offen
	buffer_load_short_d16_hi v206, v253, s[64:67], s76 offen
	s_add_u32 s72, s72, 0x1000
	s_add_u32 s76, s76, 0x800
	v_pk_mul_f32 v[244:245], v[164:165], v[236:237]
	v_pk_mul_f32 v[246:247], v[166:167], v[238:239]
	v_pk_mul_f32 v[236:237], v[236:237], v[160:161]
	v_pk_mul_f32 v[238:239], v[238:239], v[162:163]
	v_pk_fma_f32 v[228:229], v[168:169], v[216:217], v[220:221]
	v_pk_fma_f32 v[230:231], v[170:171], v[218:219], v[222:223]
	v_pk_mul_f32 v[208:209], v[164:165], v[168:169]
	v_pk_mul_f32 v[210:211], v[166:167], v[170:171]
	v_rcp_f32_e32 v240, v236
	v_rcp_f32_e32 v241, v237
	v_rcp_f32_e32 v242, v238
	v_rcp_f32_e32 v243, v239
	v_lshlrev_b32_e32 v212, 16, v172
	v_and_b32_e32 v213, 0xffff0000, v172
	v_lshlrev_b32_e32 v214, 16, v173
	v_and_b32_e32 v215, 0xffff0000, v173
	v_pk_mul_f32 v[212:213], v[212:213], v[228:229]
	v_pk_mul_f32 v[214:215], v[214:215], v[230:231]
	v_pk_mul_f32 v[208:209], v[208:209], v[240:241]
	v_pk_mul_f32 v[210:211], v[210:211], v[242:243]
	v_pk_mul_f32 v[212:213], v[212:213], v[240:241]
	v_pk_mul_f32 v[214:215], v[214:215], v[242:243]
	ds_write2_b32 v248, v208, v209 offset0:0 offset1:16
	ds_write2_b32 v248, v210, v211 offset0:32 offset1:48
	ds_write2_b32 v248, v212, v213 offset0:64 offset1:80
	ds_write2_b32 v248, v214, v215 offset0:96 offset1:112
	ds_read_b128 v[128:131], v249 offset:0
	ds_read_b128 v[132:135], v249 offset:16
	ds_read_b128 v[136:139], v249 offset:32
	ds_read_b128 v[140:143], v249 offset:48
	ds_read_b128 v[144:147], v249 offset:256
	ds_read_b128 v[148:151], v249 offset:272
	ds_read_b128 v[152:155], v249 offset:288
	ds_read_b128 v[156:159], v249 offset:304
	v_mul_f32_dpp v224, v244, v0 row_newbcast:0 row_mask:0xf bank_mask:0xf
	v_mul_f32_dpp v225, v245, v1 row_newbcast:0 row_mask:0xf bank_mask:0xf
	v_fmac_f32_dpp v224, v246, v2 row_newbcast:0 row_mask:0xf bank_mask:0xf
	v_fmac_f32_dpp v225, v247, v3 row_newbcast:0 row_mask:0xf bank_mask:0xf
	v_fmac_f32_dpp v224, v244, v4 row_newbcast:1 row_mask:0xf bank_mask:0xf
	v_fmac_f32_dpp v225, v245, v5 row_newbcast:1 row_mask:0xf bank_mask:0xf
	v_fmac_f32_dpp v224, v246, v6 row_newbcast:1 row_mask:0xf bank_mask:0xf
	v_fmac_f32_dpp v225, v247, v7 row_newbcast:1 row_mask:0xf bank_mask:0xf
	v_fmac_f32_dpp v224, v244, v8 row_newbcast:2 row_mask:0xf bank_mask:0xf
	v_fmac_f32_dpp v225, v245, v9 row_newbcast:2 row_mask:0xf bank_mask:0xf
	v_fmac_f32_dpp v224, v246, v10 row_newbcast:2 row_mask:0xf bank_mask:0xf
;     static __device__ __forceinline__ void dot(const float (&S)[64], const f32x4& a, float (&s)[4]) {
;         if constexpr (K == 0) {
;             asm volatile("v_mul_f32_dpp %0, %4, %8 row_newbcast:%16" DPPM "v_mul_f32_dpp %1, %5, %9 row_newbcast:%16" DPPM "v_mul_f32_dpp %2, %6, %10 row_newbcast:%16" DPPM "v_mul_f32_dpp %3, %7, %11 row_newbcast:%16" DPPM
;                          "v_fmac_f32_dpp %0, %4, %12 row_newbcast:%17" DPPM "v_fmac_f32_dpp %1, %5, %13 row_newbcast:%17" DPPM "v_fmac_f32_dpp %2, %6, %14 row_newbcast:%17" DPPM "v_fmac_f32_dpp %3, %7, %15 row_newbcast:%17" DPPM
;                          : "=&v"(s[0]), "=&v"(s[1]), "=&v"(s[2]), "=&v"(s[3])
;                          : "v"(a[0]), "v"(a[1]), "v"(a[2]), "v"(a[3]), "v"(S[K]), "v"(S[K + 1]), "v"(S[K + 2]), "v"(S[K + 3]), "v"(S[K + 4]), "v"(S[K + 5]), "v"(S[K + 6]), "v"(S[K + 7]), "n"(N0), "n"(N1));
;         } else
;         asm volatile("v_fmac_f32_dpp %0, %4, %8 row_newbcast:%16" DPPM "v_fmac_f32_dpp %1, %5, %9 row_newbcast:%16" DPPM "v_fmac_f32_dpp %2, %6, %10 row_newbcast:%16" DPPM "v_fmac_f32_dpp %3, %7, %11 row_newbcast:%16" DPPM
;                      "v_fmac_f32_dpp %0, %4, %12 row_newbcast:%17" DPPM "v_fmac_f32_dpp %1, %5, %13 row_newbcast:%17" DPPM "v_fmac_f32_dpp %2, %6, %14 row_newbcast:%17" DPPM "v_fmac_f32_dpp %3, %7, %15 row_newbcast:%17" DPPM
;                      : "+v"(s[0]), "+v"(s[1]), "+v"(s[2]), "+v"(s[3])
;                      : "v"(a[0]), "v"(a[1]), "v"(a[2]), "v"(a[3]), "v"(S[K]), "v"(S[K + 1]), "v"(S[K + 2]), "v"(S[K + 3]), "v"(S[K + 4]), "v"(S[K + 5]), "v"(S[K + 6]), "v"(S[K + 7]), "n"(N0), "n"(N1));
;         if constexpr (K + 8 < 64) ScanK<K + 8>::dot(S, a, s);
	v_fmac_f32_dpp v225, v247, v11 row_newbcast:2 row_mask:0xf bank_mask:0xf
	v_fmac_f32_dpp v224, v244, v12 row_newbcast:3 row_mask:0xf bank_mask:0xf
	v_fmac_f32_dpp v225, v245, v13 row_newbcast:3 row_mask:0xf bank_mask:0xf
	v_fmac_f32_dpp v224, v246, v14 row_newbcast:3 row_mask:0xf bank_mask:0xf
	v_fmac_f32_dpp v225, v247, v15 row_newbcast:3 row_mask:0xf bank_mask:0xf
	v_fmac_f32_dpp v224, v244, v16 row_newbcast:4 row_mask:0xf bank_mask:0xf
	v_fmac_f32_dpp v225, v245, v17 row_newbcast:4 row_mask:0xf bank_mask:0xf
	v_fmac_f32_dpp v224, v246, v18 row_newbcast:4 row_mask:0xf bank_mask:0xf
	v_fmac_f32_dpp v225, v247, v19 row_newbcast:4 row_mask:0xf bank_mask:0xf
	v_fmac_f32_dpp v224, v244, v20 row_newbcast:5 row_mask:0xf bank_mask:0xf
	v_fmac_f32_dpp v225, v245, v21 row_newbcast:5 row_mask:0xf bank_mask:0xf
	v_fmac_f32_dpp v224, v246, v22 row_newbcast:5 row_mask:0xf bank_mask:0xf
	v_fmac_f32_dpp v225, v247, v23 row_newbcast:5 row_mask:0xf bank_mask:0xf
	v_fmac_f32_dpp v224, v244, v24 row_newbcast:6 row_mask:0xf bank_mask:0xf
	v_fmac_f32_dpp v225, v245, v25 row_newbcast:6 row_mask:0xf bank_mask:0xf
	v_fmac_f32_dpp v224, v246, v26 row_newbcast:6 row_mask:0xf bank_mask:0xf
	v_fmac_f32_dpp v225, v247, v27 row_newbcast:6 row_mask:0xf bank_mask:0xf
	v_fmac_f32_dpp v224, v244, v28 row_newbcast:7 row_mask:0xf bank_mask:0xf
	v_fmac_f32_dpp v225, v245, v29 row_newbcast:7 row_mask:0xf bank_mask:0xf
	v_fmac_f32_dpp v224, v246, v30 row_newbcast:7 row_mask:0xf bank_mask:0xf
	v_fmac_f32_dpp v225, v247, v31 row_newbcast:7 row_mask:0xf bank_mask:0xf
	v_fmac_f32_dpp v224, v244, v32 row_newbcast:8 row_mask:0xf bank_mask:0xf
	v_fmac_f32_dpp v225, v245, v33 row_newbcast:8 row_mask:0xf bank_mask:0xf
	v_fmac_f32_dpp v224, v246, v34 row_newbcast:8 row_mask:0xf bank_mask:0xf
	v_fmac_f32_dpp v225, v247, v35 row_newbcast:8 row_mask:0xf bank_mask:0xf
	v_fmac_f32_dpp v224, v244, v36 row_newbcast:9 row_mask:0xf bank_mask:0xf
	v_fmac_f32_dpp v225, v245, v37 row_newbcast:9 row_mask:0xf bank_mask:0xf
	v_fmac_f32_dpp v224, v246, v38 row_newbcast:9 row_mask:0xf bank_mask:0xf
	v_fmac_f32_dpp v225, v247, v39 row_newbcast:9 row_mask:0xf bank_mask:0xf
	v_fmac_f32_dpp v224, v244, v40 row_newbcast:10 row_mask:0xf bank_mask:0xf
	v_fmac_f32_dpp v225, v245, v41 row_newbcast:10 row_mask:0xf bank_mask:0xf
	v_fmac_f32_dpp v224, v246, v42 row_newbcast:10 row_mask:0xf bank_mask:0xf
	v_fmac_f32_dpp v225, v247, v43 row_newbcast:10 row_mask:0xf bank_mask:0xf
	v_fmac_f32_dpp v224, v244, v44 row_newbcast:11 row_mask:0xf bank_mask:0xf
	v_fmac_f32_dpp v225, v245, v45 row_newbcast:11 row_mask:0xf bank_mask:0xf
	v_fmac_f32_dpp v224, v246, v46 row_newbcast:11 row_mask:0xf bank_mask:0xf
	v_fmac_f32_dpp v225, v247, v47 row_newbcast:11 row_mask:0xf bank_mask:0xf
	v_fmac_f32_dpp v224, v244, v48 row_newbcast:12 row_mask:0xf bank_mask:0xf
	v_fmac_f32_dpp v225, v245, v49 row_newbcast:12 row_mask:0xf bank_mask:0xf
	v_fmac_f32_dpp v224, v246, v50 row_newbcast:12 row_mask:0xf bank_mask:0xf
	v_fmac_f32_dpp v225, v247, v51 row_newbcast:12 row_mask:0xf bank_mask:0xf
	v_fmac_f32_dpp v224, v244, v52 row_newbcast:13 row_mask:0xf bank_mask:0xf
	v_fmac_f32_dpp v225, v245, v53 row_newbcast:13 row_mask:0xf bank_mask:0xf
	v_fmac_f32_dpp v224, v246, v54 row_newbcast:13 row_mask:0xf bank_mask:0xf
	v_fmac_f32_dpp v225, v247, v55 row_newbcast:13 row_mask:0xf bank_mask:0xf
	v_fmac_f32_dpp v224, v244, v56 row_newbcast:14 row_mask:0xf bank_mask:0xf
	v_fmac_f32_dpp v225, v245, v57 row_newbcast:14 row_mask:0xf bank_mask:0xf
	v_fmac_f32_dpp v224, v246, v58 row_newbcast:14 row_mask:0xf bank_mask:0xf
	v_fmac_f32_dpp v225, v247, v59 row_newbcast:14 row_mask:0xf bank_mask:0xf
	v_fmac_f32_dpp v224, v244, v60 row_newbcast:15 row_mask:0xf bank_mask:0xf
	v_fmac_f32_dpp v225, v245, v61 row_newbcast:15 row_mask:0xf bank_mask:0xf
	v_fmac_f32_dpp v224, v246, v62 row_newbcast:15 row_mask:0xf bank_mask:0xf
	v_fmac_f32_dpp v225, v247, v63 row_newbcast:15 row_mask:0xf bank_mask:0xf
	v_mul_f32_dpp v228, v244, v64 row_newbcast:0 row_mask:0xf bank_mask:0xf
	v_mul_f32_dpp v229, v245, v65 row_newbcast:0 row_mask:0xf bank_mask:0xf
	v_fmac_f32_dpp v228, v246, v66 row_newbcast:0 row_mask:0xf bank_mask:0xf
	v_fmac_f32_dpp v229, v247, v67 row_newbcast:0 row_mask:0xf bank_mask:0xf
	v_fmac_f32_dpp v228, v244, v68 row_newbcast:1 row_mask:0xf bank_mask:0xf
	v_fmac_f32_dpp v229, v245, v69 row_newbcast:1 row_mask:0xf bank_mask:0xf
	v_fmac_f32_dpp v228, v246, v70 row_newbcast:1 row_mask:0xf bank_mask:0xf
	v_fmac_f32_dpp v229, v247, v71 row_newbcast:1 row_mask:0xf bank_mask:0xf
	v_fmac_f32_dpp v228, v244, v72 row_newbcast:2 row_mask:0xf bank_mask:0xf
	v_fmac_f32_dpp v229, v245, v73 row_newbcast:2 row_mask:0xf bank_mask:0xf
	v_fmac_f32_dpp v228, v246, v74 row_newbcast:2 row_mask:0xf bank_mask:0xf
	v_fmac_f32_dpp v229, v247, v75 row_newbcast:2 row_mask:0xf bank_mask:0xf
	v_fmac_f32_dpp v228, v244, v76 row_newbcast:3 row_mask:0xf bank_mask:0xf
	v_fmac_f32_dpp v229, v245, v77 row_newbcast:3 row_mask:0xf bank_mask:0xf
	v_fmac_f32_dpp v228, v246, v78 row_newbcast:3 row_mask:0xf bank_mask:0xf
	v_fmac_f32_dpp v229, v247, v79 row_newbcast:3 row_mask:0xf bank_mask:0xf
	v_fmac_f32_dpp v228, v244, v80 row_newbcast:4 row_mask:0xf bank_mask:0xf
	v_fmac_f32_dpp v229, v245, v81 row_newbcast:4 row_mask:0xf bank_mask:0xf
	v_fmac_f32_dpp v228, v246, v82 row_newbcast:4 row_mask:0xf bank_mask:0xf
	v_fmac_f32_dpp v229, v247, v83 row_newbcast:4 row_mask:0xf bank_mask:0xf
	v_fmac_f32_dpp v228, v244, v84 row_newbcast:5 row_mask:0xf bank_mask:0xf
	v_fmac_f32_dpp v229, v245, v85 row_newbcast:5 row_mask:0xf bank_mask:0xf
	v_fmac_f32_dpp v228, v246, v86 row_newbcast:5 row_mask:0xf bank_mask:0xf
;     static __device__ __forceinline__ void dot(const float (&S)[64], const f32x4& a, float (&s)[4]) {
;         if constexpr (K == 0) {
;             asm volatile("v_mul_f32_dpp %0, %4, %8 row_newbcast:%16" DPPM "v_mul_f32_dpp %1, %5, %9 row_newbcast:%16" DPPM "v_mul_f32_dpp %2, %6, %10 row_newbcast:%16" DPPM "v_mul_f32_dpp %3, %7, %11 row_newbcast:%16" DPPM
;                          "v_fmac_f32_dpp %0, %4, %12 row_newbcast:%17" DPPM "v_fmac_f32_dpp %1, %5, %13 row_newbcast:%17" DPPM "v_fmac_f32_dpp %2, %6, %14 row_newbcast:%17" DPPM "v_fmac_f32_dpp %3, %7, %15 row_newbcast:%17" DPPM
;                          : "=&v"(s[0]), "=&v"(s[1]), "=&v"(s[2]), "=&v"(s[3])
;                          : "v"(a[0]), "v"(a[1]), "v"(a[2]), "v"(a[3]), "v"(S[K]), "v"(S[K + 1]), "v"(S[K + 2]), "v"(S[K + 3]), "v"(S[K + 4]), "v"(S[K + 5]), "v"(S[K + 6]), "v"(S[K + 7]), "n"(N0), "n"(N1));
;         } else
;         asm volatile("v_fmac_f32_dpp %0, %4, %8 row_newbcast:%16" DPPM "v_fmac_f32_dpp %1, %5, %9 row_newbcast:%16" DPPM "v_fmac_f32_dpp %2, %6, %10 row_newbcast:%16" DPPM "v_fmac_f32_dpp %3, %7, %11 row_newbcast:%16" DPPM
;                      "v_fmac_f32_dpp %0, %4, %12 row_newbcast:%17" DPPM "v_fmac_f32_dpp %1, %5, %13 row_newbcast:%17" DPPM "v_fmac_f32_dpp %2, %6, %14 row_newbcast:%17" DPPM "v_fmac_f32_dpp %3, %7, %15 row_newbcast:%17" DPPM
;                      : "+v"(s[0]), "+v"(s[1]), "+v"(s[2]), "+v"(s[3])
;                      : "v"(a[0]), "v"(a[1]), "v"(a[2]), "v"(a[3]), "v"(S[K]), "v"(S[K + 1]), "v"(S[K + 2]), "v"(S[K + 3]), "v"(S[K + 4]), "v"(S[K + 5]), "v"(S[K + 6]), "v"(S[K + 7]), "n"(N0), "n"(N1));
;         if constexpr (K + 8 < 64) ScanK<K + 8>::dot(S, a, s);
;     }
;     static __device__ __forceinline__ void upd(float (&S)[64], const In2& in, float sa, float vv, float& y0, float& y1) {
;         float t0, t1, t2, t3;
;         asm volatile("v_mul_f32_dpp %0, %10, %27 row_newbcast:%28" DPPM "v_mul_f32_dpp %1, %11, %27 row_newbcast:%28" DPPM "v_mul_f32_dpp %2, %12, %27 row_newbcast:%28" DPPM "v_mul_f32_dpp %3, %13, %27 row_newbcast:%28" DPPM
;                      "v_fmac_f32_dpp %0, %14, %6 row_newbcast:%28" DPPM "v_fmac_f32_dpp %1, %15, %7 row_newbcast:%28" DPPM "v_fmac_f32_dpp %2, %16, %8 row_newbcast:%28" DPPM "v_fmac_f32_dpp %3, %17, %9 row_newbcast:%28" DPPM
	v_fmac_f32_dpp v229, v247, v87 row_newbcast:5 row_mask:0xf bank_mask:0xf
	v_fmac_f32_dpp v228, v244, v88 row_newbcast:6 row_mask:0xf bank_mask:0xf
	v_fmac_f32_dpp v229, v245, v89 row_newbcast:6 row_mask:0xf bank_mask:0xf
	v_fmac_f32_dpp v228, v246, v90 row_newbcast:6 row_mask:0xf bank_mask:0xf
	v_fmac_f32_dpp v229, v247, v91 row_newbcast:6 row_mask:0xf bank_mask:0xf
	v_fmac_f32_dpp v228, v244, v92 row_newbcast:7 row_mask:0xf bank_mask:0xf
	v_fmac_f32_dpp v229, v245, v93 row_newbcast:7 row_mask:0xf bank_mask:0xf
	v_fmac_f32_dpp v228, v246, v94 row_newbcast:7 row_mask:0xf bank_mask:0xf
	v_fmac_f32_dpp v229, v247, v95 row_newbcast:7 row_mask:0xf bank_mask:0xf
	v_fmac_f32_dpp v228, v244, v96 row_newbcast:8 row_mask:0xf bank_mask:0xf
	v_fmac_f32_dpp v229, v245, v97 row_newbcast:8 row_mask:0xf bank_mask:0xf
	v_fmac_f32_dpp v228, v246, v98 row_newbcast:8 row_mask:0xf bank_mask:0xf
	v_fmac_f32_dpp v229, v247, v99 row_newbcast:8 row_mask:0xf bank_mask:0xf
	v_fmac_f32_dpp v228, v244, v100 row_newbcast:9 row_mask:0xf bank_mask:0xf
	v_fmac_f32_dpp v229, v245, v101 row_newbcast:9 row_mask:0xf bank_mask:0xf
	v_fmac_f32_dpp v228, v246, v102 row_newbcast:9 row_mask:0xf bank_mask:0xf
	v_fmac_f32_dpp v229, v247, v103 row_newbcast:9 row_mask:0xf bank_mask:0xf
	v_fmac_f32_dpp v228, v244, v104 row_newbcast:10 row_mask:0xf bank_mask:0xf
	v_fmac_f32_dpp v229, v245, v105 row_newbcast:10 row_mask:0xf bank_mask:0xf
	v_fmac_f32_dpp v228, v246, v106 row_newbcast:10 row_mask:0xf bank_mask:0xf
	v_fmac_f32_dpp v229, v247, v107 row_newbcast:10 row_mask:0xf bank_mask:0xf
	v_fmac_f32_dpp v228, v244, v108 row_newbcast:11 row_mask:0xf bank_mask:0xf
	v_fmac_f32_dpp v229, v245, v109 row_newbcast:11 row_mask:0xf bank_mask:0xf
	v_fmac_f32_dpp v228, v246, v110 row_newbcast:11 row_mask:0xf bank_mask:0xf
	v_fmac_f32_dpp v229, v247, v111 row_newbcast:11 row_mask:0xf bank_mask:0xf
	v_fmac_f32_dpp v228, v244, v112 row_newbcast:12 row_mask:0xf bank_mask:0xf
	v_fmac_f32_dpp v229, v245, v113 row_newbcast:12 row_mask:0xf bank_mask:0xf
	v_fmac_f32_dpp v228, v246, v114 row_newbcast:12 row_mask:0xf bank_mask:0xf
	v_fmac_f32_dpp v229, v247, v115 row_newbcast:12 row_mask:0xf bank_mask:0xf
	v_fmac_f32_dpp v228, v244, v116 row_newbcast:13 row_mask:0xf bank_mask:0xf
	v_fmac_f32_dpp v229, v245, v117 row_newbcast:13 row_mask:0xf bank_mask:0xf
	v_fmac_f32_dpp v228, v246, v118 row_newbcast:13 row_mask:0xf bank_mask:0xf
	v_fmac_f32_dpp v229, v247, v119 row_newbcast:13 row_mask:0xf bank_mask:0xf
	v_fmac_f32_dpp v228, v244, v120 row_newbcast:14 row_mask:0xf bank_mask:0xf
	v_fmac_f32_dpp v229, v245, v121 row_newbcast:14 row_mask:0xf bank_mask:0xf
	v_fmac_f32_dpp v228, v246, v122 row_newbcast:14 row_mask:0xf bank_mask:0xf
	v_fmac_f32_dpp v229, v247, v123 row_newbcast:14 row_mask:0xf bank_mask:0xf
	v_fmac_f32_dpp v228, v244, v124 row_newbcast:15 row_mask:0xf bank_mask:0xf
	v_fmac_f32_dpp v229, v245, v125 row_newbcast:15 row_mask:0xf bank_mask:0xf
	v_fmac_f32_dpp v228, v246, v126 row_newbcast:15 row_mask:0xf bank_mask:0xf
	v_fmac_f32_dpp v229, v247, v127 row_newbcast:15 row_mask:0xf bank_mask:0xf
	v_sub_f32_e64 v232, -v224, v225
	v_sub_f32_e64 v233, -v228, v229
	s_waitcnt lgkmcnt(0)
	v_mfma_f32_4x4x1_16b_f32 v[0:3], v128, v232, v[0:3]
	v_mfma_f32_4x4x1_16b_f32 v[4:7], v129, v232, v[4:7]
	v_mfma_f32_4x4x1_16b_f32 v[8:11], v130, v232, v[8:11]
	v_mfma_f32_4x4x1_16b_f32 v[12:15], v131, v232, v[12:15]
	v_mfma_f32_4x4x1_16b_f32 v[16:19], v132, v232, v[16:19]
	v_mfma_f32_4x4x1_16b_f32 v[20:23], v133, v232, v[20:23]
	v_mfma_f32_4x4x1_16b_f32 v[24:27], v134, v232, v[24:27]
	v_mfma_f32_4x4x1_16b_f32 v[28:31], v135, v232, v[28:31]
	v_mfma_f32_4x4x1_16b_f32 v[32:35], v136, v232, v[32:35]
	v_mfma_f32_4x4x1_16b_f32 v[36:39], v137, v232, v[36:39]
	v_mfma_f32_4x4x1_16b_f32 v[40:43], v138, v232, v[40:43]
	v_mfma_f32_4x4x1_16b_f32 v[44:47], v139, v232, v[44:47]
	v_mfma_f32_4x4x1_16b_f32 v[48:51], v140, v232, v[48:51]
	v_mfma_f32_4x4x1_16b_f32 v[52:55], v141, v232, v[52:55]
	v_mfma_f32_4x4x1_16b_f32 v[56:59], v142, v232, v[56:59]
	v_mfma_f32_4x4x1_16b_f32 v[60:63], v143, v232, v[60:63]
	v_mfma_f32_4x4x1_16b_f32 v[0:3], v144, v174, v[0:3]
	v_mfma_f32_4x4x1_16b_f32 v[4:7], v145, v174, v[4:7]
	v_mfma_f32_4x4x1_16b_f32 v[8:11], v146, v174, v[8:11]
	v_mfma_f32_4x4x1_16b_f32 v[12:15], v147, v174, v[12:15]
	v_mfma_f32_4x4x1_16b_f32 v[16:19], v148, v174, v[16:19]
	v_mfma_f32_4x4x1_16b_f32 v[20:23], v149, v174, v[20:23]
	v_mfma_f32_4x4x1_16b_f32 v[24:27], v150, v174, v[24:27]
	v_mfma_f32_4x4x1_16b_f32 v[28:31], v151, v174, v[28:31]
	v_mfma_f32_4x4x1_16b_f32 v[32:35], v152, v174, v[32:35]
	v_mfma_f32_4x4x1_16b_f32 v[36:39], v153, v174, v[36:39]
	v_mfma_f32_4x4x1_16b_f32 v[40:43], v154, v174, v[40:43]
	v_mfma_f32_4x4x1_16b_f32 v[44:47], v155, v174, v[44:47]
	v_mfma_f32_4x4x1_16b_f32 v[48:51], v156, v174, v[48:51]
	v_mfma_f32_4x4x1_16b_f32 v[52:55], v157, v174, v[52:55]
	v_mfma_f32_4x4x1_16b_f32 v[56:59], v158, v174, v[56:59]
	v_mfma_f32_4x4x1_16b_f32 v[60:63], v159, v174, v[60:63]
	v_mfma_f32_4x4x1_16b_f32 v[64:67], v128, v233, v[64:67]
	v_mfma_f32_4x4x1_16b_f32 v[68:71], v129, v233, v[68:71]
	v_mfma_f32_4x4x1_16b_f32 v[72:75], v130, v233, v[72:75]
	v_mfma_f32_4x4x1_16b_f32 v[76:79], v131, v233, v[76:79]
	v_mfma_f32_4x4x1_16b_f32 v[80:83], v132, v233, v[80:83]
	v_mfma_f32_4x4x1_16b_f32 v[84:87], v133, v233, v[84:87]
	v_mfma_f32_4x4x1_16b_f32 v[88:91], v134, v233, v[88:91]
	v_mfma_f32_4x4x1_16b_f32 v[92:95], v135, v233, v[92:95]
	v_mfma_f32_4x4x1_16b_f32 v[96:99], v136, v233, v[96:99]
	v_mfma_f32_4x4x1_16b_f32 v[100:103], v137, v233, v[100:103]
	v_mfma_f32_4x4x1_16b_f32 v[104:107], v138, v233, v[104:107]
;     static __device__ __forceinline__ void updS(float (&S)[64], const In1& in, float sa, float vv) {
;         float t0, t1, t2, t3;
;         asm volatile("v_mul_f32_dpp %0, %8, %21 row_newbcast:%22" DPPM "v_mul_f32_dpp %1, %9, %21 row_newbcast:%22" DPPM "v_mul_f32_dpp %2, %10, %21 row_newbcast:%22" DPPM "v_mul_f32_dpp %3, %11, %21 row_newbcast:%22" DPPM
;                      "v_fmac_f32_dpp %0, %12, %4 row_newbcast:%22" DPPM "v_fmac_f32_dpp %1, %13, %5 row_newbcast:%22" DPPM "v_fmac_f32_dpp %2, %14, %6 row_newbcast:%22" DPPM "v_fmac_f32_dpp %3, %15, %7 row_newbcast:%22" DPPM
;                      "v_fmac_f32_dpp %0, %16, %20 row_newbcast:%22" DPPM "v_fmac_f32_dpp %1, %17, %20 row_newbcast:%22" DPPM "v_fmac_f32_dpp %2, %18, %20 row_newbcast:%22" DPPM "v_fmac_f32_dpp %3, %19, %20 row_newbcast:%22" DPPM
;                      : "=&v"(t0), "=&v"(t1), "=&v"(t2), "=&v"(t3)
;                      : "v"(S[K]), "v"(S[K + 1]), "v"(S[K + 2]), "v"(S[K + 3]), "v"(in.kd[0]), "v"(in.kd[1]), "v"(in.kd[2]), "v"(in.kd[3]), "v"(in.w[0]), "v"(in.w[1]), "v"(in.w[2]), "v"(in.w[3]),
;                        "v"(in.b[0]), "v"(in.b[1]), "v"(in.b[2]), "v"(in.b[3]), "v"(sa), "v"(vv), "n"(N0));
;         S[K] = t0; S[K + 1] = t1; S[K + 2] = t2; S[K + 3] = t3;
;         if constexpr (K + 4 < 64) ScanK<K + 4>::updS(S, in, sa, vv);
;     }
;     static __device__ __forceinline__ void updP(float (&P)[64], const In1& in, float sa) {
;         float u0, u1, u2, u3;
;         asm volatile("v_mul_f32_dpp %0, %8, %4 row_newbcast:%17" DPPM "v_mul_f32_dpp %1, %9, %5 row_newbcast:%17" DPPM "v_mul_f32_dpp %2, %10, %6 row_newbcast:%17" DPPM "v_mul_f32_dpp %3, %11, %7 row_newbcast:%17" DPPM
;                      "v_fmac_f32_dpp %0, %12, %16 row_newbcast:%17" DPPM "v_fmac_f32_dpp %1, %13, %16 row_newbcast:%17" DPPM "v_fmac_f32_dpp %2, %14, %16 row_newbcast:%17" DPPM "v_fmac_f32_dpp %3, %15, %16 row_newbcast:%17" DPPM
;                      : "=&v"(u0), "=&v"(u1), "=&v"(u2), "=&v"(u3)
;                      : "v"(P[K]), "v"(P[K + 1]), "v"(P[K + 2]), "v"(P[K + 3]), "v"(in.w[0]), "v"(in.w[1]), "v"(in.w[2]), "v"(in.w[3]), "v"(in.b[0]), "v"(in.b[1]), "v"(in.b[2]), "v"(in.b[3]), "v"(sa), "n"(N0));
;         P[K] = u0; P[K + 1] = u1; P[K + 2] = u2; P[K + 3] = u3;
;         if constexpr (K + 4 < 64) ScanK<K + 4>::updP(P, in, sa);
;     }
	v_mfma_f32_4x4x1_16b_f32 v[108:111], v139, v233, v[108:111]
	v_mfma_f32_4x4x1_16b_f32 v[112:115], v140, v233, v[112:115]
	v_mfma_f32_4x4x1_16b_f32 v[116:119], v141, v233, v[116:119]
	v_mfma_f32_4x4x1_16b_f32 v[120:123], v142, v233, v[120:123]
	v_mfma_f32_4x4x1_16b_f32 v[124:127], v143, v233, v[124:127]
	v_mul_f32_dpp v0, v236, v0 row_newbcast:0 row_mask:0xf bank_mask:0xf
	v_mul_f32_dpp v1, v237, v1 row_newbcast:0 row_mask:0xf bank_mask:0xf
	v_mul_f32_dpp v2, v238, v2 row_newbcast:0 row_mask:0xf bank_mask:0xf
	v_mul_f32_dpp v3, v239, v3 row_newbcast:0 row_mask:0xf bank_mask:0xf
	v_mul_f32_dpp v4, v236, v4 row_newbcast:1 row_mask:0xf bank_mask:0xf
	v_mul_f32_dpp v5, v237, v5 row_newbcast:1 row_mask:0xf bank_mask:0xf
	v_mul_f32_dpp v6, v238, v6 row_newbcast:1 row_mask:0xf bank_mask:0xf
	v_mul_f32_dpp v7, v239, v7 row_newbcast:1 row_mask:0xf bank_mask:0xf
	v_mul_f32_dpp v8, v236, v8 row_newbcast:2 row_mask:0xf bank_mask:0xf
	v_mul_f32_dpp v9, v237, v9 row_newbcast:2 row_mask:0xf bank_mask:0xf
	v_mul_f32_dpp v10, v238, v10 row_newbcast:2 row_mask:0xf bank_mask:0xf
	v_mul_f32_dpp v11, v239, v11 row_newbcast:2 row_mask:0xf bank_mask:0xf
	v_mul_f32_dpp v12, v236, v12 row_newbcast:3 row_mask:0xf bank_mask:0xf
	v_mul_f32_dpp v13, v237, v13 row_newbcast:3 row_mask:0xf bank_mask:0xf
	v_mul_f32_dpp v14, v238, v14 row_newbcast:3 row_mask:0xf bank_mask:0xf
	v_mul_f32_dpp v15, v239, v15 row_newbcast:3 row_mask:0xf bank_mask:0xf
	v_mul_f32_dpp v16, v236, v16 row_newbcast:4 row_mask:0xf bank_mask:0xf
	v_mul_f32_dpp v17, v237, v17 row_newbcast:4 row_mask:0xf bank_mask:0xf
	v_mul_f32_dpp v18, v238, v18 row_newbcast:4 row_mask:0xf bank_mask:0xf
	v_mul_f32_dpp v19, v239, v19 row_newbcast:4 row_mask:0xf bank_mask:0xf
	v_mul_f32_dpp v20, v236, v20 row_newbcast:5 row_mask:0xf bank_mask:0xf
	v_mul_f32_dpp v21, v237, v21 row_newbcast:5 row_mask:0xf bank_mask:0xf
	v_mul_f32_dpp v22, v238, v22 row_newbcast:5 row_mask:0xf bank_mask:0xf
	v_mul_f32_dpp v23, v239, v23 row_newbcast:5 row_mask:0xf bank_mask:0xf
	v_mul_f32_dpp v24, v236, v24 row_newbcast:6 row_mask:0xf bank_mask:0xf
	v_mul_f32_dpp v25, v237, v25 row_newbcast:6 row_mask:0xf bank_mask:0xf
	v_mul_f32_dpp v26, v238, v26 row_newbcast:6 row_mask:0xf bank_mask:0xf
	v_mul_f32_dpp v27, v239, v27 row_newbcast:6 row_mask:0xf bank_mask:0xf
	v_mul_f32_dpp v28, v236, v28 row_newbcast:7 row_mask:0xf bank_mask:0xf
	v_mul_f32_dpp v29, v237, v29 row_newbcast:7 row_mask:0xf bank_mask:0xf
	v_mul_f32_dpp v30, v238, v30 row_newbcast:7 row_mask:0xf bank_mask:0xf
	v_mul_f32_dpp v31, v239, v31 row_newbcast:7 row_mask:0xf bank_mask:0xf
	v_mul_f32_dpp v32, v236, v32 row_newbcast:8 row_mask:0xf bank_mask:0xf
	v_mul_f32_dpp v33, v237, v33 row_newbcast:8 row_mask:0xf bank_mask:0xf
	v_mul_f32_dpp v34, v238, v34 row_newbcast:8 row_mask:0xf bank_mask:0xf
	v_mul_f32_dpp v35, v239, v35 row_newbcast:8 row_mask:0xf bank_mask:0xf
	v_mul_f32_dpp v36, v236, v36 row_newbcast:9 row_mask:0xf bank_mask:0xf
	v_mul_f32_dpp v37, v237, v37 row_newbcast:9 row_mask:0xf bank_mask:0xf
	v_mul_f32_dpp v38, v238, v38 row_newbcast:9 row_mask:0xf bank_mask:0xf
	v_mul_f32_dpp v39, v239, v39 row_newbcast:9 row_mask:0xf bank_mask:0xf
	v_mul_f32_dpp v40, v236, v40 row_newbcast:10 row_mask:0xf bank_mask:0xf
	v_mul_f32_dpp v41, v237, v41 row_newbcast:10 row_mask:0xf bank_mask:0xf
	v_mul_f32_dpp v42, v238, v42 row_newbcast:10 row_mask:0xf bank_mask:0xf
	v_mul_f32_dpp v43, v239, v43 row_newbcast:10 row_mask:0xf bank_mask:0xf
	v_mul_f32_dpp v44, v236, v44 row_newbcast:11 row_mask:0xf bank_mask:0xf
	v_mul_f32_dpp v45, v237, v45 row_newbcast:11 row_mask:0xf bank_mask:0xf
	v_mul_f32_dpp v46, v238, v46 row_newbcast:11 row_mask:0xf bank_mask:0xf
	v_mul_f32_dpp v47, v239, v47 row_newbcast:11 row_mask:0xf bank_mask:0xf
	v_mul_f32_dpp v48, v236, v48 row_newbcast:12 row_mask:0xf bank_mask:0xf
	v_mul_f32_dpp v49, v237, v49 row_newbcast:12 row_mask:0xf bank_mask:0xf
	v_mul_f32_dpp v50, v238, v50 row_newbcast:12 row_mask:0xf bank_mask:0xf
	v_mul_f32_dpp v51, v239, v51 row_newbcast:12 row_mask:0xf bank_mask:0xf
	v_mul_f32_dpp v52, v236, v52 row_newbcast:13 row_mask:0xf bank_mask:0xf
	v_mul_f32_dpp v53, v237, v53 row_newbcast:13 row_mask:0xf bank_mask:0xf
	v_mul_f32_dpp v54, v238, v54 row_newbcast:13 row_mask:0xf bank_mask:0xf
	v_mul_f32_dpp v55, v239, v55 row_newbcast:13 row_mask:0xf bank_mask:0xf
	v_mul_f32_dpp v56, v236, v56 row_newbcast:14 row_mask:0xf bank_mask:0xf
	v_mul_f32_dpp v57, v237, v57 row_newbcast:14 row_mask:0xf bank_mask:0xf
	v_mul_f32_dpp v58, v238, v58 row_newbcast:14 row_mask:0xf bank_mask:0xf
	v_mul_f32_dpp v59, v239, v59 row_newbcast:14 row_mask:0xf bank_mask:0xf
	v_mul_f32_dpp v60, v236, v60 row_newbcast:15 row_mask:0xf bank_mask:0xf
	v_mul_f32_dpp v61, v237, v61 row_newbcast:15 row_mask:0xf bank_mask:0xf
	v_mul_f32_dpp v62, v238, v62 row_newbcast:15 row_mask:0xf bank_mask:0xf
	v_mul_f32_dpp v63, v239, v63 row_newbcast:15 row_mask:0xf bank_mask:0xf
	v_mul_f32_dpp v64, v236, v64 row_newbcast:0 row_mask:0xf bank_mask:0xf
	v_mul_f32_dpp v65, v237, v65 row_newbcast:0 row_mask:0xf bank_mask:0xf
	v_mul_f32_dpp v66, v238, v66 row_newbcast:0 row_mask:0xf bank_mask:0xf
	v_mul_f32_dpp v67, v239, v67 row_newbcast:0 row_mask:0xf bank_mask:0xf
	v_mul_f32_dpp v68, v236, v68 row_newbcast:1 row_mask:0xf bank_mask:0xf
	v_mul_f32_dpp v69, v237, v69 row_newbcast:1 row_mask:0xf bank_mask:0xf
	v_mul_f32_dpp v70, v238, v70 row_newbcast:1 row_mask:0xf bank_mask:0xf
	v_mul_f32_dpp v71, v239, v71 row_newbcast:1 row_mask:0xf bank_mask:0xf
	v_mul_f32_dpp v72, v236, v72 row_newbcast:2 row_mask:0xf bank_mask:0xf
	v_mul_f32_dpp v73, v237, v73 row_newbcast:2 row_mask:0xf bank_mask:0xf
;     static __device__ __forceinline__ void updS(float (&S)[64], const In1& in, float sa, float vv) {
;         float t0, t1, t2, t3;
;         asm volatile("v_mul_f32_dpp %0, %8, %21 row_newbcast:%22" DPPM "v_mul_f32_dpp %1, %9, %21 row_newbcast:%22" DPPM "v_mul_f32_dpp %2, %10, %21 row_newbcast:%22" DPPM "v_mul_f32_dpp %3, %11, %21 row_newbcast:%22" DPPM
;                      "v_fmac_f32_dpp %0, %12, %4 row_newbcast:%22" DPPM "v_fmac_f32_dpp %1, %13, %5 row_newbcast:%22" DPPM "v_fmac_f32_dpp %2, %14, %6 row_newbcast:%22" DPPM "v_fmac_f32_dpp %3, %15, %7 row_newbcast:%22" DPPM
;                      "v_fmac_f32_dpp %0, %16, %20 row_newbcast:%22" DPPM "v_fmac_f32_dpp %1, %17, %20 row_newbcast:%22" DPPM "v_fmac_f32_dpp %2, %18, %20 row_newbcast:%22" DPPM "v_fmac_f32_dpp %3, %19, %20 row_newbcast:%22" DPPM
;                      : "=&v"(t0), "=&v"(t1), "=&v"(t2), "=&v"(t3)
;                      : "v"(S[K]), "v"(S[K + 1]), "v"(S[K + 2]), "v"(S[K + 3]), "v"(in.kd[0]), "v"(in.kd[1]), "v"(in.kd[2]), "v"(in.kd[3]), "v"(in.w[0]), "v"(in.w[1]), "v"(in.w[2]), "v"(in.w[3]),
;                        "v"(in.b[0]), "v"(in.b[1]), "v"(in.b[2]), "v"(in.b[3]), "v"(sa), "v"(vv), "n"(N0));
;         S[K] = t0; S[K + 1] = t1; S[K + 2] = t2; S[K + 3] = t3;
;         if constexpr (K + 4 < 64) ScanK<K + 4>::updS(S, in, sa, vv);
;     }
;     static __device__ __forceinline__ void updP(float (&P)[64], const In1& in, float sa) {
;         float u0, u1, u2, u3;
;         asm volatile("v_mul_f32_dpp %0, %8, %4 row_newbcast:%17" DPPM "v_mul_f32_dpp %1, %9, %5 row_newbcast:%17" DPPM "v_mul_f32_dpp %2, %10, %6 row_newbcast:%17" DPPM "v_mul_f32_dpp %3, %11, %7 row_newbcast:%17" DPPM
;                      "v_fmac_f32_dpp %0, %12, %16 row_newbcast:%17" DPPM "v_fmac_f32_dpp %1, %13, %16 row_newbcast:%17" DPPM "v_fmac_f32_dpp %2, %14, %16 row_newbcast:%17" DPPM "v_fmac_f32_dpp %3, %15, %16 row_newbcast:%17" DPPM
;                      : "=&v"(u0), "=&v"(u1), "=&v"(u2), "=&v"(u3)
;                      : "v"(P[K]), "v"(P[K + 1]), "v"(P[K + 2]), "v"(P[K + 3]), "v"(in.w[0]), "v"(in.w[1]), "v"(in.w[2]), "v"(in.w[3]), "v"(in.b[0]), "v"(in.b[1]), "v"(in.b[2]), "v"(in.b[3]), "v"(sa), "n"(N0));
;         P[K] = u0; P[K + 1] = u1; P[K + 2] = u2; P[K + 3] = u3;
;         if constexpr (K + 4 < 64) ScanK<K + 4>::updP(P, in, sa);
;     }
	v_mul_f32_dpp v74, v238, v74 row_newbcast:2 row_mask:0xf bank_mask:0xf
	v_mul_f32_dpp v75, v239, v75 row_newbcast:2 row_mask:0xf bank_mask:0xf
	v_mul_f32_dpp v76, v236, v76 row_newbcast:3 row_mask:0xf bank_mask:0xf
	v_mul_f32_dpp v77, v237, v77 row_newbcast:3 row_mask:0xf bank_mask:0xf
	v_mul_f32_dpp v78, v238, v78 row_newbcast:3 row_mask:0xf bank_mask:0xf
	v_mul_f32_dpp v79, v239, v79 row_newbcast:3 row_mask:0xf bank_mask:0xf
	v_mul_f32_dpp v80, v236, v80 row_newbcast:4 row_mask:0xf bank_mask:0xf
	v_mul_f32_dpp v81, v237, v81 row_newbcast:4 row_mask:0xf bank_mask:0xf
	v_mul_f32_dpp v82, v238, v82 row_newbcast:4 row_mask:0xf bank_mask:0xf
	v_mul_f32_dpp v83, v239, v83 row_newbcast:4 row_mask:0xf bank_mask:0xf
	v_mul_f32_dpp v84, v236, v84 row_newbcast:5 row_mask:0xf bank_mask:0xf
	v_mul_f32_dpp v85, v237, v85 row_newbcast:5 row_mask:0xf bank_mask:0xf
	v_mul_f32_dpp v86, v238, v86 row_newbcast:5 row_mask:0xf bank_mask:0xf
	v_mul_f32_dpp v87, v239, v87 row_newbcast:5 row_mask:0xf bank_mask:0xf
	v_mul_f32_dpp v88, v236, v88 row_newbcast:6 row_mask:0xf bank_mask:0xf
	v_mul_f32_dpp v89, v237, v89 row_newbcast:6 row_mask:0xf bank_mask:0xf
	v_mul_f32_dpp v90, v238, v90 row_newbcast:6 row_mask:0xf bank_mask:0xf
	v_mul_f32_dpp v91, v239, v91 row_newbcast:6 row_mask:0xf bank_mask:0xf
	v_mul_f32_dpp v92, v236, v92 row_newbcast:7 row_mask:0xf bank_mask:0xf
	v_mul_f32_dpp v93, v237, v93 row_newbcast:7 row_mask:0xf bank_mask:0xf
	v_mul_f32_dpp v94, v238, v94 row_newbcast:7 row_mask:0xf bank_mask:0xf
	v_mul_f32_dpp v95, v239, v95 row_newbcast:7 row_mask:0xf bank_mask:0xf
	v_mul_f32_dpp v96, v236, v96 row_newbcast:8 row_mask:0xf bank_mask:0xf
	v_mul_f32_dpp v97, v237, v97 row_newbcast:8 row_mask:0xf bank_mask:0xf
	v_mul_f32_dpp v98, v238, v98 row_newbcast:8 row_mask:0xf bank_mask:0xf
	v_mul_f32_dpp v99, v239, v99 row_newbcast:8 row_mask:0xf bank_mask:0xf
	v_mul_f32_dpp v100, v236, v100 row_newbcast:9 row_mask:0xf bank_mask:0xf
	v_mul_f32_dpp v101, v237, v101 row_newbcast:9 row_mask:0xf bank_mask:0xf
	v_mul_f32_dpp v102, v238, v102 row_newbcast:9 row_mask:0xf bank_mask:0xf
	v_mul_f32_dpp v103, v239, v103 row_newbcast:9 row_mask:0xf bank_mask:0xf
	v_mul_f32_dpp v104, v236, v104 row_newbcast:10 row_mask:0xf bank_mask:0xf
	v_mul_f32_dpp v105, v237, v105 row_newbcast:10 row_mask:0xf bank_mask:0xf
	v_mul_f32_dpp v106, v238, v106 row_newbcast:10 row_mask:0xf bank_mask:0xf
	v_mul_f32_dpp v107, v239, v107 row_newbcast:10 row_mask:0xf bank_mask:0xf
	v_mul_f32_dpp v108, v236, v108 row_newbcast:11 row_mask:0xf bank_mask:0xf
	v_mul_f32_dpp v109, v237, v109 row_newbcast:11 row_mask:0xf bank_mask:0xf
	v_mul_f32_dpp v110, v238, v110 row_newbcast:11 row_mask:0xf bank_mask:0xf
	v_mul_f32_dpp v111, v239, v111 row_newbcast:11 row_mask:0xf bank_mask:0xf
	v_mul_f32_dpp v112, v236, v112 row_newbcast:12 row_mask:0xf bank_mask:0xf
	v_mul_f32_dpp v113, v237, v113 row_newbcast:12 row_mask:0xf bank_mask:0xf
	v_mul_f32_dpp v114, v238, v114 row_newbcast:12 row_mask:0xf bank_mask:0xf
	v_mul_f32_dpp v115, v239, v115 row_newbcast:12 row_mask:0xf bank_mask:0xf
	v_mul_f32_dpp v116, v236, v116 row_newbcast:13 row_mask:0xf bank_mask:0xf
	v_mul_f32_dpp v117, v237, v117 row_newbcast:13 row_mask:0xf bank_mask:0xf
	v_mul_f32_dpp v118, v238, v118 row_newbcast:13 row_mask:0xf bank_mask:0xf
	v_mul_f32_dpp v119, v239, v119 row_newbcast:13 row_mask:0xf bank_mask:0xf
	v_mul_f32_dpp v120, v236, v120 row_newbcast:14 row_mask:0xf bank_mask:0xf
	v_mul_f32_dpp v121, v237, v121 row_newbcast:14 row_mask:0xf bank_mask:0xf
	v_mul_f32_dpp v122, v238, v122 row_newbcast:14 row_mask:0xf bank_mask:0xf
	v_mul_f32_dpp v123, v239, v123 row_newbcast:14 row_mask:0xf bank_mask:0xf
	v_mul_f32_dpp v124, v236, v124 row_newbcast:15 row_mask:0xf bank_mask:0xf
	v_mul_f32_dpp v125, v237, v125 row_newbcast:15 row_mask:0xf bank_mask:0xf
	v_mul_f32_dpp v126, v238, v126 row_newbcast:15 row_mask:0xf bank_mask:0xf
	v_mul_f32_dpp v127, v239, v127 row_newbcast:15 row_mask:0xf bank_mask:0xf
	v_mov_b32_e32 v236, 1.0
	v_mov_b32_e32 v237, 1.0
	v_mov_b32_e32 v238, 1.0
	v_mov_b32_e32 v239, 1.0
	s_waitcnt vmcnt(0)
; #define NEXT_ITEM() (MIX ? (int)__builtin_amdgcn_readfirstlane(lane == 0 ? __hip_atomic_fetch_add(qctr, 1u, __ATOMIC_RELAXED, __HIP_MEMORY_SCOPE_AGENT) : 0u) : item + (int)gridDim.x * 8)
; template <bool MIX> __device__ __forceinline__ void scan_pass1(const Params& p, int d, float* ldsf) {
;     ...
;     for (int item = MIX ? NEXT_ITEM() : (int)(blockIdx.x * 8 + wid); item < 2 * NS; item = NEXT_ITEM()) {
;     ...
;         float* po = (isP ? PT : SLT) + ((size_t)(bh * NC + c)) * 4096 + lane * 64;
; #pragma unroll
;         for (int i = 0; i < 16; ++i) *(f32x4*)(po + 4 * i) = (f32x4){S[4 * i], S[4 * i + 1], S[4 * i + 2], S[4 * i + 3]};
	s_nop 1
	v_and_b32_e32 v128, 63, v254
	v_lshlrev_b32_e32 v129, 8, v128
	v_lshlrev_b32_e32 v130, 2, v128
	global_store_dwordx4 v129, v[0:3], s[90:91] offset:0
	global_store_dwordx4 v129, v[4:7], s[90:91] offset:16
	global_store_dwordx4 v129, v[8:11], s[90:91] offset:32
	global_store_dwordx4 v129, v[12:15], s[90:91] offset:48
	global_store_dwordx4 v129, v[16:19], s[90:91] offset:64
	global_store_dwordx4 v129, v[20:23], s[90:91] offset:80
	global_store_dwordx4 v129, v[24:27], s[90:91] offset:96
	global_store_dwordx4 v129, v[28:31], s[90:91] offset:112
	global_store_dwordx4 v129, v[32:35], s[90:91] offset:128
	global_store_dwordx4 v129, v[36:39], s[90:91] offset:144
	global_store_dwordx4 v129, v[40:43], s[90:91] offset:160
	global_store_dwordx4 v129, v[44:47], s[90:91] offset:176
	global_store_dwordx4 v129, v[48:51], s[90:91] offset:192
	global_store_dwordx4 v129, v[52:55], s[90:91] offset:208
	global_store_dwordx4 v129, v[56:59], s[90:91] offset:224
	global_store_dwordx4 v129, v[60:63], s[90:91] offset:240
	global_store_dword v130, v64, s[92:93] offset:0
	global_store_dword v130, v65, s[92:93] offset:256
	global_store_dword v130, v66, s[92:93] offset:512
	global_store_dword v130, v67, s[92:93] offset:768
	global_store_dword v130, v68, s[92:93] offset:1024
	global_store_dword v130, v69, s[92:93] offset:1280
	global_store_dword v130, v70, s[92:93] offset:1536
	global_store_dword v130, v71, s[92:93] offset:1792
	global_store_dword v130, v72, s[92:93] offset:2048
	global_store_dword v130, v73, s[92:93] offset:2304
	global_store_dword v130, v74, s[92:93] offset:2560
	global_store_dword v130, v75, s[92:93] offset:2816
	global_store_dword v130, v76, s[92:93] offset:3072
	global_store_dword v130, v77, s[92:93] offset:3328
	global_store_dword v130, v78, s[92:93] offset:3584
	global_store_dword v130, v79, s[92:93] offset:3840
	s_add_u32 s92, s92, 0x1000
	s_addc_u32 s93, s93, 0
	global_store_dword v130, v80, s[92:93] offset:0
	global_store_dword v130, v81, s[92:93] offset:256
	global_store_dword v130, v82, s[92:93] offset:512
	global_store_dword v130, v83, s[92:93] offset:768
	global_store_dword v130, v84, s[92:93] offset:1024
	global_store_dword v130, v85, s[92:93] offset:1280
	global_store_dword v130, v86, s[92:93] offset:1536
	global_store_dword v130, v87, s[92:93] offset:1792
	global_store_dword v130, v88, s[92:93] offset:2048
	global_store_dword v130, v89, s[92:93] offset:2304
	global_store_dword v130, v90, s[92:93] offset:2560
	global_store_dword v130, v91, s[92:93] offset:2816
	global_store_dword v130, v92, s[92:93] offset:3072
	global_store_dword v130, v93, s[92:93] offset:3328
	global_store_dword v130, v94, s[92:93] offset:3584
	global_store_dword v130, v95, s[92:93] offset:3840
	s_add_u32 s92, s92, 0x1000
	s_addc_u32 s93, s93, 0
	global_store_dword v130, v96, s[92:93] offset:0
	global_store_dword v130, v97, s[92:93] offset:256
	global_store_dword v130, v98, s[92:93] offset:512
	global_store_dword v130, v99, s[92:93] offset:768
	global_store_dword v130, v100, s[92:93] offset:1024
	global_store_dword v130, v101, s[92:93] offset:1280
	global_store_dword v130, v102, s[92:93] offset:1536
	global_store_dword v130, v103, s[92:93] offset:1792
	global_store_dword v130, v104, s[92:93] offset:2048
	global_store_dword v130, v105, s[92:93] offset:2304
	global_store_dword v130, v106, s[92:93] offset:2560
	global_store_dword v130, v107, s[92:93] offset:2816
	global_store_dword v130, v108, s[92:93] offset:3072
	global_store_dword v130, v109, s[92:93] offset:3328
	global_store_dword v130, v110, s[92:93] offset:3584
	global_store_dword v130, v111, s[92:93] offset:3840
	s_add_u32 s92, s92, 0x1000
	s_addc_u32 s93, s93, 0
	global_store_dword v130, v112, s[92:93] offset:0
	global_store_dword v130, v113, s[92:93] offset:256
	global_store_dword v130, v114, s[92:93] offset:512
	global_store_dword v130, v115, s[92:93] offset:768
	global_store_dword v130, v116, s[92:93] offset:1024
	global_store_dword v130, v117, s[92:93] offset:1280
	global_store_dword v130, v118, s[92:93] offset:1536
	global_store_dword v130, v119, s[92:93] offset:1792
	global_store_dword v130, v120, s[92:93] offset:2048
	global_store_dword v130, v121, s[92:93] offset:2304
	global_store_dword v130, v122, s[92:93] offset:2560
	global_store_dword v130, v123, s[92:93] offset:2816
	global_store_dword v130, v124, s[92:93] offset:3072
	global_store_dword v130, v125, s[92:93] offset:3328
	global_store_dword v130, v126, s[92:93] offset:3584
	global_store_dword v130, v127, s[92:93] offset:3840
	s_nop 1
	s_lshl_b32 s6, s96, 3
	s_add_i32 s0, s0, s6
	s_branch .Lmy_p1d0_item

; #define NEXT_ITEM() (MIX ? (int)__builtin_amdgcn_readfirstlane(lane == 0 ? __hip_atomic_fetch_add(qctr, 1u, __ATOMIC_RELAXED, __HIP_MEMORY_SCOPE_AGENT) : 0u) : item + (int)gridDim.x * 8)
; #define MKR(ptr) __builtin_amdgcn_make_buffer_rsrc((void*)(ptr), 0, 0x7fffffff, 0x00027000)
; #define LD1(set, s) { const int e_ = min((int)(s), LC - 1) * (int)stp; const unsigned s4_ = ob4 + (unsigned)(e_ * 4), s2_ = ob2 + (unsigned)(e_ * 2); set.w = LDX(rW, s4_); set.a = LDX(rA, s4_); set.b = LDX(rB, s4_); \
;             set.kw = __builtin_amdgcn_raw_buffer_load_b64(rK, lo8, s2_, 0); set.v = __builtin_amdgcn_raw_buffer_load_b16(rV, lo2, s2_, 0); }
; #define LD1(set, s) { const int e_ = min((int)(s), LC - 1) * (int)stp; const unsigned s4_ = ob4 + (unsigned)(e_ * 4); set.w = LDX(rW, s4_); set.a = LDX(rA, s4_); set.b = LDX(rB, s4_); }
; template <bool MIX> __device__ __forceinline__ void scan_pass1(const Params& p, int d, float* ldsf) {
;     ...
;     for (int item = MIX ? NEXT_ITEM() : (int)(blockIdx.x * 8 + wid); item < 2 * NS; item = NEXT_ITEM()) {
;         const bool isP = item >= NS; const int idx = isP ? item - NS : item;
;         const int bh = idx / (NC - 1), c = idx - bh * (NC - 1), b = bh >> 4, h = bh & 15;
;         const int t0 = d ? (SEQ - 1 - c * LC) : c * LC;
;         const size_t off0 = ((size_t)(b * SEQ + t0)) * RW + h * 64; const long stp = d ? -(long)RW : (long)RW;
;         const unsigned ob4 = (unsigned)(off0 * 4), ob2 = (unsigned)(off0 * 2);
;         const f32x4 ka4 = *(const f32x4*)(p.k_a + h * 64 + (lane & 15) * 4), c04 = 1.0f - ka4;
;         float S[64]; int ln = lane; asm volatile("" : "+v"(ln));
;     ...
;         const __amdgpu_buffer_rsrc_t rW = MKR(Wd), rA = MKR(A), rB = MKR(Bd), rK = MKR(KB), rV = MKR(V);
;         if (!isP) {
; #pragma unroll
;             for (int i = 0; i < 64; ++i) S[i] = 0.f;
;     ...
;             In1 i0, i1; LD1(i0, 0);
;     ...
; #pragma unroll
;             for (int i = 0; i < 64; ++i) S[i] = (ln == i) ? 1.f : 0.f;
.Lmy_p1d1_item:
	s_cmpk_gt_i32 s0, 0x7df
	s_cbranch_scc1 .Lmy_p1d1_end
	s_mul_i32 s86, s0, 2081
	s_lshr_b32 s86, s86, 17
	s_mul_i32 s7, s86, 63
	s_sub_u32 s85, s0, s7
	s_and_b32 s87, s86, 15
	s_lshr_b32 s6, s86, 4
	s_lshl_b32 s6, s6, 14
	s_lshl_b32 s7, s85, 8
	s_sub_u32 s7, 0x3fff, s7
	s_add_u32 s6, s6, s7
	s_lshl_b32 s6, s6, 10
	s_lshl_b32 s7, s87, 6
	s_add_u32 s84, s6, s7
	s_lshl_b32 s72, s84, 2
	s_lshl_b32 s76, s84, 1
	s_lshl_b32 s6, s86, 6
	s_add_u32 s6, s6, s85
	s_lshl_b32 s6, s6, 14
	s_add_u32 s7, s6, 0x15800000
	s_add_u32 s90, s56, s7
	s_addc_u32 s91, s57, 0
	s_add_u32 s7, s6, 0x13800000
	s_add_u32 s92, s56, s7
	s_addc_u32 s93, s57, 0
	s_lshl_b32 s8, s87, 8
	s_add_u32 s4, s42, s8
	s_addc_u32 s5, s43, 0
	v_and_b32_e32 v129, 15, v254
	v_lshlrev_b32_e32 v130, 4, v129
	global_load_dwordx4 v[216:219], v130, s[4:5]
	v_mov_b32_e32 v174, 0
	v_mov_b32_e32 v190, 0
	v_mov_b32_e32 v206, 0
	buffer_load_dwordx4 v[160:163], v235, s[64:67], s72 offen
	buffer_load_dwordx4 v[164:167], v250, s[64:67], s72 offen
	buffer_load_dwordx4 v[168:171], v251, s[64:67], s72 offen
	buffer_load_dwordx2 v[172:173], v252, s[64:67], s76 offen
	buffer_load_short_d16_hi v174, v253, s[64:67], s76 offen
	s_add_i32 s72, s72, 0xfffff000
	s_max_i32 s72, s72, 0
	s_add_i32 s76, s76, 0xfffff800
	s_max_i32 s76, s76, 0
	buffer_load_dwordx4 v[176:179], v235, s[64:67], s72 offen
	buffer_load_dwordx4 v[180:183], v250, s[64:67], s72 offen
	buffer_load_dwordx4 v[184:187], v251, s[64:67], s72 offen
	buffer_load_dwordx2 v[188:189], v252, s[64:67], s76 offen
	buffer_load_short_d16_hi v190, v253, s[64:67], s76 offen
	s_add_i32 s72, s72, 0xfffff000
	s_max_i32 s72, s72, 0
	s_add_i32 s76, s76, 0xfffff800
	s_max_i32 s76, s76, 0
	v_and_b32_e32 v128, 63, v254
	v_mov_b32_e32 v129, 1.0
	v_mov_b32_e32 v0, 0
	v_mov_b32_e32 v1, 0
	v_mov_b32_e32 v2, 0
	v_mov_b32_e32 v3, 0
	v_mov_b32_e32 v4, 0
	v_mov_b32_e32 v5, 0
	v_mov_b32_e32 v6, 0
	v_mov_b32_e32 v7, 0
	v_mov_b32_e32 v8, 0
	v_mov_b32_e32 v9, 0
	v_mov_b32_e32 v10, 0
	v_mov_b32_e32 v11, 0
	v_mov_b32_e32 v12, 0
	v_mov_b32_e32 v13, 0
	v_mov_b32_e32 v14, 0
	v_mov_b32_e32 v15, 0
	v_mov_b32_e32 v16, 0
	v_mov_b32_e32 v17, 0
	v_mov_b32_e32 v18, 0
	v_mov_b32_e32 v19, 0
	v_mov_b32_e32 v20, 0
	v_mov_b32_e32 v21, 0
	v_mov_b32_e32 v22, 0
	v_mov_b32_e32 v23, 0
	v_mov_b32_e32 v24, 0
	v_mov_b32_e32 v25, 0
	v_mov_b32_e32 v26, 0
	v_mov_b32_e32 v27, 0
	v_mov_b32_e32 v28, 0
	v_mov_b32_e32 v29, 0
	v_mov_b32_e32 v30, 0
	v_mov_b32_e32 v31, 0
	v_mov_b32_e32 v32, 0
	v_mov_b32_e32 v33, 0
	v_mov_b32_e32 v34, 0
	v_mov_b32_e32 v35, 0
	v_mov_b32_e32 v36, 0
	v_mov_b32_e32 v37, 0
	v_mov_b32_e32 v38, 0
	v_mov_b32_e32 v39, 0
	v_mov_b32_e32 v40, 0
	v_mov_b32_e32 v41, 0
	v_mov_b32_e32 v42, 0
	v_mov_b32_e32 v43, 0
	v_mov_b32_e32 v44, 0
	v_mov_b32_e32 v45, 0
	v_mov_b32_e32 v46, 0
	v_mov_b32_e32 v47, 0
	v_mov_b32_e32 v48, 0
	v_mov_b32_e32 v49, 0
	v_mov_b32_e32 v50, 0
	v_mov_b32_e32 v51, 0
	v_mov_b32_e32 v52, 0
	v_mov_b32_e32 v53, 0
	v_mov_b32_e32 v54, 0
	v_mov_b32_e32 v55, 0
	v_mov_b32_e32 v56, 0
	v_mov_b32_e32 v57, 0
	v_mov_b32_e32 v58, 0
	v_mov_b32_e32 v59, 0
	v_mov_b32_e32 v60, 0
	v_mov_b32_e32 v61, 0
	v_mov_b32_e32 v62, 0
	v_mov_b32_e32 v63, 0
	v_cmp_eq_u32_e32 vcc, 0, v128
	s_nop 1
	v_cndmask_b32_e32 v64, 0, v129, vcc
	v_cmp_eq_u32_e32 vcc, 1, v128
	s_nop 1
	v_cndmask_b32_e32 v65, 0, v129, vcc
	v_cmp_eq_u32_e32 vcc, 2, v128
	s_nop 1
	v_cndmask_b32_e32 v66, 0, v129, vcc
	v_cmp_eq_u32_e32 vcc, 3, v128
	s_nop 1
	v_cndmask_b32_e32 v67, 0, v129, vcc
	v_cmp_eq_u32_e32 vcc, 4, v128
	s_nop 1
	v_cndmask_b32_e32 v68, 0, v129, vcc
	v_cmp_eq_u32_e32 vcc, 5, v128
	s_nop 1
	v_cndmask_b32_e32 v69, 0, v129, vcc
	v_cmp_eq_u32_e32 vcc, 6, v128
	s_nop 1
	v_cndmask_b32_e32 v70, 0, v129, vcc
	v_cmp_eq_u32_e32 vcc, 7, v128
	s_nop 1
	v_cndmask_b32_e32 v71, 0, v129, vcc
	v_cmp_eq_u32_e32 vcc, 8, v128
	s_nop 1
	v_cndmask_b32_e32 v72, 0, v129, vcc
	v_cmp_eq_u32_e32 vcc, 9, v128
	s_nop 1
	v_cndmask_b32_e32 v73, 0, v129, vcc
	v_cmp_eq_u32_e32 vcc, 10, v128
	s_nop 1
	v_cndmask_b32_e32 v74, 0, v129, vcc
	v_cmp_eq_u32_e32 vcc, 11, v128
	s_nop 1
	v_cndmask_b32_e32 v75, 0, v129, vcc
	v_cmp_eq_u32_e32 vcc, 12, v128
	s_nop 1
	v_cndmask_b32_e32 v76, 0, v129, vcc
	v_cmp_eq_u32_e32 vcc, 13, v128
	s_nop 1
	v_cndmask_b32_e32 v77, 0, v129, vcc
; #define SB __builtin_amdgcn_sched_barrier(0)
; #define MKR(ptr) __builtin_amdgcn_make_buffer_rsrc((void*)(ptr), 0, 0x7fffffff, 0x00027000)
; #define LD1(set, s) { const int e_ = min((int)(s), LC - 1) * (int)stp; const unsigned s4_ = ob4 + (unsigned)(e_ * 4), s2_ = ob2 + (unsigned)(e_ * 2); set.w = LDX(rW, s4_); set.a = LDX(rA, s4_); set.b = LDX(rB, s4_); \
;             set.kw = __builtin_amdgcn_raw_buffer_load_b64(rK, lo8, s2_, 0); set.v = __builtin_amdgcn_raw_buffer_load_b16(rV, lo2, s2_, 0); }
; #define TOUCH1(set) asm volatile("" :: "v"(set.w), "v"(set.a), "v"(set.b), "v"(set.kw), "v"(set.v))
; #define ST1(set) { DERIVE_BK(set); float sd[4]; ScanK<0>::dot(S, set.a, sd); ScanK<0>::updS(S, set, -((sd[0] + sd[1]) + (sd[2] + sd[3])), __uint_as_float(set.v << 16)); }
; #define LD1(set, s) { const int e_ = min((int)(s), LC - 1) * (int)stp; const unsigned s4_ = ob4 + (unsigned)(e_ * 4); set.w = LDX(rW, s4_); set.a = LDX(rA, s4_); set.b = LDX(rB, s4_); }
; #define TOUCH1(set) asm volatile("" :: "v"(set.w), "v"(set.a), "v"(set.b))
; #define ST1(set) { DERIVE_B(set); float sd[4]; ScanK<0>::dot(S, set.a, sd); ScanK<0>::updP(S, set, -((sd[0] + sd[1]) + (sd[2] + sd[3]))); }
; template <bool MIX> __device__ __forceinline__ void scan_pass1(const Params& p, int d, float* ldsf) {
;     ...
;         const f32x4 ka4 = *(const f32x4*)(p.k_a + h * 64 + (lane & 15) * 4), c04 = 1.0f - ka4;
;         float S[64]; int ln = lane; asm volatile("" : "+v"(ln));
;     ...
;         const __amdgpu_buffer_rsrc_t rW = MKR(Wd), rA = MKR(A), rB = MKR(Bd), rK = MKR(KB), rV = MKR(V);
;         if (!isP) {
; #pragma unroll
;             for (int i = 0; i < 64; ++i) S[i] = 0.f;
;     ...
;             In1 i0, i1; LD1(i0, 0);
; #pragma unroll 1
;             for (int s = 0; s < LC; s += 2) { TOUCH1(i0); SB; LD1(i1, s + 1); SB; ST1(i0); TOUCH1(i1); SB; LD1(i0, s + 2); SB; ST1(i1); }
;     ...
;         } else {
; #pragma unroll
;             for (int i = 0; i < 64; ++i) S[i] = (ln == i) ? 1.f : 0.f;
;     ...
;             In1 i0, i1; LD1(i0, 0);
	v_cmp_eq_u32_e32 vcc, 14, v128
	s_nop 1
	v_cndmask_b32_e32 v78, 0, v129, vcc
	v_cmp_eq_u32_e32 vcc, 15, v128
	s_nop 1
	v_cndmask_b32_e32 v79, 0, v129, vcc
	v_cmp_eq_u32_e32 vcc, 16, v128
	s_nop 1
	v_cndmask_b32_e32 v80, 0, v129, vcc
	v_cmp_eq_u32_e32 vcc, 17, v128
	s_nop 1
	v_cndmask_b32_e32 v81, 0, v129, vcc
	v_cmp_eq_u32_e32 vcc, 18, v128
	s_nop 1
	v_cndmask_b32_e32 v82, 0, v129, vcc
	v_cmp_eq_u32_e32 vcc, 19, v128
	s_nop 1
	v_cndmask_b32_e32 v83, 0, v129, vcc
	v_cmp_eq_u32_e32 vcc, 20, v128
	s_nop 1
	v_cndmask_b32_e32 v84, 0, v129, vcc
	v_cmp_eq_u32_e32 vcc, 21, v128
	s_nop 1
	v_cndmask_b32_e32 v85, 0, v129, vcc
	v_cmp_eq_u32_e32 vcc, 22, v128
	s_nop 1
	v_cndmask_b32_e32 v86, 0, v129, vcc
	v_cmp_eq_u32_e32 vcc, 23, v128
	s_nop 1
	v_cndmask_b32_e32 v87, 0, v129, vcc
	v_cmp_eq_u32_e32 vcc, 24, v128
	s_nop 1
	v_cndmask_b32_e32 v88, 0, v129, vcc
	v_cmp_eq_u32_e32 vcc, 25, v128
	s_nop 1
	v_cndmask_b32_e32 v89, 0, v129, vcc
	v_cmp_eq_u32_e32 vcc, 26, v128
	s_nop 1
	v_cndmask_b32_e32 v90, 0, v129, vcc
	v_cmp_eq_u32_e32 vcc, 27, v128
	s_nop 1
	v_cndmask_b32_e32 v91, 0, v129, vcc
	v_cmp_eq_u32_e32 vcc, 28, v128
	s_nop 1
	v_cndmask_b32_e32 v92, 0, v129, vcc
	v_cmp_eq_u32_e32 vcc, 29, v128
	s_nop 1
	v_cndmask_b32_e32 v93, 0, v129, vcc
	v_cmp_eq_u32_e32 vcc, 30, v128
	s_nop 1
	v_cndmask_b32_e32 v94, 0, v129, vcc
	v_cmp_eq_u32_e32 vcc, 31, v128
	s_nop 1
	v_cndmask_b32_e32 v95, 0, v129, vcc
	v_cmp_eq_u32_e32 vcc, 32, v128
	s_nop 1
	v_cndmask_b32_e32 v96, 0, v129, vcc
	v_cmp_eq_u32_e32 vcc, 33, v128
	s_nop 1
	v_cndmask_b32_e32 v97, 0, v129, vcc
	v_cmp_eq_u32_e32 vcc, 34, v128
	s_nop 1
	v_cndmask_b32_e32 v98, 0, v129, vcc
	v_cmp_eq_u32_e32 vcc, 35, v128
	s_nop 1
	v_cndmask_b32_e32 v99, 0, v129, vcc
	v_cmp_eq_u32_e32 vcc, 36, v128
	s_nop 1
	v_cndmask_b32_e32 v100, 0, v129, vcc
	v_cmp_eq_u32_e32 vcc, 37, v128
	s_nop 1
	v_cndmask_b32_e32 v101, 0, v129, vcc
	v_cmp_eq_u32_e32 vcc, 38, v128
	s_nop 1
	v_cndmask_b32_e32 v102, 0, v129, vcc
	v_cmp_eq_u32_e32 vcc, 39, v128
	s_nop 1
	v_cndmask_b32_e32 v103, 0, v129, vcc
	v_cmp_eq_u32_e32 vcc, 40, v128
	s_nop 1
	v_cndmask_b32_e32 v104, 0, v129, vcc
	v_cmp_eq_u32_e32 vcc, 41, v128
	s_nop 1
	v_cndmask_b32_e32 v105, 0, v129, vcc
	v_cmp_eq_u32_e32 vcc, 42, v128
	s_nop 1
	v_cndmask_b32_e32 v106, 0, v129, vcc
	v_cmp_eq_u32_e32 vcc, 43, v128
	s_nop 1
	v_cndmask_b32_e32 v107, 0, v129, vcc
	v_cmp_eq_u32_e32 vcc, 44, v128
	s_nop 1
	v_cndmask_b32_e32 v108, 0, v129, vcc
	v_cmp_eq_u32_e32 vcc, 45, v128
	s_nop 1
	v_cndmask_b32_e32 v109, 0, v129, vcc
	v_cmp_eq_u32_e32 vcc, 46, v128
	s_nop 1
	v_cndmask_b32_e32 v110, 0, v129, vcc
	v_cmp_eq_u32_e32 vcc, 47, v128
	s_nop 1
	v_cndmask_b32_e32 v111, 0, v129, vcc
	v_cmp_eq_u32_e32 vcc, 48, v128
	s_nop 1
	v_cndmask_b32_e32 v112, 0, v129, vcc
	v_cmp_eq_u32_e32 vcc, 49, v128
	s_nop 1
	v_cndmask_b32_e32 v113, 0, v129, vcc
	v_cmp_eq_u32_e32 vcc, 50, v128
	s_nop 1
	v_cndmask_b32_e32 v114, 0, v129, vcc
	v_cmp_eq_u32_e32 vcc, 51, v128
	s_nop 1
	v_cndmask_b32_e32 v115, 0, v129, vcc
	v_cmp_eq_u32_e32 vcc, 52, v128
	s_nop 1
	v_cndmask_b32_e32 v116, 0, v129, vcc
	v_cmp_eq_u32_e32 vcc, 53, v128
	s_nop 1
	v_cndmask_b32_e32 v117, 0, v129, vcc
	v_cmp_eq_u32_e32 vcc, 54, v128
	s_nop 1
	v_cndmask_b32_e32 v118, 0, v129, vcc
	v_cmp_eq_u32_e32 vcc, 55, v128
	s_nop 1
	v_cndmask_b32_e32 v119, 0, v129, vcc
	v_cmp_eq_u32_e32 vcc, 56, v128
	s_nop 1
	v_cndmask_b32_e32 v120, 0, v129, vcc
	v_cmp_eq_u32_e32 vcc, 57, v128
	s_nop 1
	v_cndmask_b32_e32 v121, 0, v129, vcc
	v_cmp_eq_u32_e32 vcc, 58, v128
	s_nop 1
	v_cndmask_b32_e32 v122, 0, v129, vcc
	v_cmp_eq_u32_e32 vcc, 59, v128
	s_nop 1
	v_cndmask_b32_e32 v123, 0, v129, vcc
	v_cmp_eq_u32_e32 vcc, 60, v128
	s_nop 1
	v_cndmask_b32_e32 v124, 0, v129, vcc
	v_cmp_eq_u32_e32 vcc, 61, v128
	s_nop 1
	v_cndmask_b32_e32 v125, 0, v129, vcc
	v_cmp_eq_u32_e32 vcc, 62, v128
	s_nop 1
	v_cndmask_b32_e32 v126, 0, v129, vcc
	v_cmp_eq_u32_e32 vcc, 63, v128
	s_nop 1
	v_cndmask_b32_e32 v127, 0, v129, vcc
	s_waitcnt vmcnt(0)
	v_sub_f32_e32 v220, 1.0, v216
	v_sub_f32_e32 v221, 1.0, v217
	v_sub_f32_e32 v222, 1.0, v218
	v_sub_f32_e32 v223, 1.0, v219
	v_mov_b32_e32 v236, 1.0
	v_mov_b32_e32 v237, 1.0
	v_mov_b32_e32 v238, 1.0
	v_mov_b32_e32 v239, 1.0
	s_movk_i32 s83, 85
	s_movk_i32 s9, 11
	s_branch .Lmy_p1d1_loop

; #define SB __builtin_amdgcn_sched_barrier(0)
; #define TOUCH1(set) asm volatile("" :: "v"(set.w), "v"(set.a), "v"(set.b), "v"(set.kw), "v"(set.v))
; #define ST1(set) { DERIVE_BK(set); float sd[4]; ScanK<0>::dot(S, set.a, sd); ScanK<0>::updS(S, set, -((sd[0] + sd[1]) + (sd[2] + sd[3])), __uint_as_float(set.v << 16)); }
; #define TOUCH1(set) asm volatile("" :: "v"(set.w), "v"(set.a), "v"(set.b))
;     static __device__ __forceinline__ void dot(const float (&S)[64], const f32x4& a, float (&s)[4]) {
;         if constexpr (K == 0) {
;             asm volatile("v_mul_f32_dpp %0, %4, %8 row_newbcast:%16" DPPM "v_mul_f32_dpp %1, %5, %9 row_newbcast:%16" DPPM "v_mul_f32_dpp %2, %6, %10 row_newbcast:%16" DPPM "v_mul_f32_dpp %3, %7, %11 row_newbcast:%16" DPPM
;                          "v_fmac_f32_dpp %0, %4, %12 row_newbcast:%17" DPPM "v_fmac_f32_dpp %1, %5, %13 row_newbcast:%17" DPPM "v_fmac_f32_dpp %2, %6, %14 row_newbcast:%17" DPPM "v_fmac_f32_dpp %3, %7, %15 row_newbcast:%17" DPPM
;                          : "=&v"(s[0]), "=&v"(s[1]), "=&v"(s[2]), "=&v"(s[3])
;                          : "v"(a[0]), "v"(a[1]), "v"(a[2]), "v"(a[3]), "v"(S[K]), "v"(S[K + 1]), "v"(S[K + 2]), "v"(S[K + 3]), "v"(S[K + 4]), "v"(S[K + 5]), "v"(S[K + 6]), "v"(S[K + 7]), "n"(N0), "n"(N1));
;         } else
;         asm volatile("v_fmac_f32_dpp %0, %4, %8 row_newbcast:%16" DPPM "v_fmac_f32_dpp %1, %5, %9 row_newbcast:%16" DPPM "v_fmac_f32_dpp %2, %6, %10 row_newbcast:%16" DPPM "v_fmac_f32_dpp %3, %7, %11 row_newbcast:%16" DPPM
;                      "v_fmac_f32_dpp %0, %4, %12 row_newbcast:%17" DPPM "v_fmac_f32_dpp %1, %5, %13 row_newbcast:%17" DPPM "v_fmac_f32_dpp %2, %6, %14 row_newbcast:%17" DPPM "v_fmac_f32_dpp %3, %7, %15 row_newbcast:%17" DPPM
;                      : "+v"(s[0]), "+v"(s[1]), "+v"(s[2]), "+v"(s[3])
;                      : "v"(a[0]), "v"(a[1]), "v"(a[2]), "v"(a[3]), "v"(S[K]), "v"(S[K + 1]), "v"(S[K + 2]), "v"(S[K + 3]), "v"(S[K + 4]), "v"(S[K + 5]), "v"(S[K + 6]), "v"(S[K + 7]), "n"(N0), "n"(N1));
;         if constexpr (K + 8 < 64) ScanK<K + 8>::dot(S, a, s);
; template <bool MIX> __device__ __forceinline__ void scan_pass1(const Params& p, int d, float* ldsf) {
;     ...
;             In1 i0, i1; LD1(i0, 0);
; #pragma unroll 1
;             for (int s = 0; s < LC; s += 2) { TOUCH1(i0); SB; LD1(i1, s + 1); SB; ST1(i0); TOUCH1(i1); SB; LD1(i0, s + 2); SB; ST1(i1); }
.Lmy_p1d1_loop:
	s_waitcnt vmcnt(5)
	buffer_load_dwordx4 v[192:195], v235, s[64:67], s72 offen
	buffer_load_dwordx4 v[196:199], v250, s[64:67], s72 offen
	buffer_load_dwordx4 v[200:203], v251, s[64:67], s72 offen
	buffer_load_dwordx2 v[204:205], v252, s[64:67], s76 offen
	buffer_load_short_d16_hi v206, v253, s[64:67], s76 offen
	s_add_i32 s72, s72, 0xfffff000
	s_max_i32 s72, s72, 0
	s_add_i32 s76, s76, 0xfffff800
	s_max_i32 s76, s76, 0
	v_pk_mul_f32 v[244:245], v[164:165], v[236:237]
	v_pk_mul_f32 v[246:247], v[166:167], v[238:239]
	v_pk_mul_f32 v[236:237], v[236:237], v[160:161]
	v_pk_mul_f32 v[238:239], v[238:239], v[162:163]
	v_pk_fma_f32 v[228:229], v[168:169], v[216:217], v[220:221]
	v_pk_fma_f32 v[230:231], v[170:171], v[218:219], v[222:223]
	v_pk_mul_f32 v[208:209], v[164:165], v[168:169]
	v_pk_mul_f32 v[210:211], v[166:167], v[170:171]
	v_rcp_f32_e32 v240, v236
	v_rcp_f32_e32 v241, v237
	v_rcp_f32_e32 v242, v238
	v_rcp_f32_e32 v243, v239
	v_lshlrev_b32_e32 v212, 16, v172
	v_and_b32_e32 v213, 0xffff0000, v172
	v_lshlrev_b32_e32 v214, 16, v173
	v_and_b32_e32 v215, 0xffff0000, v173
	v_pk_mul_f32 v[212:213], v[212:213], v[228:229]
	v_pk_mul_f32 v[214:215], v[214:215], v[230:231]
	v_pk_mul_f32 v[208:209], v[208:209], v[240:241]
	v_pk_mul_f32 v[210:211], v[210:211], v[242:243]
	v_pk_mul_f32 v[212:213], v[212:213], v[240:241]
	v_pk_mul_f32 v[214:215], v[214:215], v[242:243]
	ds_write2_b32 v248, v208, v209 offset0:0 offset1:16
	ds_write2_b32 v248, v210, v211 offset0:32 offset1:48
	ds_write2_b32 v248, v212, v213 offset0:64 offset1:80
	ds_write2_b32 v248, v214, v215 offset0:96 offset1:112
	ds_read_b128 v[128:131], v249 offset:0
	ds_read_b128 v[132:135], v249 offset:16
	ds_read_b128 v[136:139], v249 offset:32
	ds_read_b128 v[140:143], v249 offset:48
	ds_read_b128 v[144:147], v249 offset:256
	ds_read_b128 v[148:151], v249 offset:272
	ds_read_b128 v[152:155], v249 offset:288
	ds_read_b128 v[156:159], v249 offset:304
	v_mul_f32_dpp v224, v244, v0 row_newbcast:0 row_mask:0xf bank_mask:0xf
	v_mul_f32_dpp v225, v245, v1 row_newbcast:0 row_mask:0xf bank_mask:0xf
	v_fmac_f32_dpp v224, v246, v2 row_newbcast:0 row_mask:0xf bank_mask:0xf
	v_fmac_f32_dpp v225, v247, v3 row_newbcast:0 row_mask:0xf bank_mask:0xf
	v_fmac_f32_dpp v224, v244, v4 row_newbcast:1 row_mask:0xf bank_mask:0xf
	v_fmac_f32_dpp v225, v245, v5 row_newbcast:1 row_mask:0xf bank_mask:0xf
	v_fmac_f32_dpp v224, v246, v6 row_newbcast:1 row_mask:0xf bank_mask:0xf
	v_fmac_f32_dpp v225, v247, v7 row_newbcast:1 row_mask:0xf bank_mask:0xf
	v_fmac_f32_dpp v224, v244, v8 row_newbcast:2 row_mask:0xf bank_mask:0xf
	v_fmac_f32_dpp v225, v245, v9 row_newbcast:2 row_mask:0xf bank_mask:0xf
	v_fmac_f32_dpp v224, v246, v10 row_newbcast:2 row_mask:0xf bank_mask:0xf
	v_fmac_f32_dpp v225, v247, v11 row_newbcast:2 row_mask:0xf bank_mask:0xf
	v_fmac_f32_dpp v224, v244, v12 row_newbcast:3 row_mask:0xf bank_mask:0xf
	v_fmac_f32_dpp v225, v245, v13 row_newbcast:3 row_mask:0xf bank_mask:0xf
	v_fmac_f32_dpp v224, v246, v14 row_newbcast:3 row_mask:0xf bank_mask:0xf
	v_fmac_f32_dpp v225, v247, v15 row_newbcast:3 row_mask:0xf bank_mask:0xf
	v_fmac_f32_dpp v224, v244, v16 row_newbcast:4 row_mask:0xf bank_mask:0xf
	v_fmac_f32_dpp v225, v245, v17 row_newbcast:4 row_mask:0xf bank_mask:0xf
	v_fmac_f32_dpp v224, v246, v18 row_newbcast:4 row_mask:0xf bank_mask:0xf
	v_fmac_f32_dpp v225, v247, v19 row_newbcast:4 row_mask:0xf bank_mask:0xf
	v_fmac_f32_dpp v224, v244, v20 row_newbcast:5 row_mask:0xf bank_mask:0xf
	v_fmac_f32_dpp v225, v245, v21 row_newbcast:5 row_mask:0xf bank_mask:0xf
	v_fmac_f32_dpp v224, v246, v22 row_newbcast:5 row_mask:0xf bank_mask:0xf
	v_fmac_f32_dpp v225, v247, v23 row_newbcast:5 row_mask:0xf bank_mask:0xf
	v_fmac_f32_dpp v224, v244, v24 row_newbcast:6 row_mask:0xf bank_mask:0xf
	v_fmac_f32_dpp v225, v245, v25 row_newbcast:6 row_mask:0xf bank_mask:0xf
	v_fmac_f32_dpp v224, v246, v26 row_newbcast:6 row_mask:0xf bank_mask:0xf
	v_fmac_f32_dpp v225, v247, v27 row_newbcast:6 row_mask:0xf bank_mask:0xf
	v_fmac_f32_dpp v224, v244, v28 row_newbcast:7 row_mask:0xf bank_mask:0xf
	v_fmac_f32_dpp v225, v245, v29 row_newbcast:7 row_mask:0xf bank_mask:0xf
	v_fmac_f32_dpp v224, v246, v30 row_newbcast:7 row_mask:0xf bank_mask:0xf
	v_fmac_f32_dpp v225, v247, v31 row_newbcast:7 row_mask:0xf bank_mask:0xf
	v_fmac_f32_dpp v224, v244, v32 row_newbcast:8 row_mask:0xf bank_mask:0xf
	v_fmac_f32_dpp v225, v245, v33 row_newbcast:8 row_mask:0xf bank_mask:0xf
	v_fmac_f32_dpp v224, v246, v34 row_newbcast:8 row_mask:0xf bank_mask:0xf
	v_fmac_f32_dpp v225, v247, v35 row_newbcast:8 row_mask:0xf bank_mask:0xf
	v_fmac_f32_dpp v224, v244, v36 row_newbcast:9 row_mask:0xf bank_mask:0xf
	v_fmac_f32_dpp v225, v245, v37 row_newbcast:9 row_mask:0xf bank_mask:0xf
	v_fmac_f32_dpp v224, v246, v38 row_newbcast:9 row_mask:0xf bank_mask:0xf
	v_fmac_f32_dpp v225, v247, v39 row_newbcast:9 row_mask:0xf bank_mask:0xf
	v_fmac_f32_dpp v224, v244, v40 row_newbcast:10 row_mask:0xf bank_mask:0xf
	v_fmac_f32_dpp v225, v245, v41 row_newbcast:10 row_mask:0xf bank_mask:0xf
	v_fmac_f32_dpp v224, v246, v42 row_newbcast:10 row_mask:0xf bank_mask:0xf
	v_fmac_f32_dpp v225, v247, v43 row_newbcast:10 row_mask:0xf bank_mask:0xf
	v_fmac_f32_dpp v224, v244, v44 row_newbcast:11 row_mask:0xf bank_mask:0xf
	v_fmac_f32_dpp v225, v245, v45 row_newbcast:11 row_mask:0xf bank_mask:0xf
	v_fmac_f32_dpp v224, v246, v46 row_newbcast:11 row_mask:0xf bank_mask:0xf
	v_fmac_f32_dpp v225, v247, v47 row_newbcast:11 row_mask:0xf bank_mask:0xf
	v_fmac_f32_dpp v224, v244, v48 row_newbcast:12 row_mask:0xf bank_mask:0xf
	v_fmac_f32_dpp v225, v245, v49 row_newbcast:12 row_mask:0xf bank_mask:0xf
;     static __device__ __forceinline__ void dot(const float (&S)[64], const f32x4& a, float (&s)[4]) {
;         if constexpr (K == 0) {
;             asm volatile("v_mul_f32_dpp %0, %4, %8 row_newbcast:%16" DPPM "v_mul_f32_dpp %1, %5, %9 row_newbcast:%16" DPPM "v_mul_f32_dpp %2, %6, %10 row_newbcast:%16" DPPM "v_mul_f32_dpp %3, %7, %11 row_newbcast:%16" DPPM
;                          "v_fmac_f32_dpp %0, %4, %12 row_newbcast:%17" DPPM "v_fmac_f32_dpp %1, %5, %13 row_newbcast:%17" DPPM "v_fmac_f32_dpp %2, %6, %14 row_newbcast:%17" DPPM "v_fmac_f32_dpp %3, %7, %15 row_newbcast:%17" DPPM
;                          : "=&v"(s[0]), "=&v"(s[1]), "=&v"(s[2]), "=&v"(s[3])
;                          : "v"(a[0]), "v"(a[1]), "v"(a[2]), "v"(a[3]), "v"(S[K]), "v"(S[K + 1]), "v"(S[K + 2]), "v"(S[K + 3]), "v"(S[K + 4]), "v"(S[K + 5]), "v"(S[K + 6]), "v"(S[K + 7]), "n"(N0), "n"(N1));
;         } else
;         asm volatile("v_fmac_f32_dpp %0, %4, %8 row_newbcast:%16" DPPM "v_fmac_f32_dpp %1, %5, %9 row_newbcast:%16" DPPM "v_fmac_f32_dpp %2, %6, %10 row_newbcast:%16" DPPM "v_fmac_f32_dpp %3, %7, %11 row_newbcast:%16" DPPM
;                      "v_fmac_f32_dpp %0, %4, %12 row_newbcast:%17" DPPM "v_fmac_f32_dpp %1, %5, %13 row_newbcast:%17" DPPM "v_fmac_f32_dpp %2, %6, %14 row_newbcast:%17" DPPM "v_fmac_f32_dpp %3, %7, %15 row_newbcast:%17" DPPM
;                      : "+v"(s[0]), "+v"(s[1]), "+v"(s[2]), "+v"(s[3])
;                      : "v"(a[0]), "v"(a[1]), "v"(a[2]), "v"(a[3]), "v"(S[K]), "v"(S[K + 1]), "v"(S[K + 2]), "v"(S[K + 3]), "v"(S[K + 4]), "v"(S[K + 5]), "v"(S[K + 6]), "v"(S[K + 7]), "n"(N0), "n"(N1));
;         if constexpr (K + 8 < 64) ScanK<K + 8>::dot(S, a, s);
	v_fmac_f32_dpp v224, v246, v50 row_newbcast:12 row_mask:0xf bank_mask:0xf
	v_fmac_f32_dpp v225, v247, v51 row_newbcast:12 row_mask:0xf bank_mask:0xf
	v_fmac_f32_dpp v224, v244, v52 row_newbcast:13 row_mask:0xf bank_mask:0xf
	v_fmac_f32_dpp v225, v245, v53 row_newbcast:13 row_mask:0xf bank_mask:0xf
	v_fmac_f32_dpp v224, v246, v54 row_newbcast:13 row_mask:0xf bank_mask:0xf
	v_fmac_f32_dpp v225, v247, v55 row_newbcast:13 row_mask:0xf bank_mask:0xf
	v_fmac_f32_dpp v224, v244, v56 row_newbcast:14 row_mask:0xf bank_mask:0xf
	v_fmac_f32_dpp v225, v245, v57 row_newbcast:14 row_mask:0xf bank_mask:0xf
	v_fmac_f32_dpp v224, v246, v58 row_newbcast:14 row_mask:0xf bank_mask:0xf
	v_fmac_f32_dpp v225, v247, v59 row_newbcast:14 row_mask:0xf bank_mask:0xf
	v_fmac_f32_dpp v224, v244, v60 row_newbcast:15 row_mask:0xf bank_mask:0xf
	v_fmac_f32_dpp v225, v245, v61 row_newbcast:15 row_mask:0xf bank_mask:0xf
	v_fmac_f32_dpp v224, v246, v62 row_newbcast:15 row_mask:0xf bank_mask:0xf
	v_fmac_f32_dpp v225, v247, v63 row_newbcast:15 row_mask:0xf bank_mask:0xf
	v_mul_f32_dpp v228, v244, v64 row_newbcast:0 row_mask:0xf bank_mask:0xf
	v_mul_f32_dpp v229, v245, v65 row_newbcast:0 row_mask:0xf bank_mask:0xf
	v_fmac_f32_dpp v228, v246, v66 row_newbcast:0 row_mask:0xf bank_mask:0xf
	v_fmac_f32_dpp v229, v247, v67 row_newbcast:0 row_mask:0xf bank_mask:0xf
	v_fmac_f32_dpp v228, v244, v68 row_newbcast:1 row_mask:0xf bank_mask:0xf
	v_fmac_f32_dpp v229, v245, v69 row_newbcast:1 row_mask:0xf bank_mask:0xf
	v_fmac_f32_dpp v228, v246, v70 row_newbcast:1 row_mask:0xf bank_mask:0xf
	v_fmac_f32_dpp v229, v247, v71 row_newbcast:1 row_mask:0xf bank_mask:0xf
	v_fmac_f32_dpp v228, v244, v72 row_newbcast:2 row_mask:0xf bank_mask:0xf
	v_fmac_f32_dpp v229, v245, v73 row_newbcast:2 row_mask:0xf bank_mask:0xf
	v_fmac_f32_dpp v228, v246, v74 row_newbcast:2 row_mask:0xf bank_mask:0xf
	v_fmac_f32_dpp v229, v247, v75 row_newbcast:2 row_mask:0xf bank_mask:0xf
	v_fmac_f32_dpp v228, v244, v76 row_newbcast:3 row_mask:0xf bank_mask:0xf
	v_fmac_f32_dpp v229, v245, v77 row_newbcast:3 row_mask:0xf bank_mask:0xf
	v_fmac_f32_dpp v228, v246, v78 row_newbcast:3 row_mask:0xf bank_mask:0xf
	v_fmac_f32_dpp v229, v247, v79 row_newbcast:3 row_mask:0xf bank_mask:0xf
	v_fmac_f32_dpp v228, v244, v80 row_newbcast:4 row_mask:0xf bank_mask:0xf
	v_fmac_f32_dpp v229, v245, v81 row_newbcast:4 row_mask:0xf bank_mask:0xf
	v_fmac_f32_dpp v228, v246, v82 row_newbcast:4 row_mask:0xf bank_mask:0xf
	v_fmac_f32_dpp v229, v247, v83 row_newbcast:4 row_mask:0xf bank_mask:0xf
	v_fmac_f32_dpp v228, v244, v84 row_newbcast:5 row_mask:0xf bank_mask:0xf
	v_fmac_f32_dpp v229, v245, v85 row_newbcast:5 row_mask:0xf bank_mask:0xf
	v_fmac_f32_dpp v228, v246, v86 row_newbcast:5 row_mask:0xf bank_mask:0xf
	v_fmac_f32_dpp v229, v247, v87 row_newbcast:5 row_mask:0xf bank_mask:0xf
	v_fmac_f32_dpp v228, v244, v88 row_newbcast:6 row_mask:0xf bank_mask:0xf
	v_fmac_f32_dpp v229, v245, v89 row_newbcast:6 row_mask:0xf bank_mask:0xf
	v_fmac_f32_dpp v228, v246, v90 row_newbcast:6 row_mask:0xf bank_mask:0xf
	v_fmac_f32_dpp v229, v247, v91 row_newbcast:6 row_mask:0xf bank_mask:0xf
	v_fmac_f32_dpp v228, v244, v92 row_newbcast:7 row_mask:0xf bank_mask:0xf
	v_fmac_f32_dpp v229, v245, v93 row_newbcast:7 row_mask:0xf bank_mask:0xf
	v_fmac_f32_dpp v228, v246, v94 row_newbcast:7 row_mask:0xf bank_mask:0xf
	v_fmac_f32_dpp v229, v247, v95 row_newbcast:7 row_mask:0xf bank_mask:0xf
	v_fmac_f32_dpp v228, v244, v96 row_newbcast:8 row_mask:0xf bank_mask:0xf
	v_fmac_f32_dpp v229, v245, v97 row_newbcast:8 row_mask:0xf bank_mask:0xf
	v_fmac_f32_dpp v228, v246, v98 row_newbcast:8 row_mask:0xf bank_mask:0xf
	v_fmac_f32_dpp v229, v247, v99 row_newbcast:8 row_mask:0xf bank_mask:0xf
	v_fmac_f32_dpp v228, v244, v100 row_newbcast:9 row_mask:0xf bank_mask:0xf
	v_fmac_f32_dpp v229, v245, v101 row_newbcast:9 row_mask:0xf bank_mask:0xf
	v_fmac_f32_dpp v228, v246, v102 row_newbcast:9 row_mask:0xf bank_mask:0xf
	v_fmac_f32_dpp v229, v247, v103 row_newbcast:9 row_mask:0xf bank_mask:0xf
	v_fmac_f32_dpp v228, v244, v104 row_newbcast:10 row_mask:0xf bank_mask:0xf
	v_fmac_f32_dpp v229, v245, v105 row_newbcast:10 row_mask:0xf bank_mask:0xf
	v_fmac_f32_dpp v228, v246, v106 row_newbcast:10 row_mask:0xf bank_mask:0xf
	v_fmac_f32_dpp v229, v247, v107 row_newbcast:10 row_mask:0xf bank_mask:0xf
	v_fmac_f32_dpp v228, v244, v108 row_newbcast:11 row_mask:0xf bank_mask:0xf
	v_fmac_f32_dpp v229, v245, v109 row_newbcast:11 row_mask:0xf bank_mask:0xf
	v_fmac_f32_dpp v228, v246, v110 row_newbcast:11 row_mask:0xf bank_mask:0xf
	v_fmac_f32_dpp v229, v247, v111 row_newbcast:11 row_mask:0xf bank_mask:0xf
	v_fmac_f32_dpp v228, v244, v112 row_newbcast:12 row_mask:0xf bank_mask:0xf
	v_fmac_f32_dpp v229, v245, v113 row_newbcast:12 row_mask:0xf bank_mask:0xf
	v_fmac_f32_dpp v228, v246, v114 row_newbcast:12 row_mask:0xf bank_mask:0xf
	v_fmac_f32_dpp v229, v247, v115 row_newbcast:12 row_mask:0xf bank_mask:0xf
	v_fmac_f32_dpp v228, v244, v116 row_newbcast:13 row_mask:0xf bank_mask:0xf
	v_fmac_f32_dpp v229, v245, v117 row_newbcast:13 row_mask:0xf bank_mask:0xf
	v_fmac_f32_dpp v228, v246, v118 row_newbcast:13 row_mask:0xf bank_mask:0xf
	v_fmac_f32_dpp v229, v247, v119 row_newbcast:13 row_mask:0xf bank_mask:0xf
	v_fmac_f32_dpp v228, v244, v120 row_newbcast:14 row_mask:0xf bank_mask:0xf
	v_fmac_f32_dpp v229, v245, v121 row_newbcast:14 row_mask:0xf bank_mask:0xf
	v_fmac_f32_dpp v228, v246, v122 row_newbcast:14 row_mask:0xf bank_mask:0xf
	v_fmac_f32_dpp v229, v247, v123 row_newbcast:14 row_mask:0xf bank_mask:0xf
	v_fmac_f32_dpp v228, v244, v124 row_newbcast:15 row_mask:0xf bank_mask:0xf
	v_fmac_f32_dpp v229, v245, v125 row_newbcast:15 row_mask:0xf bank_mask:0xf
	v_fmac_f32_dpp v228, v246, v126 row_newbcast:15 row_mask:0xf bank_mask:0xf
	v_fmac_f32_dpp v229, v247, v127 row_newbcast:15 row_mask:0xf bank_mask:0xf
	v_sub_f32_e64 v232, -v224, v225
	v_sub_f32_e64 v233, -v228, v229
	s_waitcnt lgkmcnt(0)
;     static __device__ __forceinline__ void updS(float (&S)[64], const In1& in, float sa, float vv) {
;         float t0, t1, t2, t3;
;         asm volatile("v_mul_f32_dpp %0, %8, %21 row_newbcast:%22" DPPM "v_mul_f32_dpp %1, %9, %21 row_newbcast:%22" DPPM "v_mul_f32_dpp %2, %10, %21 row_newbcast:%22" DPPM "v_mul_f32_dpp %3, %11, %21 row_newbcast:%22" DPPM
;                      "v_fmac_f32_dpp %0, %12, %4 row_newbcast:%22" DPPM "v_fmac_f32_dpp %1, %13, %5 row_newbcast:%22" DPPM "v_fmac_f32_dpp %2, %14, %6 row_newbcast:%22" DPPM "v_fmac_f32_dpp %3, %15, %7 row_newbcast:%22" DPPM
;                      "v_fmac_f32_dpp %0, %16, %20 row_newbcast:%22" DPPM "v_fmac_f32_dpp %1, %17, %20 row_newbcast:%22" DPPM "v_fmac_f32_dpp %2, %18, %20 row_newbcast:%22" DPPM "v_fmac_f32_dpp %3, %19, %20 row_newbcast:%22" DPPM
;                      : "=&v"(t0), "=&v"(t1), "=&v"(t2), "=&v"(t3)
;                      : "v"(S[K]), "v"(S[K + 1]), "v"(S[K + 2]), "v"(S[K + 3]), "v"(in.kd[0]), "v"(in.kd[1]), "v"(in.kd[2]), "v"(in.kd[3]), "v"(in.w[0]), "v"(in.w[1]), "v"(in.w[2]), "v"(in.w[3]),
;                        "v"(in.b[0]), "v"(in.b[1]), "v"(in.b[2]), "v"(in.b[3]), "v"(sa), "v"(vv), "n"(N0));
;         S[K] = t0; S[K + 1] = t1; S[K + 2] = t2; S[K + 3] = t3;
;         if constexpr (K + 4 < 64) ScanK<K + 4>::updS(S, in, sa, vv);
;     }
;     static __device__ __forceinline__ void updP(float (&P)[64], const In1& in, float sa) {
;         float u0, u1, u2, u3;
;         asm volatile("v_mul_f32_dpp %0, %8, %4 row_newbcast:%17" DPPM "v_mul_f32_dpp %1, %9, %5 row_newbcast:%17" DPPM "v_mul_f32_dpp %2, %10, %6 row_newbcast:%17" DPPM "v_mul_f32_dpp %3, %11, %7 row_newbcast:%17" DPPM
;                      "v_fmac_f32_dpp %0, %12, %16 row_newbcast:%17" DPPM "v_fmac_f32_dpp %1, %13, %16 row_newbcast:%17" DPPM "v_fmac_f32_dpp %2, %14, %16 row_newbcast:%17" DPPM "v_fmac_f32_dpp %3, %15, %16 row_newbcast:%17" DPPM
;                      : "=&v"(u0), "=&v"(u1), "=&v"(u2), "=&v"(u3)
;                      : "v"(P[K]), "v"(P[K + 1]), "v"(P[K + 2]), "v"(P[K + 3]), "v"(in.w[0]), "v"(in.w[1]), "v"(in.w[2]), "v"(in.w[3]), "v"(in.b[0]), "v"(in.b[1]), "v"(in.b[2]), "v"(in.b[3]), "v"(sa), "n"(N0));
;         P[K] = u0; P[K + 1] = u1; P[K + 2] = u2; P[K + 3] = u3;
;         if constexpr (K + 4 < 64) ScanK<K + 4>::updP(P, in, sa);
;     }
	v_mfma_f32_4x4x1_16b_f32 v[0:3], v128, v232, v[0:3]
	v_mfma_f32_4x4x1_16b_f32 v[4:7], v129, v232, v[4:7]
	v_mfma_f32_4x4x1_16b_f32 v[8:11], v130, v232, v[8:11]
	v_mfma_f32_4x4x1_16b_f32 v[12:15], v131, v232, v[12:15]
	v_mfma_f32_4x4x1_16b_f32 v[16:19], v132, v232, v[16:19]
	v_mfma_f32_4x4x1_16b_f32 v[20:23], v133, v232, v[20:23]
	v_mfma_f32_4x4x1_16b_f32 v[24:27], v134, v232, v[24:27]
	v_mfma_f32_4x4x1_16b_f32 v[28:31], v135, v232, v[28:31]
	v_mfma_f32_4x4x1_16b_f32 v[32:35], v136, v232, v[32:35]
	v_mfma_f32_4x4x1_16b_f32 v[36:39], v137, v232, v[36:39]
	v_mfma_f32_4x4x1_16b_f32 v[40:43], v138, v232, v[40:43]
	v_mfma_f32_4x4x1_16b_f32 v[44:47], v139, v232, v[44:47]
	v_mfma_f32_4x4x1_16b_f32 v[48:51], v140, v232, v[48:51]
	v_mfma_f32_4x4x1_16b_f32 v[52:55], v141, v232, v[52:55]
	v_mfma_f32_4x4x1_16b_f32 v[56:59], v142, v232, v[56:59]
	v_mfma_f32_4x4x1_16b_f32 v[60:63], v143, v232, v[60:63]
	v_mfma_f32_4x4x1_16b_f32 v[0:3], v144, v174, v[0:3]
	v_mfma_f32_4x4x1_16b_f32 v[4:7], v145, v174, v[4:7]
	v_mfma_f32_4x4x1_16b_f32 v[8:11], v146, v174, v[8:11]
	v_mfma_f32_4x4x1_16b_f32 v[12:15], v147, v174, v[12:15]
	v_mfma_f32_4x4x1_16b_f32 v[16:19], v148, v174, v[16:19]
	v_mfma_f32_4x4x1_16b_f32 v[20:23], v149, v174, v[20:23]
	v_mfma_f32_4x4x1_16b_f32 v[24:27], v150, v174, v[24:27]
	v_mfma_f32_4x4x1_16b_f32 v[28:31], v151, v174, v[28:31]
	v_mfma_f32_4x4x1_16b_f32 v[32:35], v152, v174, v[32:35]
	v_mfma_f32_4x4x1_16b_f32 v[36:39], v153, v174, v[36:39]
	v_mfma_f32_4x4x1_16b_f32 v[40:43], v154, v174, v[40:43]
	v_mfma_f32_4x4x1_16b_f32 v[44:47], v155, v174, v[44:47]
	v_mfma_f32_4x4x1_16b_f32 v[48:51], v156, v174, v[48:51]
	v_mfma_f32_4x4x1_16b_f32 v[52:55], v157, v174, v[52:55]
	v_mfma_f32_4x4x1_16b_f32 v[56:59], v158, v174, v[56:59]
	v_mfma_f32_4x4x1_16b_f32 v[60:63], v159, v174, v[60:63]
	v_mfma_f32_4x4x1_16b_f32 v[64:67], v128, v233, v[64:67]
	v_mfma_f32_4x4x1_16b_f32 v[68:71], v129, v233, v[68:71]
	v_mfma_f32_4x4x1_16b_f32 v[72:75], v130, v233, v[72:75]
	v_mfma_f32_4x4x1_16b_f32 v[76:79], v131, v233, v[76:79]
	v_mfma_f32_4x4x1_16b_f32 v[80:83], v132, v233, v[80:83]
	v_mfma_f32_4x4x1_16b_f32 v[84:87], v133, v233, v[84:87]
	v_mfma_f32_4x4x1_16b_f32 v[88:91], v134, v233, v[88:91]
	v_mfma_f32_4x4x1_16b_f32 v[92:95], v135, v233, v[92:95]
	v_mfma_f32_4x4x1_16b_f32 v[96:99], v136, v233, v[96:99]
	v_mfma_f32_4x4x1_16b_f32 v[100:103], v137, v233, v[100:103]
	v_mfma_f32_4x4x1_16b_f32 v[104:107], v138, v233, v[104:107]
	v_mfma_f32_4x4x1_16b_f32 v[108:111], v139, v233, v[108:111]
	v_mfma_f32_4x4x1_16b_f32 v[112:115], v140, v233, v[112:115]
	v_mfma_f32_4x4x1_16b_f32 v[116:119], v141, v233, v[116:119]
	v_mfma_f32_4x4x1_16b_f32 v[120:123], v142, v233, v[120:123]
	v_mfma_f32_4x4x1_16b_f32 v[124:127], v143, v233, v[124:127]
	s_waitcnt vmcnt(5)
	buffer_load_dwordx4 v[160:163], v235, s[64:67], s72 offen
	buffer_load_dwordx4 v[164:167], v250, s[64:67], s72 offen
	buffer_load_dwordx4 v[168:171], v251, s[64:67], s72 offen
	buffer_load_dwordx2 v[172:173], v252, s[64:67], s76 offen
	buffer_load_short_d16_hi v174, v253, s[64:67], s76 offen
	s_add_i32 s72, s72, 0xfffff000
	s_max_i32 s72, s72, 0
	s_add_i32 s76, s76, 0xfffff800
	s_max_i32 s76, s76, 0
	v_pk_mul_f32 v[244:245], v[180:181], v[236:237]
	v_pk_mul_f32 v[246:247], v[182:183], v[238:239]
	v_pk_mul_f32 v[236:237], v[236:237], v[176:177]
	v_pk_mul_f32 v[238:239], v[238:239], v[178:179]
	v_pk_fma_f32 v[228:229], v[184:185], v[216:217], v[220:221]
	v_pk_fma_f32 v[230:231], v[186:187], v[218:219], v[222:223]
	v_pk_mul_f32 v[208:209], v[180:181], v[184:185]
	v_pk_mul_f32 v[210:211], v[182:183], v[186:187]
	v_rcp_f32_e32 v240, v236
	v_rcp_f32_e32 v241, v237
	v_rcp_f32_e32 v242, v238
	v_rcp_f32_e32 v243, v239
	v_lshlrev_b32_e32 v212, 16, v188
	v_and_b32_e32 v213, 0xffff0000, v188
	v_lshlrev_b32_e32 v214, 16, v189
	v_and_b32_e32 v215, 0xffff0000, v189
	v_pk_mul_f32 v[212:213], v[212:213], v[228:229]
	v_pk_mul_f32 v[214:215], v[214:215], v[230:231]
	v_pk_mul_f32 v[208:209], v[208:209], v[240:241]
	v_pk_mul_f32 v[210:211], v[210:211], v[242:243]
	v_pk_mul_f32 v[212:213], v[212:213], v[240:241]
	v_pk_mul_f32 v[214:215], v[214:215], v[242:243]
	ds_write2_b32 v248, v208, v209 offset0:0 offset1:16
	ds_write2_b32 v248, v210, v211 offset0:32 offset1:48
	ds_write2_b32 v248, v212, v213 offset0:64 offset1:80
	ds_write2_b32 v248, v214, v215 offset0:96 offset1:112
	ds_read_b128 v[128:131], v249 offset:0
	ds_read_b128 v[132:135], v249 offset:16
	ds_read_b128 v[136:139], v249 offset:32
	ds_read_b128 v[140:143], v249 offset:48
	ds_read_b128 v[144:147], v249 offset:256
	ds_read_b128 v[148:151], v249 offset:272
	ds_read_b128 v[152:155], v249 offset:288
	ds_read_b128 v[156:159], v249 offset:304
	v_mul_f32_dpp v224, v244, v0 row_newbcast:0 row_mask:0xf bank_mask:0xf
	v_mul_f32_dpp v225, v245, v1 row_newbcast:0 row_mask:0xf bank_mask:0xf
	v_fmac_f32_dpp v224, v246, v2 row_newbcast:0 row_mask:0xf bank_mask:0xf
	v_fmac_f32_dpp v225, v247, v3 row_newbcast:0 row_mask:0xf bank_mask:0xf
	v_fmac_f32_dpp v224, v244, v4 row_newbcast:1 row_mask:0xf bank_mask:0xf
	v_fmac_f32_dpp v225, v245, v5 row_newbcast:1 row_mask:0xf bank_mask:0xf
	v_fmac_f32_dpp v224, v246, v6 row_newbcast:1 row_mask:0xf bank_mask:0xf
	v_fmac_f32_dpp v225, v247, v7 row_newbcast:1 row_mask:0xf bank_mask:0xf
	v_fmac_f32_dpp v224, v244, v8 row_newbcast:2 row_mask:0xf bank_mask:0xf
	v_fmac_f32_dpp v225, v245, v9 row_newbcast:2 row_mask:0xf bank_mask:0xf
	v_fmac_f32_dpp v224, v246, v10 row_newbcast:2 row_mask:0xf bank_mask:0xf
	v_fmac_f32_dpp v225, v247, v11 row_newbcast:2 row_mask:0xf bank_mask:0xf
	v_fmac_f32_dpp v224, v244, v12 row_newbcast:3 row_mask:0xf bank_mask:0xf
;     static __device__ __forceinline__ void dot(const float (&S)[64], const f32x4& a, float (&s)[4]) {
;         if constexpr (K == 0) {
;             asm volatile("v_mul_f32_dpp %0, %4, %8 row_newbcast:%16" DPPM "v_mul_f32_dpp %1, %5, %9 row_newbcast:%16" DPPM "v_mul_f32_dpp %2, %6, %10 row_newbcast:%16" DPPM "v_mul_f32_dpp %3, %7, %11 row_newbcast:%16" DPPM
;                          "v_fmac_f32_dpp %0, %4, %12 row_newbcast:%17" DPPM "v_fmac_f32_dpp %1, %5, %13 row_newbcast:%17" DPPM "v_fmac_f32_dpp %2, %6, %14 row_newbcast:%17" DPPM "v_fmac_f32_dpp %3, %7, %15 row_newbcast:%17" DPPM
;                          : "=&v"(s[0]), "=&v"(s[1]), "=&v"(s[2]), "=&v"(s[3])
;                          : "v"(a[0]), "v"(a[1]), "v"(a[2]), "v"(a[3]), "v"(S[K]), "v"(S[K + 1]), "v"(S[K + 2]), "v"(S[K + 3]), "v"(S[K + 4]), "v"(S[K + 5]), "v"(S[K + 6]), "v"(S[K + 7]), "n"(N0), "n"(N1));
;         } else
;         asm volatile("v_fmac_f32_dpp %0, %4, %8 row_newbcast:%16" DPPM "v_fmac_f32_dpp %1, %5, %9 row_newbcast:%16" DPPM "v_fmac_f32_dpp %2, %6, %10 row_newbcast:%16" DPPM "v_fmac_f32_dpp %3, %7, %11 row_newbcast:%16" DPPM
;                      "v_fmac_f32_dpp %0, %4, %12 row_newbcast:%17" DPPM "v_fmac_f32_dpp %1, %5, %13 row_newbcast:%17" DPPM "v_fmac_f32_dpp %2, %6, %14 row_newbcast:%17" DPPM "v_fmac_f32_dpp %3, %7, %15 row_newbcast:%17" DPPM
;                      : "+v"(s[0]), "+v"(s[1]), "+v"(s[2]), "+v"(s[3])
;                      : "v"(a[0]), "v"(a[1]), "v"(a[2]), "v"(a[3]), "v"(S[K]), "v"(S[K + 1]), "v"(S[K + 2]), "v"(S[K + 3]), "v"(S[K + 4]), "v"(S[K + 5]), "v"(S[K + 6]), "v"(S[K + 7]), "n"(N0), "n"(N1));
;         if constexpr (K + 8 < 64) ScanK<K + 8>::dot(S, a, s);
	v_fmac_f32_dpp v225, v245, v13 row_newbcast:3 row_mask:0xf bank_mask:0xf
	v_fmac_f32_dpp v224, v246, v14 row_newbcast:3 row_mask:0xf bank_mask:0xf
	v_fmac_f32_dpp v225, v247, v15 row_newbcast:3 row_mask:0xf bank_mask:0xf
	v_fmac_f32_dpp v224, v244, v16 row_newbcast:4 row_mask:0xf bank_mask:0xf
	v_fmac_f32_dpp v225, v245, v17 row_newbcast:4 row_mask:0xf bank_mask:0xf
	v_fmac_f32_dpp v224, v246, v18 row_newbcast:4 row_mask:0xf bank_mask:0xf
	v_fmac_f32_dpp v225, v247, v19 row_newbcast:4 row_mask:0xf bank_mask:0xf
	v_fmac_f32_dpp v224, v244, v20 row_newbcast:5 row_mask:0xf bank_mask:0xf
	v_fmac_f32_dpp v225, v245, v21 row_newbcast:5 row_mask:0xf bank_mask:0xf
	v_fmac_f32_dpp v224, v246, v22 row_newbcast:5 row_mask:0xf bank_mask:0xf
	v_fmac_f32_dpp v225, v247, v23 row_newbcast:5 row_mask:0xf bank_mask:0xf
	v_fmac_f32_dpp v224, v244, v24 row_newbcast:6 row_mask:0xf bank_mask:0xf
	v_fmac_f32_dpp v225, v245, v25 row_newbcast:6 row_mask:0xf bank_mask:0xf
	v_fmac_f32_dpp v224, v246, v26 row_newbcast:6 row_mask:0xf bank_mask:0xf
	v_fmac_f32_dpp v225, v247, v27 row_newbcast:6 row_mask:0xf bank_mask:0xf
	v_fmac_f32_dpp v224, v244, v28 row_newbcast:7 row_mask:0xf bank_mask:0xf
	v_fmac_f32_dpp v225, v245, v29 row_newbcast:7 row_mask:0xf bank_mask:0xf
	v_fmac_f32_dpp v224, v246, v30 row_newbcast:7 row_mask:0xf bank_mask:0xf
	v_fmac_f32_dpp v225, v247, v31 row_newbcast:7 row_mask:0xf bank_mask:0xf
	v_fmac_f32_dpp v224, v244, v32 row_newbcast:8 row_mask:0xf bank_mask:0xf
	v_fmac_f32_dpp v225, v245, v33 row_newbcast:8 row_mask:0xf bank_mask:0xf
	v_fmac_f32_dpp v224, v246, v34 row_newbcast:8 row_mask:0xf bank_mask:0xf
	v_fmac_f32_dpp v225, v247, v35 row_newbcast:8 row_mask:0xf bank_mask:0xf
	v_fmac_f32_dpp v224, v244, v36 row_newbcast:9 row_mask:0xf bank_mask:0xf
	v_fmac_f32_dpp v225, v245, v37 row_newbcast:9 row_mask:0xf bank_mask:0xf
	v_fmac_f32_dpp v224, v246, v38 row_newbcast:9 row_mask:0xf bank_mask:0xf
	v_fmac_f32_dpp v225, v247, v39 row_newbcast:9 row_mask:0xf bank_mask:0xf
	v_fmac_f32_dpp v224, v244, v40 row_newbcast:10 row_mask:0xf bank_mask:0xf
	v_fmac_f32_dpp v225, v245, v41 row_newbcast:10 row_mask:0xf bank_mask:0xf
	v_fmac_f32_dpp v224, v246, v42 row_newbcast:10 row_mask:0xf bank_mask:0xf
	v_fmac_f32_dpp v225, v247, v43 row_newbcast:10 row_mask:0xf bank_mask:0xf
	v_fmac_f32_dpp v224, v244, v44 row_newbcast:11 row_mask:0xf bank_mask:0xf
	v_fmac_f32_dpp v225, v245, v45 row_newbcast:11 row_mask:0xf bank_mask:0xf
	v_fmac_f32_dpp v224, v246, v46 row_newbcast:11 row_mask:0xf bank_mask:0xf
	v_fmac_f32_dpp v225, v247, v47 row_newbcast:11 row_mask:0xf bank_mask:0xf
	v_fmac_f32_dpp v224, v244, v48 row_newbcast:12 row_mask:0xf bank_mask:0xf
	v_fmac_f32_dpp v225, v245, v49 row_newbcast:12 row_mask:0xf bank_mask:0xf
	v_fmac_f32_dpp v224, v246, v50 row_newbcast:12 row_mask:0xf bank_mask:0xf
	v_fmac_f32_dpp v225, v247, v51 row_newbcast:12 row_mask:0xf bank_mask:0xf
	v_fmac_f32_dpp v224, v244, v52 row_newbcast:13 row_mask:0xf bank_mask:0xf
	v_fmac_f32_dpp v225, v245, v53 row_newbcast:13 row_mask:0xf bank_mask:0xf
	v_fmac_f32_dpp v224, v246, v54 row_newbcast:13 row_mask:0xf bank_mask:0xf
	v_fmac_f32_dpp v225, v247, v55 row_newbcast:13 row_mask:0xf bank_mask:0xf
	v_fmac_f32_dpp v224, v244, v56 row_newbcast:14 row_mask:0xf bank_mask:0xf
	v_fmac_f32_dpp v225, v245, v57 row_newbcast:14 row_mask:0xf bank_mask:0xf
	v_fmac_f32_dpp v224, v246, v58 row_newbcast:14 row_mask:0xf bank_mask:0xf
	v_fmac_f32_dpp v225, v247, v59 row_newbcast:14 row_mask:0xf bank_mask:0xf
	v_fmac_f32_dpp v224, v244, v60 row_newbcast:15 row_mask:0xf bank_mask:0xf
	v_fmac_f32_dpp v225, v245, v61 row_newbcast:15 row_mask:0xf bank_mask:0xf
	v_fmac_f32_dpp v224, v246, v62 row_newbcast:15 row_mask:0xf bank_mask:0xf
	v_fmac_f32_dpp v225, v247, v63 row_newbcast:15 row_mask:0xf bank_mask:0xf
	v_mul_f32_dpp v228, v244, v64 row_newbcast:0 row_mask:0xf bank_mask:0xf
	v_mul_f32_dpp v229, v245, v65 row_newbcast:0 row_mask:0xf bank_mask:0xf
	v_fmac_f32_dpp v228, v246, v66 row_newbcast:0 row_mask:0xf bank_mask:0xf
	v_fmac_f32_dpp v229, v247, v67 row_newbcast:0 row_mask:0xf bank_mask:0xf
	v_fmac_f32_dpp v228, v244, v68 row_newbcast:1 row_mask:0xf bank_mask:0xf
	v_fmac_f32_dpp v229, v245, v69 row_newbcast:1 row_mask:0xf bank_mask:0xf
	v_fmac_f32_dpp v228, v246, v70 row_newbcast:1 row_mask:0xf bank_mask:0xf
	v_fmac_f32_dpp v229, v247, v71 row_newbcast:1 row_mask:0xf bank_mask:0xf
	v_fmac_f32_dpp v228, v244, v72 row_newbcast:2 row_mask:0xf bank_mask:0xf
	v_fmac_f32_dpp v229, v245, v73 row_newbcast:2 row_mask:0xf bank_mask:0xf
	v_fmac_f32_dpp v228, v246, v74 row_newbcast:2 row_mask:0xf bank_mask:0xf
	v_fmac_f32_dpp v229, v247, v75 row_newbcast:2 row_mask:0xf bank_mask:0xf
	v_fmac_f32_dpp v228, v244, v76 row_newbcast:3 row_mask:0xf bank_mask:0xf
	v_fmac_f32_dpp v229, v245, v77 row_newbcast:3 row_mask:0xf bank_mask:0xf
	v_fmac_f32_dpp v228, v246, v78 row_newbcast:3 row_mask:0xf bank_mask:0xf
	v_fmac_f32_dpp v229, v247, v79 row_newbcast:3 row_mask:0xf bank_mask:0xf
	v_fmac_f32_dpp v228, v244, v80 row_newbcast:4 row_mask:0xf bank_mask:0xf
	v_fmac_f32_dpp v229, v245, v81 row_newbcast:4 row_mask:0xf bank_mask:0xf
	v_fmac_f32_dpp v228, v246, v82 row_newbcast:4 row_mask:0xf bank_mask:0xf
	v_fmac_f32_dpp v229, v247, v83 row_newbcast:4 row_mask:0xf bank_mask:0xf
	v_fmac_f32_dpp v228, v244, v84 row_newbcast:5 row_mask:0xf bank_mask:0xf
	v_fmac_f32_dpp v229, v245, v85 row_newbcast:5 row_mask:0xf bank_mask:0xf
	v_fmac_f32_dpp v228, v246, v86 row_newbcast:5 row_mask:0xf bank_mask:0xf
	v_fmac_f32_dpp v229, v247, v87 row_newbcast:5 row_mask:0xf bank_mask:0xf
	v_fmac_f32_dpp v228, v244, v88 row_newbcast:6 row_mask:0xf bank_mask:0xf
;     static __device__ __forceinline__ void updS(float (&S)[64], const In1& in, float sa, float vv) {
;         float t0, t1, t2, t3;
;         asm volatile("v_mul_f32_dpp %0, %8, %21 row_newbcast:%22" DPPM "v_mul_f32_dpp %1, %9, %21 row_newbcast:%22" DPPM "v_mul_f32_dpp %2, %10, %21 row_newbcast:%22" DPPM "v_mul_f32_dpp %3, %11, %21 row_newbcast:%22" DPPM
;                      "v_fmac_f32_dpp %0, %12, %4 row_newbcast:%22" DPPM "v_fmac_f32_dpp %1, %13, %5 row_newbcast:%22" DPPM "v_fmac_f32_dpp %2, %14, %6 row_newbcast:%22" DPPM "v_fmac_f32_dpp %3, %15, %7 row_newbcast:%22" DPPM
;                      "v_fmac_f32_dpp %0, %16, %20 row_newbcast:%22" DPPM "v_fmac_f32_dpp %1, %17, %20 row_newbcast:%22" DPPM "v_fmac_f32_dpp %2, %18, %20 row_newbcast:%22" DPPM "v_fmac_f32_dpp %3, %19, %20 row_newbcast:%22" DPPM
;                      : "=&v"(t0), "=&v"(t1), "=&v"(t2), "=&v"(t3)
;                      : "v"(S[K]), "v"(S[K + 1]), "v"(S[K + 2]), "v"(S[K + 3]), "v"(in.kd[0]), "v"(in.kd[1]), "v"(in.kd[2]), "v"(in.kd[3]), "v"(in.w[0]), "v"(in.w[1]), "v"(in.w[2]), "v"(in.w[3]),
;                        "v"(in.b[0]), "v"(in.b[1]), "v"(in.b[2]), "v"(in.b[3]), "v"(sa), "v"(vv), "n"(N0));
;         S[K] = t0; S[K + 1] = t1; S[K + 2] = t2; S[K + 3] = t3;
;         if constexpr (K + 4 < 64) ScanK<K + 4>::updS(S, in, sa, vv);
;     }
;     static __device__ __forceinline__ void updP(float (&P)[64], const In1& in, float sa) {
;         float u0, u1, u2, u3;
;         asm volatile("v_mul_f32_dpp %0, %8, %4 row_newbcast:%17" DPPM "v_mul_f32_dpp %1, %9, %5 row_newbcast:%17" DPPM "v_mul_f32_dpp %2, %10, %6 row_newbcast:%17" DPPM "v_mul_f32_dpp %3, %11, %7 row_newbcast:%17" DPPM
;                      "v_fmac_f32_dpp %0, %12, %16 row_newbcast:%17" DPPM "v_fmac_f32_dpp %1, %13, %16 row_newbcast:%17" DPPM "v_fmac_f32_dpp %2, %14, %16 row_newbcast:%17" DPPM "v_fmac_f32_dpp %3, %15, %16 row_newbcast:%17" DPPM
;                      : "=&v"(u0), "=&v"(u1), "=&v"(u2), "=&v"(u3)
;                      : "v"(P[K]), "v"(P[K + 1]), "v"(P[K + 2]), "v"(P[K + 3]), "v"(in.w[0]), "v"(in.w[1]), "v"(in.w[2]), "v"(in.w[3]), "v"(in.b[0]), "v"(in.b[1]), "v"(in.b[2]), "v"(in.b[3]), "v"(sa), "n"(N0));
;         P[K] = u0; P[K + 1] = u1; P[K + 2] = u2; P[K + 3] = u3;
;         if constexpr (K + 4 < 64) ScanK<K + 4>::updP(P, in, sa);
;     }
	v_fmac_f32_dpp v229, v245, v89 row_newbcast:6 row_mask:0xf bank_mask:0xf
	v_fmac_f32_dpp v228, v246, v90 row_newbcast:6 row_mask:0xf bank_mask:0xf
	v_fmac_f32_dpp v229, v247, v91 row_newbcast:6 row_mask:0xf bank_mask:0xf
	v_fmac_f32_dpp v228, v244, v92 row_newbcast:7 row_mask:0xf bank_mask:0xf
	v_fmac_f32_dpp v229, v245, v93 row_newbcast:7 row_mask:0xf bank_mask:0xf
	v_fmac_f32_dpp v228, v246, v94 row_newbcast:7 row_mask:0xf bank_mask:0xf
	v_fmac_f32_dpp v229, v247, v95 row_newbcast:7 row_mask:0xf bank_mask:0xf
	v_fmac_f32_dpp v228, v244, v96 row_newbcast:8 row_mask:0xf bank_mask:0xf
	v_fmac_f32_dpp v229, v245, v97 row_newbcast:8 row_mask:0xf bank_mask:0xf
	v_fmac_f32_dpp v228, v246, v98 row_newbcast:8 row_mask:0xf bank_mask:0xf
	v_fmac_f32_dpp v229, v247, v99 row_newbcast:8 row_mask:0xf bank_mask:0xf
	v_fmac_f32_dpp v228, v244, v100 row_newbcast:9 row_mask:0xf bank_mask:0xf
	v_fmac_f32_dpp v229, v245, v101 row_newbcast:9 row_mask:0xf bank_mask:0xf
	v_fmac_f32_dpp v228, v246, v102 row_newbcast:9 row_mask:0xf bank_mask:0xf
	v_fmac_f32_dpp v229, v247, v103 row_newbcast:9 row_mask:0xf bank_mask:0xf
	v_fmac_f32_dpp v228, v244, v104 row_newbcast:10 row_mask:0xf bank_mask:0xf
	v_fmac_f32_dpp v229, v245, v105 row_newbcast:10 row_mask:0xf bank_mask:0xf
	v_fmac_f32_dpp v228, v246, v106 row_newbcast:10 row_mask:0xf bank_mask:0xf
	v_fmac_f32_dpp v229, v247, v107 row_newbcast:10 row_mask:0xf bank_mask:0xf
	v_fmac_f32_dpp v228, v244, v108 row_newbcast:11 row_mask:0xf bank_mask:0xf
	v_fmac_f32_dpp v229, v245, v109 row_newbcast:11 row_mask:0xf bank_mask:0xf
	v_fmac_f32_dpp v228, v246, v110 row_newbcast:11 row_mask:0xf bank_mask:0xf
	v_fmac_f32_dpp v229, v247, v111 row_newbcast:11 row_mask:0xf bank_mask:0xf
	v_fmac_f32_dpp v228, v244, v112 row_newbcast:12 row_mask:0xf bank_mask:0xf
	v_fmac_f32_dpp v229, v245, v113 row_newbcast:12 row_mask:0xf bank_mask:0xf
	v_fmac_f32_dpp v228, v246, v114 row_newbcast:12 row_mask:0xf bank_mask:0xf
	v_fmac_f32_dpp v229, v247, v115 row_newbcast:12 row_mask:0xf bank_mask:0xf
	v_fmac_f32_dpp v228, v244, v116 row_newbcast:13 row_mask:0xf bank_mask:0xf
	v_fmac_f32_dpp v229, v245, v117 row_newbcast:13 row_mask:0xf bank_mask:0xf
	v_fmac_f32_dpp v228, v246, v118 row_newbcast:13 row_mask:0xf bank_mask:0xf
	v_fmac_f32_dpp v229, v247, v119 row_newbcast:13 row_mask:0xf bank_mask:0xf
	v_fmac_f32_dpp v228, v244, v120 row_newbcast:14 row_mask:0xf bank_mask:0xf
	v_fmac_f32_dpp v229, v245, v121 row_newbcast:14 row_mask:0xf bank_mask:0xf
	v_fmac_f32_dpp v228, v246, v122 row_newbcast:14 row_mask:0xf bank_mask:0xf
	v_fmac_f32_dpp v229, v247, v123 row_newbcast:14 row_mask:0xf bank_mask:0xf
	v_fmac_f32_dpp v228, v244, v124 row_newbcast:15 row_mask:0xf bank_mask:0xf
	v_fmac_f32_dpp v229, v245, v125 row_newbcast:15 row_mask:0xf bank_mask:0xf
	v_fmac_f32_dpp v228, v246, v126 row_newbcast:15 row_mask:0xf bank_mask:0xf
	v_fmac_f32_dpp v229, v247, v127 row_newbcast:15 row_mask:0xf bank_mask:0xf
	v_sub_f32_e64 v232, -v224, v225
	v_sub_f32_e64 v233, -v228, v229
	s_waitcnt lgkmcnt(0)
	v_mfma_f32_4x4x1_16b_f32 v[0:3], v128, v232, v[0:3]
	v_mfma_f32_4x4x1_16b_f32 v[4:7], v129, v232, v[4:7]
	v_mfma_f32_4x4x1_16b_f32 v[8:11], v130, v232, v[8:11]
	v_mfma_f32_4x4x1_16b_f32 v[12:15], v131, v232, v[12:15]
	v_mfma_f32_4x4x1_16b_f32 v[16:19], v132, v232, v[16:19]
	v_mfma_f32_4x4x1_16b_f32 v[20:23], v133, v232, v[20:23]
	v_mfma_f32_4x4x1_16b_f32 v[24:27], v134, v232, v[24:27]
	v_mfma_f32_4x4x1_16b_f32 v[28:31], v135, v232, v[28:31]
	v_mfma_f32_4x4x1_16b_f32 v[32:35], v136, v232, v[32:35]
	v_mfma_f32_4x4x1_16b_f32 v[36:39], v137, v232, v[36:39]
	v_mfma_f32_4x4x1_16b_f32 v[40:43], v138, v232, v[40:43]
	v_mfma_f32_4x4x1_16b_f32 v[44:47], v139, v232, v[44:47]
	v_mfma_f32_4x4x1_16b_f32 v[48:51], v140, v232, v[48:51]
	v_mfma_f32_4x4x1_16b_f32 v[52:55], v141, v232, v[52:55]
	v_mfma_f32_4x4x1_16b_f32 v[56:59], v142, v232, v[56:59]
	v_mfma_f32_4x4x1_16b_f32 v[60:63], v143, v232, v[60:63]
	v_mfma_f32_4x4x1_16b_f32 v[0:3], v144, v190, v[0:3]
	v_mfma_f32_4x4x1_16b_f32 v[4:7], v145, v190, v[4:7]
	v_mfma_f32_4x4x1_16b_f32 v[8:11], v146, v190, v[8:11]
	v_mfma_f32_4x4x1_16b_f32 v[12:15], v147, v190, v[12:15]
	v_mfma_f32_4x4x1_16b_f32 v[16:19], v148, v190, v[16:19]
	v_mfma_f32_4x4x1_16b_f32 v[20:23], v149, v190, v[20:23]
	v_mfma_f32_4x4x1_16b_f32 v[24:27], v150, v190, v[24:27]
	v_mfma_f32_4x4x1_16b_f32 v[28:31], v151, v190, v[28:31]
	v_mfma_f32_4x4x1_16b_f32 v[32:35], v152, v190, v[32:35]
	v_mfma_f32_4x4x1_16b_f32 v[36:39], v153, v190, v[36:39]
	v_mfma_f32_4x4x1_16b_f32 v[40:43], v154, v190, v[40:43]
	v_mfma_f32_4x4x1_16b_f32 v[44:47], v155, v190, v[44:47]
	v_mfma_f32_4x4x1_16b_f32 v[48:51], v156, v190, v[48:51]
	v_mfma_f32_4x4x1_16b_f32 v[52:55], v157, v190, v[52:55]
	v_mfma_f32_4x4x1_16b_f32 v[56:59], v158, v190, v[56:59]
	v_mfma_f32_4x4x1_16b_f32 v[60:63], v159, v190, v[60:63]
	v_mfma_f32_4x4x1_16b_f32 v[64:67], v128, v233, v[64:67]
	v_mfma_f32_4x4x1_16b_f32 v[68:71], v129, v233, v[68:71]
	v_mfma_f32_4x4x1_16b_f32 v[72:75], v130, v233, v[72:75]
	v_mfma_f32_4x4x1_16b_f32 v[76:79], v131, v233, v[76:79]
	v_mfma_f32_4x4x1_16b_f32 v[80:83], v132, v233, v[80:83]
	v_mfma_f32_4x4x1_16b_f32 v[84:87], v133, v233, v[84:87]
	v_mfma_f32_4x4x1_16b_f32 v[88:91], v134, v233, v[88:91]
	v_mfma_f32_4x4x1_16b_f32 v[92:95], v135, v233, v[92:95]
	v_mfma_f32_4x4x1_16b_f32 v[96:99], v136, v233, v[96:99]
	v_mfma_f32_4x4x1_16b_f32 v[100:103], v137, v233, v[100:103]
	v_mfma_f32_4x4x1_16b_f32 v[104:107], v138, v233, v[104:107]
	v_mfma_f32_4x4x1_16b_f32 v[108:111], v139, v233, v[108:111]
	v_mfma_f32_4x4x1_16b_f32 v[112:115], v140, v233, v[112:115]
	v_mfma_f32_4x4x1_16b_f32 v[116:119], v141, v233, v[116:119]
	v_mfma_f32_4x4x1_16b_f32 v[120:123], v142, v233, v[120:123]
	v_mfma_f32_4x4x1_16b_f32 v[124:127], v143, v233, v[124:127]
	s_waitcnt vmcnt(5)
; #define SB __builtin_amdgcn_sched_barrier(0)
; #define TOUCH1(set) asm volatile("" :: "v"(set.w), "v"(set.a), "v"(set.b), "v"(set.kw), "v"(set.v))
; #define ST1(set) { DERIVE_BK(set); float sd[4]; ScanK<0>::dot(S, set.a, sd); ScanK<0>::updS(S, set, -((sd[0] + sd[1]) + (sd[2] + sd[3])), __uint_as_float(set.v << 16)); }
; #define TOUCH1(set) asm volatile("" :: "v"(set.w), "v"(set.a), "v"(set.b))
;     static __device__ __forceinline__ void dot(const float (&S)[64], const f32x4& a, float (&s)[4]) {
;         if constexpr (K == 0) {
;             asm volatile("v_mul_f32_dpp %0, %4, %8 row_newbcast:%16" DPPM "v_mul_f32_dpp %1, %5, %9 row_newbcast:%16" DPPM "v_mul_f32_dpp %2, %6, %10 row_newbcast:%16" DPPM "v_mul_f32_dpp %3, %7, %11 row_newbcast:%16" DPPM
;                          "v_fmac_f32_dpp %0, %4, %12 row_newbcast:%17" DPPM "v_fmac_f32_dpp %1, %5, %13 row_newbcast:%17" DPPM "v_fmac_f32_dpp %2, %6, %14 row_newbcast:%17" DPPM "v_fmac_f32_dpp %3, %7, %15 row_newbcast:%17" DPPM
;                          : "=&v"(s[0]), "=&v"(s[1]), "=&v"(s[2]), "=&v"(s[3])
;                          : "v"(a[0]), "v"(a[1]), "v"(a[2]), "v"(a[3]), "v"(S[K]), "v"(S[K + 1]), "v"(S[K + 2]), "v"(S[K + 3]), "v"(S[K + 4]), "v"(S[K + 5]), "v"(S[K + 6]), "v"(S[K + 7]), "n"(N0), "n"(N1));
;         } else
;         asm volatile("v_fmac_f32_dpp %0, %4, %8 row_newbcast:%16" DPPM "v_fmac_f32_dpp %1, %5, %9 row_newbcast:%16" DPPM "v_fmac_f32_dpp %2, %6, %10 row_newbcast:%16" DPPM "v_fmac_f32_dpp %3, %7, %11 row_newbcast:%16" DPPM
;                      "v_fmac_f32_dpp %0, %4, %12 row_newbcast:%17" DPPM "v_fmac_f32_dpp %1, %5, %13 row_newbcast:%17" DPPM "v_fmac_f32_dpp %2, %6, %14 row_newbcast:%17" DPPM "v_fmac_f32_dpp %3, %7, %15 row_newbcast:%17" DPPM
;                      : "+v"(s[0]), "+v"(s[1]), "+v"(s[2]), "+v"(s[3])
;                      : "v"(a[0]), "v"(a[1]), "v"(a[2]), "v"(a[3]), "v"(S[K]), "v"(S[K + 1]), "v"(S[K + 2]), "v"(S[K + 3]), "v"(S[K + 4]), "v"(S[K + 5]), "v"(S[K + 6]), "v"(S[K + 7]), "n"(N0), "n"(N1));
;         if constexpr (K + 8 < 64) ScanK<K + 8>::dot(S, a, s);
; template <bool MIX> __device__ __forceinline__ void scan_pass1(const Params& p, int d, float* ldsf) {
;     ...
;             In1 i0, i1; LD1(i0, 0);
; #pragma unroll 1
;             for (int s = 0; s < LC; s += 2) { TOUCH1(i0); SB; LD1(i1, s + 1); SB; ST1(i0); TOUCH1(i1); SB; LD1(i0, s + 2); SB; ST1(i1); }
	buffer_load_dwordx4 v[176:179], v235, s[64:67], s72 offen
	buffer_load_dwordx4 v[180:183], v250, s[64:67], s72 offen
	buffer_load_dwordx4 v[184:187], v251, s[64:67], s72 offen
	buffer_load_dwordx2 v[188:189], v252, s[64:67], s76 offen
	buffer_load_short_d16_hi v190, v253, s[64:67], s76 offen
	s_add_i32 s72, s72, 0xfffff000
	s_max_i32 s72, s72, 0
	s_add_i32 s76, s76, 0xfffff800
	s_max_i32 s76, s76, 0
	v_pk_mul_f32 v[244:245], v[196:197], v[236:237]
	v_pk_mul_f32 v[246:247], v[198:199], v[238:239]
	v_pk_mul_f32 v[236:237], v[236:237], v[192:193]
	v_pk_mul_f32 v[238:239], v[238:239], v[194:195]
	v_pk_fma_f32 v[228:229], v[200:201], v[216:217], v[220:221]
	v_pk_fma_f32 v[230:231], v[202:203], v[218:219], v[222:223]
	v_pk_mul_f32 v[208:209], v[196:197], v[200:201]
	v_pk_mul_f32 v[210:211], v[198:199], v[202:203]
	v_rcp_f32_e32 v240, v236
	v_rcp_f32_e32 v241, v237
	v_rcp_f32_e32 v242, v238
	v_rcp_f32_e32 v243, v239
	v_lshlrev_b32_e32 v212, 16, v204
	v_and_b32_e32 v213, 0xffff0000, v204
	v_lshlrev_b32_e32 v214, 16, v205
	v_and_b32_e32 v215, 0xffff0000, v205
	v_pk_mul_f32 v[212:213], v[212:213], v[228:229]
	v_pk_mul_f32 v[214:215], v[214:215], v[230:231]
	v_pk_mul_f32 v[208:209], v[208:209], v[240:241]
	v_pk_mul_f32 v[210:211], v[210:211], v[242:243]
	v_pk_mul_f32 v[212:213], v[212:213], v[240:241]
	v_pk_mul_f32 v[214:215], v[214:215], v[242:243]
	ds_write2_b32 v248, v208, v209 offset0:0 offset1:16
	ds_write2_b32 v248, v210, v211 offset0:32 offset1:48
	ds_write2_b32 v248, v212, v213 offset0:64 offset1:80
	ds_write2_b32 v248, v214, v215 offset0:96 offset1:112
	ds_read_b128 v[128:131], v249 offset:0
	ds_read_b128 v[132:135], v249 offset:16
	ds_read_b128 v[136:139], v249 offset:32
	ds_read_b128 v[140:143], v249 offset:48
	ds_read_b128 v[144:147], v249 offset:256
	ds_read_b128 v[148:151], v249 offset:272
	ds_read_b128 v[152:155], v249 offset:288
	ds_read_b128 v[156:159], v249 offset:304
	v_mul_f32_dpp v224, v244, v0 row_newbcast:0 row_mask:0xf bank_mask:0xf
	v_mul_f32_dpp v225, v245, v1 row_newbcast:0 row_mask:0xf bank_mask:0xf
	v_fmac_f32_dpp v224, v246, v2 row_newbcast:0 row_mask:0xf bank_mask:0xf
	v_fmac_f32_dpp v225, v247, v3 row_newbcast:0 row_mask:0xf bank_mask:0xf
	v_fmac_f32_dpp v224, v244, v4 row_newbcast:1 row_mask:0xf bank_mask:0xf
	v_fmac_f32_dpp v225, v245, v5 row_newbcast:1 row_mask:0xf bank_mask:0xf
	v_fmac_f32_dpp v224, v246, v6 row_newbcast:1 row_mask:0xf bank_mask:0xf
	v_fmac_f32_dpp v225, v247, v7 row_newbcast:1 row_mask:0xf bank_mask:0xf
	v_fmac_f32_dpp v224, v244, v8 row_newbcast:2 row_mask:0xf bank_mask:0xf
	v_fmac_f32_dpp v225, v245, v9 row_newbcast:2 row_mask:0xf bank_mask:0xf
	v_fmac_f32_dpp v224, v246, v10 row_newbcast:2 row_mask:0xf bank_mask:0xf
	v_fmac_f32_dpp v225, v247, v11 row_newbcast:2 row_mask:0xf bank_mask:0xf
	v_fmac_f32_dpp v224, v244, v12 row_newbcast:3 row_mask:0xf bank_mask:0xf
	v_fmac_f32_dpp v225, v245, v13 row_newbcast:3 row_mask:0xf bank_mask:0xf
	v_fmac_f32_dpp v224, v246, v14 row_newbcast:3 row_mask:0xf bank_mask:0xf
	v_fmac_f32_dpp v225, v247, v15 row_newbcast:3 row_mask:0xf bank_mask:0xf
	v_fmac_f32_dpp v224, v244, v16 row_newbcast:4 row_mask:0xf bank_mask:0xf
	v_fmac_f32_dpp v225, v245, v17 row_newbcast:4 row_mask:0xf bank_mask:0xf
	v_fmac_f32_dpp v224, v246, v18 row_newbcast:4 row_mask:0xf bank_mask:0xf
	v_fmac_f32_dpp v225, v247, v19 row_newbcast:4 row_mask:0xf bank_mask:0xf
	v_fmac_f32_dpp v224, v244, v20 row_newbcast:5 row_mask:0xf bank_mask:0xf
	v_fmac_f32_dpp v225, v245, v21 row_newbcast:5 row_mask:0xf bank_mask:0xf
	v_fmac_f32_dpp v224, v246, v22 row_newbcast:5 row_mask:0xf bank_mask:0xf
	v_fmac_f32_dpp v225, v247, v23 row_newbcast:5 row_mask:0xf bank_mask:0xf
	v_fmac_f32_dpp v224, v244, v24 row_newbcast:6 row_mask:0xf bank_mask:0xf
	v_fmac_f32_dpp v225, v245, v25 row_newbcast:6 row_mask:0xf bank_mask:0xf
	v_fmac_f32_dpp v224, v246, v26 row_newbcast:6 row_mask:0xf bank_mask:0xf
	v_fmac_f32_dpp v225, v247, v27 row_newbcast:6 row_mask:0xf bank_mask:0xf
	v_fmac_f32_dpp v224, v244, v28 row_newbcast:7 row_mask:0xf bank_mask:0xf
	v_fmac_f32_dpp v225, v245, v29 row_newbcast:7 row_mask:0xf bank_mask:0xf
	v_fmac_f32_dpp v224, v246, v30 row_newbcast:7 row_mask:0xf bank_mask:0xf
	v_fmac_f32_dpp v225, v247, v31 row_newbcast:7 row_mask:0xf bank_mask:0xf
	v_fmac_f32_dpp v224, v244, v32 row_newbcast:8 row_mask:0xf bank_mask:0xf
	v_fmac_f32_dpp v225, v245, v33 row_newbcast:8 row_mask:0xf bank_mask:0xf
	v_fmac_f32_dpp v224, v246, v34 row_newbcast:8 row_mask:0xf bank_mask:0xf
	v_fmac_f32_dpp v225, v247, v35 row_newbcast:8 row_mask:0xf bank_mask:0xf
	v_fmac_f32_dpp v224, v244, v36 row_newbcast:9 row_mask:0xf bank_mask:0xf
	v_fmac_f32_dpp v225, v245, v37 row_newbcast:9 row_mask:0xf bank_mask:0xf
	v_fmac_f32_dpp v224, v246, v38 row_newbcast:9 row_mask:0xf bank_mask:0xf
	v_fmac_f32_dpp v225, v247, v39 row_newbcast:9 row_mask:0xf bank_mask:0xf
	v_fmac_f32_dpp v224, v244, v40 row_newbcast:10 row_mask:0xf bank_mask:0xf
	v_fmac_f32_dpp v225, v245, v41 row_newbcast:10 row_mask:0xf bank_mask:0xf
	v_fmac_f32_dpp v224, v246, v42 row_newbcast:10 row_mask:0xf bank_mask:0xf
	v_fmac_f32_dpp v225, v247, v43 row_newbcast:10 row_mask:0xf bank_mask:0xf
	v_fmac_f32_dpp v224, v244, v44 row_newbcast:11 row_mask:0xf bank_mask:0xf
	v_fmac_f32_dpp v225, v245, v45 row_newbcast:11 row_mask:0xf bank_mask:0xf
	v_fmac_f32_dpp v224, v246, v46 row_newbcast:11 row_mask:0xf bank_mask:0xf
	v_fmac_f32_dpp v225, v247, v47 row_newbcast:11 row_mask:0xf bank_mask:0xf
	v_fmac_f32_dpp v224, v244, v48 row_newbcast:12 row_mask:0xf bank_mask:0xf
	v_fmac_f32_dpp v225, v245, v49 row_newbcast:12 row_mask:0xf bank_mask:0xf
;     static __device__ __forceinline__ void dot(const float (&S)[64], const f32x4& a, float (&s)[4]) {
;         if constexpr (K == 0) {
;             asm volatile("v_mul_f32_dpp %0, %4, %8 row_newbcast:%16" DPPM "v_mul_f32_dpp %1, %5, %9 row_newbcast:%16" DPPM "v_mul_f32_dpp %2, %6, %10 row_newbcast:%16" DPPM "v_mul_f32_dpp %3, %7, %11 row_newbcast:%16" DPPM
;                          "v_fmac_f32_dpp %0, %4, %12 row_newbcast:%17" DPPM "v_fmac_f32_dpp %1, %5, %13 row_newbcast:%17" DPPM "v_fmac_f32_dpp %2, %6, %14 row_newbcast:%17" DPPM "v_fmac_f32_dpp %3, %7, %15 row_newbcast:%17" DPPM
;                          : "=&v"(s[0]), "=&v"(s[1]), "=&v"(s[2]), "=&v"(s[3])
;                          : "v"(a[0]), "v"(a[1]), "v"(a[2]), "v"(a[3]), "v"(S[K]), "v"(S[K + 1]), "v"(S[K + 2]), "v"(S[K + 3]), "v"(S[K + 4]), "v"(S[K + 5]), "v"(S[K + 6]), "v"(S[K + 7]), "n"(N0), "n"(N1));
;         } else
;         asm volatile("v_fmac_f32_dpp %0, %4, %8 row_newbcast:%16" DPPM "v_fmac_f32_dpp %1, %5, %9 row_newbcast:%16" DPPM "v_fmac_f32_dpp %2, %6, %10 row_newbcast:%16" DPPM "v_fmac_f32_dpp %3, %7, %11 row_newbcast:%16" DPPM
;                      "v_fmac_f32_dpp %0, %4, %12 row_newbcast:%17" DPPM "v_fmac_f32_dpp %1, %5, %13 row_newbcast:%17" DPPM "v_fmac_f32_dpp %2, %6, %14 row_newbcast:%17" DPPM "v_fmac_f32_dpp %3, %7, %15 row_newbcast:%17" DPPM
;                      : "+v"(s[0]), "+v"(s[1]), "+v"(s[2]), "+v"(s[3])
;                      : "v"(a[0]), "v"(a[1]), "v"(a[2]), "v"(a[3]), "v"(S[K]), "v"(S[K + 1]), "v"(S[K + 2]), "v"(S[K + 3]), "v"(S[K + 4]), "v"(S[K + 5]), "v"(S[K + 6]), "v"(S[K + 7]), "n"(N0), "n"(N1));
;         if constexpr (K + 8 < 64) ScanK<K + 8>::dot(S, a, s);
	v_fmac_f32_dpp v224, v246, v50 row_newbcast:12 row_mask:0xf bank_mask:0xf
	v_fmac_f32_dpp v225, v247, v51 row_newbcast:12 row_mask:0xf bank_mask:0xf
	v_fmac_f32_dpp v224, v244, v52 row_newbcast:13 row_mask:0xf bank_mask:0xf
	v_fmac_f32_dpp v225, v245, v53 row_newbcast:13 row_mask:0xf bank_mask:0xf
	v_fmac_f32_dpp v224, v246, v54 row_newbcast:13 row_mask:0xf bank_mask:0xf
	v_fmac_f32_dpp v225, v247, v55 row_newbcast:13 row_mask:0xf bank_mask:0xf
	v_fmac_f32_dpp v224, v244, v56 row_newbcast:14 row_mask:0xf bank_mask:0xf
	v_fmac_f32_dpp v225, v245, v57 row_newbcast:14 row_mask:0xf bank_mask:0xf
	v_fmac_f32_dpp v224, v246, v58 row_newbcast:14 row_mask:0xf bank_mask:0xf
	v_fmac_f32_dpp v225, v247, v59 row_newbcast:14 row_mask:0xf bank_mask:0xf
	v_fmac_f32_dpp v224, v244, v60 row_newbcast:15 row_mask:0xf bank_mask:0xf
	v_fmac_f32_dpp v225, v245, v61 row_newbcast:15 row_mask:0xf bank_mask:0xf
	v_fmac_f32_dpp v224, v246, v62 row_newbcast:15 row_mask:0xf bank_mask:0xf
	v_fmac_f32_dpp v225, v247, v63 row_newbcast:15 row_mask:0xf bank_mask:0xf
	v_mul_f32_dpp v228, v244, v64 row_newbcast:0 row_mask:0xf bank_mask:0xf
	v_mul_f32_dpp v229, v245, v65 row_newbcast:0 row_mask:0xf bank_mask:0xf
	v_fmac_f32_dpp v228, v246, v66 row_newbcast:0 row_mask:0xf bank_mask:0xf
	v_fmac_f32_dpp v229, v247, v67 row_newbcast:0 row_mask:0xf bank_mask:0xf
	v_fmac_f32_dpp v228, v244, v68 row_newbcast:1 row_mask:0xf bank_mask:0xf
	v_fmac_f32_dpp v229, v245, v69 row_newbcast:1 row_mask:0xf bank_mask:0xf
	v_fmac_f32_dpp v228, v246, v70 row_newbcast:1 row_mask:0xf bank_mask:0xf
	v_fmac_f32_dpp v229, v247, v71 row_newbcast:1 row_mask:0xf bank_mask:0xf
	v_fmac_f32_dpp v228, v244, v72 row_newbcast:2 row_mask:0xf bank_mask:0xf
	v_fmac_f32_dpp v229, v245, v73 row_newbcast:2 row_mask:0xf bank_mask:0xf
	v_fmac_f32_dpp v228, v246, v74 row_newbcast:2 row_mask:0xf bank_mask:0xf
	v_fmac_f32_dpp v229, v247, v75 row_newbcast:2 row_mask:0xf bank_mask:0xf
	v_fmac_f32_dpp v228, v244, v76 row_newbcast:3 row_mask:0xf bank_mask:0xf
	v_fmac_f32_dpp v229, v245, v77 row_newbcast:3 row_mask:0xf bank_mask:0xf
	v_fmac_f32_dpp v228, v246, v78 row_newbcast:3 row_mask:0xf bank_mask:0xf
	v_fmac_f32_dpp v229, v247, v79 row_newbcast:3 row_mask:0xf bank_mask:0xf
	v_fmac_f32_dpp v228, v244, v80 row_newbcast:4 row_mask:0xf bank_mask:0xf
	v_fmac_f32_dpp v229, v245, v81 row_newbcast:4 row_mask:0xf bank_mask:0xf
	v_fmac_f32_dpp v228, v246, v82 row_newbcast:4 row_mask:0xf bank_mask:0xf
	v_fmac_f32_dpp v229, v247, v83 row_newbcast:4 row_mask:0xf bank_mask:0xf
	v_fmac_f32_dpp v228, v244, v84 row_newbcast:5 row_mask:0xf bank_mask:0xf
	v_fmac_f32_dpp v229, v245, v85 row_newbcast:5 row_mask:0xf bank_mask:0xf
	v_fmac_f32_dpp v228, v246, v86 row_newbcast:5 row_mask:0xf bank_mask:0xf
	v_fmac_f32_dpp v229, v247, v87 row_newbcast:5 row_mask:0xf bank_mask:0xf
	v_fmac_f32_dpp v228, v244, v88 row_newbcast:6 row_mask:0xf bank_mask:0xf
	v_fmac_f32_dpp v229, v245, v89 row_newbcast:6 row_mask:0xf bank_mask:0xf
	v_fmac_f32_dpp v228, v246, v90 row_newbcast:6 row_mask:0xf bank_mask:0xf
	v_fmac_f32_dpp v229, v247, v91 row_newbcast:6 row_mask:0xf bank_mask:0xf
	v_fmac_f32_dpp v228, v244, v92 row_newbcast:7 row_mask:0xf bank_mask:0xf
	v_fmac_f32_dpp v229, v245, v93 row_newbcast:7 row_mask:0xf bank_mask:0xf
	v_fmac_f32_dpp v228, v246, v94 row_newbcast:7 row_mask:0xf bank_mask:0xf
	v_fmac_f32_dpp v229, v247, v95 row_newbcast:7 row_mask:0xf bank_mask:0xf
	v_fmac_f32_dpp v228, v244, v96 row_newbcast:8 row_mask:0xf bank_mask:0xf
	v_fmac_f32_dpp v229, v245, v97 row_newbcast:8 row_mask:0xf bank_mask:0xf
	v_fmac_f32_dpp v228, v246, v98 row_newbcast:8 row_mask:0xf bank_mask:0xf
	v_fmac_f32_dpp v229, v247, v99 row_newbcast:8 row_mask:0xf bank_mask:0xf
	v_fmac_f32_dpp v228, v244, v100 row_newbcast:9 row_mask:0xf bank_mask:0xf
	v_fmac_f32_dpp v229, v245, v101 row_newbcast:9 row_mask:0xf bank_mask:0xf
	v_fmac_f32_dpp v228, v246, v102 row_newbcast:9 row_mask:0xf bank_mask:0xf
	v_fmac_f32_dpp v229, v247, v103 row_newbcast:9 row_mask:0xf bank_mask:0xf
	v_fmac_f32_dpp v228, v244, v104 row_newbcast:10 row_mask:0xf bank_mask:0xf
	v_fmac_f32_dpp v229, v245, v105 row_newbcast:10 row_mask:0xf bank_mask:0xf
	v_fmac_f32_dpp v228, v246, v106 row_newbcast:10 row_mask:0xf bank_mask:0xf
	v_fmac_f32_dpp v229, v247, v107 row_newbcast:10 row_mask:0xf bank_mask:0xf
	v_fmac_f32_dpp v228, v244, v108 row_newbcast:11 row_mask:0xf bank_mask:0xf
	v_fmac_f32_dpp v229, v245, v109 row_newbcast:11 row_mask:0xf bank_mask:0xf
	v_fmac_f32_dpp v228, v246, v110 row_newbcast:11 row_mask:0xf bank_mask:0xf
	v_fmac_f32_dpp v229, v247, v111 row_newbcast:11 row_mask:0xf bank_mask:0xf
	v_fmac_f32_dpp v228, v244, v112 row_newbcast:12 row_mask:0xf bank_mask:0xf
	v_fmac_f32_dpp v229, v245, v113 row_newbcast:12 row_mask:0xf bank_mask:0xf
	v_fmac_f32_dpp v228, v246, v114 row_newbcast:12 row_mask:0xf bank_mask:0xf
	v_fmac_f32_dpp v229, v247, v115 row_newbcast:12 row_mask:0xf bank_mask:0xf
	v_fmac_f32_dpp v228, v244, v116 row_newbcast:13 row_mask:0xf bank_mask:0xf
	v_fmac_f32_dpp v229, v245, v117 row_newbcast:13 row_mask:0xf bank_mask:0xf
	v_fmac_f32_dpp v228, v246, v118 row_newbcast:13 row_mask:0xf bank_mask:0xf
	v_fmac_f32_dpp v229, v247, v119 row_newbcast:13 row_mask:0xf bank_mask:0xf
	v_fmac_f32_dpp v228, v244, v120 row_newbcast:14 row_mask:0xf bank_mask:0xf
	v_fmac_f32_dpp v229, v245, v121 row_newbcast:14 row_mask:0xf bank_mask:0xf
	v_fmac_f32_dpp v228, v246, v122 row_newbcast:14 row_mask:0xf bank_mask:0xf
	v_fmac_f32_dpp v229, v247, v123 row_newbcast:14 row_mask:0xf bank_mask:0xf
	v_fmac_f32_dpp v228, v244, v124 row_newbcast:15 row_mask:0xf bank_mask:0xf
	v_fmac_f32_dpp v229, v245, v125 row_newbcast:15 row_mask:0xf bank_mask:0xf
	v_fmac_f32_dpp v228, v246, v126 row_newbcast:15 row_mask:0xf bank_mask:0xf
	v_fmac_f32_dpp v229, v247, v127 row_newbcast:15 row_mask:0xf bank_mask:0xf
	v_sub_f32_e64 v232, -v224, v225
	v_sub_f32_e64 v233, -v228, v229
	s_waitcnt lgkmcnt(0)
;     static __device__ __forceinline__ void updS(float (&S)[64], const In1& in, float sa, float vv) {
;         float t0, t1, t2, t3;
;         asm volatile("v_mul_f32_dpp %0, %8, %21 row_newbcast:%22" DPPM "v_mul_f32_dpp %1, %9, %21 row_newbcast:%22" DPPM "v_mul_f32_dpp %2, %10, %21 row_newbcast:%22" DPPM "v_mul_f32_dpp %3, %11, %21 row_newbcast:%22" DPPM
;                      "v_fmac_f32_dpp %0, %12, %4 row_newbcast:%22" DPPM "v_fmac_f32_dpp %1, %13, %5 row_newbcast:%22" DPPM "v_fmac_f32_dpp %2, %14, %6 row_newbcast:%22" DPPM "v_fmac_f32_dpp %3, %15, %7 row_newbcast:%22" DPPM
;                      "v_fmac_f32_dpp %0, %16, %20 row_newbcast:%22" DPPM "v_fmac_f32_dpp %1, %17, %20 row_newbcast:%22" DPPM "v_fmac_f32_dpp %2, %18, %20 row_newbcast:%22" DPPM "v_fmac_f32_dpp %3, %19, %20 row_newbcast:%22" DPPM
;                      : "=&v"(t0), "=&v"(t1), "=&v"(t2), "=&v"(t3)
;                      : "v"(S[K]), "v"(S[K + 1]), "v"(S[K + 2]), "v"(S[K + 3]), "v"(in.kd[0]), "v"(in.kd[1]), "v"(in.kd[2]), "v"(in.kd[3]), "v"(in.w[0]), "v"(in.w[1]), "v"(in.w[2]), "v"(in.w[3]),
;                        "v"(in.b[0]), "v"(in.b[1]), "v"(in.b[2]), "v"(in.b[3]), "v"(sa), "v"(vv), "n"(N0));
;         S[K] = t0; S[K + 1] = t1; S[K + 2] = t2; S[K + 3] = t3;
;         if constexpr (K + 4 < 64) ScanK<K + 4>::updS(S, in, sa, vv);
;     }
;     static __device__ __forceinline__ void updP(float (&P)[64], const In1& in, float sa) {
;         float u0, u1, u2, u3;
;         asm volatile("v_mul_f32_dpp %0, %8, %4 row_newbcast:%17" DPPM "v_mul_f32_dpp %1, %9, %5 row_newbcast:%17" DPPM "v_mul_f32_dpp %2, %10, %6 row_newbcast:%17" DPPM "v_mul_f32_dpp %3, %11, %7 row_newbcast:%17" DPPM
;                      "v_fmac_f32_dpp %0, %12, %16 row_newbcast:%17" DPPM "v_fmac_f32_dpp %1, %13, %16 row_newbcast:%17" DPPM "v_fmac_f32_dpp %2, %14, %16 row_newbcast:%17" DPPM "v_fmac_f32_dpp %3, %15, %16 row_newbcast:%17" DPPM
;                      : "=&v"(u0), "=&v"(u1), "=&v"(u2), "=&v"(u3)
;                      : "v"(P[K]), "v"(P[K + 1]), "v"(P[K + 2]), "v"(P[K + 3]), "v"(in.w[0]), "v"(in.w[1]), "v"(in.w[2]), "v"(in.w[3]), "v"(in.b[0]), "v"(in.b[1]), "v"(in.b[2]), "v"(in.b[3]), "v"(sa), "n"(N0));
;         P[K] = u0; P[K + 1] = u1; P[K + 2] = u2; P[K + 3] = u3;
;         if constexpr (K + 4 < 64) ScanK<K + 4>::updP(P, in, sa);
;     }
	v_mfma_f32_4x4x1_16b_f32 v[0:3], v128, v232, v[0:3]
	v_mfma_f32_4x4x1_16b_f32 v[4:7], v129, v232, v[4:7]
	v_mfma_f32_4x4x1_16b_f32 v[8:11], v130, v232, v[8:11]
	v_mfma_f32_4x4x1_16b_f32 v[12:15], v131, v232, v[12:15]
	v_mfma_f32_4x4x1_16b_f32 v[16:19], v132, v232, v[16:19]
	v_mfma_f32_4x4x1_16b_f32 v[20:23], v133, v232, v[20:23]
	v_mfma_f32_4x4x1_16b_f32 v[24:27], v134, v232, v[24:27]
	v_mfma_f32_4x4x1_16b_f32 v[28:31], v135, v232, v[28:31]
	v_mfma_f32_4x4x1_16b_f32 v[32:35], v136, v232, v[32:35]
	v_mfma_f32_4x4x1_16b_f32 v[36:39], v137, v232, v[36:39]
	v_mfma_f32_4x4x1_16b_f32 v[40:43], v138, v232, v[40:43]
	v_mfma_f32_4x4x1_16b_f32 v[44:47], v139, v232, v[44:47]
	v_mfma_f32_4x4x1_16b_f32 v[48:51], v140, v232, v[48:51]
	v_mfma_f32_4x4x1_16b_f32 v[52:55], v141, v232, v[52:55]
	v_mfma_f32_4x4x1_16b_f32 v[56:59], v142, v232, v[56:59]
	v_mfma_f32_4x4x1_16b_f32 v[60:63], v143, v232, v[60:63]
	v_mfma_f32_4x4x1_16b_f32 v[0:3], v144, v206, v[0:3]
	v_mfma_f32_4x4x1_16b_f32 v[4:7], v145, v206, v[4:7]
	v_mfma_f32_4x4x1_16b_f32 v[8:11], v146, v206, v[8:11]
	v_mfma_f32_4x4x1_16b_f32 v[12:15], v147, v206, v[12:15]
	v_mfma_f32_4x4x1_16b_f32 v[16:19], v148, v206, v[16:19]
	v_mfma_f32_4x4x1_16b_f32 v[20:23], v149, v206, v[20:23]
	v_mfma_f32_4x4x1_16b_f32 v[24:27], v150, v206, v[24:27]
	v_mfma_f32_4x4x1_16b_f32 v[28:31], v151, v206, v[28:31]
	v_mfma_f32_4x4x1_16b_f32 v[32:35], v152, v206, v[32:35]
	v_mfma_f32_4x4x1_16b_f32 v[36:39], v153, v206, v[36:39]
	v_mfma_f32_4x4x1_16b_f32 v[40:43], v154, v206, v[40:43]
	v_mfma_f32_4x4x1_16b_f32 v[44:47], v155, v206, v[44:47]
	v_mfma_f32_4x4x1_16b_f32 v[48:51], v156, v206, v[48:51]
	v_mfma_f32_4x4x1_16b_f32 v[52:55], v157, v206, v[52:55]
	v_mfma_f32_4x4x1_16b_f32 v[56:59], v158, v206, v[56:59]
	v_mfma_f32_4x4x1_16b_f32 v[60:63], v159, v206, v[60:63]
	v_mfma_f32_4x4x1_16b_f32 v[64:67], v128, v233, v[64:67]
	v_mfma_f32_4x4x1_16b_f32 v[68:71], v129, v233, v[68:71]
	v_mfma_f32_4x4x1_16b_f32 v[72:75], v130, v233, v[72:75]
	v_mfma_f32_4x4x1_16b_f32 v[76:79], v131, v233, v[76:79]
	v_mfma_f32_4x4x1_16b_f32 v[80:83], v132, v233, v[80:83]
	v_mfma_f32_4x4x1_16b_f32 v[84:87], v133, v233, v[84:87]
	v_mfma_f32_4x4x1_16b_f32 v[88:91], v134, v233, v[88:91]
	v_mfma_f32_4x4x1_16b_f32 v[92:95], v135, v233, v[92:95]
	v_mfma_f32_4x4x1_16b_f32 v[96:99], v136, v233, v[96:99]
	v_mfma_f32_4x4x1_16b_f32 v[100:103], v137, v233, v[100:103]
	v_mfma_f32_4x4x1_16b_f32 v[104:107], v138, v233, v[104:107]
	v_mfma_f32_4x4x1_16b_f32 v[108:111], v139, v233, v[108:111]
	v_mfma_f32_4x4x1_16b_f32 v[112:115], v140, v233, v[112:115]
	v_mfma_f32_4x4x1_16b_f32 v[116:119], v141, v233, v[116:119]
	v_mfma_f32_4x4x1_16b_f32 v[120:123], v142, v233, v[120:123]
	v_mfma_f32_4x4x1_16b_f32 v[124:127], v143, v233, v[124:127]
	s_sub_u32 s83, s83, 1
	s_cmp_eq_u32 s83, 0
	s_cbranch_scc1 .Lmy_p1d1_ldone
	s_sub_u32 s9, s9, 1
	s_cmp_eq_u32 s9, 0
	s_cbranch_scc1 .Lmy_p1d1_renorm
	s_branch .Lmy_p1d1_loop
.Lmy_p1d1_ldone:
	s_waitcnt vmcnt(5)
	buffer_load_dwordx4 v[192:195], v235, s[64:67], s72 offen
	buffer_load_dwordx4 v[196:199], v250, s[64:67], s72 offen
	buffer_load_dwordx4 v[200:203], v251, s[64:67], s72 offen
	buffer_load_dwordx2 v[204:205], v252, s[64:67], s76 offen
	buffer_load_short_d16_hi v206, v253, s[64:67], s76 offen
	s_add_i32 s72, s72, 0xfffff000
	s_max_i32 s72, s72, 0
	s_add_i32 s76, s76, 0xfffff800
	s_max_i32 s76, s76, 0
	v_pk_mul_f32 v[244:245], v[164:165], v[236:237]
	v_pk_mul_f32 v[246:247], v[166:167], v[238:239]
	v_pk_mul_f32 v[236:237], v[236:237], v[160:161]
	v_pk_mul_f32 v[238:239], v[238:239], v[162:163]
	v_pk_fma_f32 v[228:229], v[168:169], v[216:217], v[220:221]
	v_pk_fma_f32 v[230:231], v[170:171], v[218:219], v[222:223]
	v_pk_mul_f32 v[208:209], v[164:165], v[168:169]
	v_pk_mul_f32 v[210:211], v[166:167], v[170:171]
	v_rcp_f32_e32 v240, v236
	v_rcp_f32_e32 v241, v237
	v_rcp_f32_e32 v242, v238
	v_rcp_f32_e32 v243, v239
	v_lshlrev_b32_e32 v212, 16, v172
	v_and_b32_e32 v213, 0xffff0000, v172
	v_lshlrev_b32_e32 v214, 16, v173
	v_and_b32_e32 v215, 0xffff0000, v173
	v_pk_mul_f32 v[212:213], v[212:213], v[228:229]
	v_pk_mul_f32 v[214:215], v[214:215], v[230:231]
	v_pk_mul_f32 v[208:209], v[208:209], v[240:241]
	v_pk_mul_f32 v[210:211], v[210:211], v[242:243]
	v_pk_mul_f32 v[212:213], v[212:213], v[240:241]
	v_pk_mul_f32 v[214:215], v[214:215], v[242:243]
	ds_write2_b32 v248, v208, v209 offset0:0 offset1:16
	ds_write2_b32 v248, v210, v211 offset0:32 offset1:48
	ds_write2_b32 v248, v212, v213 offset0:64 offset1:80
	ds_write2_b32 v248, v214, v215 offset0:96 offset1:112
	ds_read_b128 v[128:131], v249 offset:0
	ds_read_b128 v[132:135], v249 offset:16
	ds_read_b128 v[136:139], v249 offset:32
	ds_read_b128 v[140:143], v249 offset:48
	ds_read_b128 v[144:147], v249 offset:256
	ds_read_b128 v[148:151], v249 offset:272
	ds_read_b128 v[152:155], v249 offset:288
	ds_read_b128 v[156:159], v249 offset:304
	v_mul_f32_dpp v224, v244, v0 row_newbcast:0 row_mask:0xf bank_mask:0xf
	v_mul_f32_dpp v225, v245, v1 row_newbcast:0 row_mask:0xf bank_mask:0xf
	v_fmac_f32_dpp v224, v246, v2 row_newbcast:0 row_mask:0xf bank_mask:0xf
	v_fmac_f32_dpp v225, v247, v3 row_newbcast:0 row_mask:0xf bank_mask:0xf
	v_fmac_f32_dpp v224, v244, v4 row_newbcast:1 row_mask:0xf bank_mask:0xf
	v_fmac_f32_dpp v225, v245, v5 row_newbcast:1 row_mask:0xf bank_mask:0xf
	v_fmac_f32_dpp v224, v246, v6 row_newbcast:1 row_mask:0xf bank_mask:0xf
	v_fmac_f32_dpp v225, v247, v7 row_newbcast:1 row_mask:0xf bank_mask:0xf
	v_fmac_f32_dpp v224, v244, v8 row_newbcast:2 row_mask:0xf bank_mask:0xf
	v_fmac_f32_dpp v225, v245, v9 row_newbcast:2 row_mask:0xf bank_mask:0xf
	v_fmac_f32_dpp v224, v246, v10 row_newbcast:2 row_mask:0xf bank_mask:0xf
;     static __device__ __forceinline__ void dot(const float (&S)[64], const f32x4& a, float (&s)[4]) {
;         if constexpr (K == 0) {
;             asm volatile("v_mul_f32_dpp %0, %4, %8 row_newbcast:%16" DPPM "v_mul_f32_dpp %1, %5, %9 row_newbcast:%16" DPPM "v_mul_f32_dpp %2, %6, %10 row_newbcast:%16" DPPM "v_mul_f32_dpp %3, %7, %11 row_newbcast:%16" DPPM
;                          "v_fmac_f32_dpp %0, %4, %12 row_newbcast:%17" DPPM "v_fmac_f32_dpp %1, %5, %13 row_newbcast:%17" DPPM "v_fmac_f32_dpp %2, %6, %14 row_newbcast:%17" DPPM "v_fmac_f32_dpp %3, %7, %15 row_newbcast:%17" DPPM
;                          : "=&v"(s[0]), "=&v"(s[1]), "=&v"(s[2]), "=&v"(s[3])
;                          : "v"(a[0]), "v"(a[1]), "v"(a[2]), "v"(a[3]), "v"(S[K]), "v"(S[K + 1]), "v"(S[K + 2]), "v"(S[K + 3]), "v"(S[K + 4]), "v"(S[K + 5]), "v"(S[K + 6]), "v"(S[K + 7]), "n"(N0), "n"(N1));
;         } else
;         asm volatile("v_fmac_f32_dpp %0, %4, %8 row_newbcast:%16" DPPM "v_fmac_f32_dpp %1, %5, %9 row_newbcast:%16" DPPM "v_fmac_f32_dpp %2, %6, %10 row_newbcast:%16" DPPM "v_fmac_f32_dpp %3, %7, %11 row_newbcast:%16" DPPM
;                      "v_fmac_f32_dpp %0, %4, %12 row_newbcast:%17" DPPM "v_fmac_f32_dpp %1, %5, %13 row_newbcast:%17" DPPM "v_fmac_f32_dpp %2, %6, %14 row_newbcast:%17" DPPM "v_fmac_f32_dpp %3, %7, %15 row_newbcast:%17" DPPM
;                      : "+v"(s[0]), "+v"(s[1]), "+v"(s[2]), "+v"(s[3])
;                      : "v"(a[0]), "v"(a[1]), "v"(a[2]), "v"(a[3]), "v"(S[K]), "v"(S[K + 1]), "v"(S[K + 2]), "v"(S[K + 3]), "v"(S[K + 4]), "v"(S[K + 5]), "v"(S[K + 6]), "v"(S[K + 7]), "n"(N0), "n"(N1));
;         if constexpr (K + 8 < 64) ScanK<K + 8>::dot(S, a, s);
	v_fmac_f32_dpp v225, v247, v11 row_newbcast:2 row_mask:0xf bank_mask:0xf
	v_fmac_f32_dpp v224, v244, v12 row_newbcast:3 row_mask:0xf bank_mask:0xf
	v_fmac_f32_dpp v225, v245, v13 row_newbcast:3 row_mask:0xf bank_mask:0xf
	v_fmac_f32_dpp v224, v246, v14 row_newbcast:3 row_mask:0xf bank_mask:0xf
	v_fmac_f32_dpp v225, v247, v15 row_newbcast:3 row_mask:0xf bank_mask:0xf
	v_fmac_f32_dpp v224, v244, v16 row_newbcast:4 row_mask:0xf bank_mask:0xf
	v_fmac_f32_dpp v225, v245, v17 row_newbcast:4 row_mask:0xf bank_mask:0xf
	v_fmac_f32_dpp v224, v246, v18 row_newbcast:4 row_mask:0xf bank_mask:0xf
	v_fmac_f32_dpp v225, v247, v19 row_newbcast:4 row_mask:0xf bank_mask:0xf
	v_fmac_f32_dpp v224, v244, v20 row_newbcast:5 row_mask:0xf bank_mask:0xf
	v_fmac_f32_dpp v225, v245, v21 row_newbcast:5 row_mask:0xf bank_mask:0xf
	v_fmac_f32_dpp v224, v246, v22 row_newbcast:5 row_mask:0xf bank_mask:0xf
	v_fmac_f32_dpp v225, v247, v23 row_newbcast:5 row_mask:0xf bank_mask:0xf
	v_fmac_f32_dpp v224, v244, v24 row_newbcast:6 row_mask:0xf bank_mask:0xf
	v_fmac_f32_dpp v225, v245, v25 row_newbcast:6 row_mask:0xf bank_mask:0xf
	v_fmac_f32_dpp v224, v246, v26 row_newbcast:6 row_mask:0xf bank_mask:0xf
	v_fmac_f32_dpp v225, v247, v27 row_newbcast:6 row_mask:0xf bank_mask:0xf
	v_fmac_f32_dpp v224, v244, v28 row_newbcast:7 row_mask:0xf bank_mask:0xf
	v_fmac_f32_dpp v225, v245, v29 row_newbcast:7 row_mask:0xf bank_mask:0xf
	v_fmac_f32_dpp v224, v246, v30 row_newbcast:7 row_mask:0xf bank_mask:0xf
	v_fmac_f32_dpp v225, v247, v31 row_newbcast:7 row_mask:0xf bank_mask:0xf
	v_fmac_f32_dpp v224, v244, v32 row_newbcast:8 row_mask:0xf bank_mask:0xf
	v_fmac_f32_dpp v225, v245, v33 row_newbcast:8 row_mask:0xf bank_mask:0xf
	v_fmac_f32_dpp v224, v246, v34 row_newbcast:8 row_mask:0xf bank_mask:0xf
	v_fmac_f32_dpp v225, v247, v35 row_newbcast:8 row_mask:0xf bank_mask:0xf
	v_fmac_f32_dpp v224, v244, v36 row_newbcast:9 row_mask:0xf bank_mask:0xf
	v_fmac_f32_dpp v225, v245, v37 row_newbcast:9 row_mask:0xf bank_mask:0xf
	v_fmac_f32_dpp v224, v246, v38 row_newbcast:9 row_mask:0xf bank_mask:0xf
	v_fmac_f32_dpp v225, v247, v39 row_newbcast:9 row_mask:0xf bank_mask:0xf
	v_fmac_f32_dpp v224, v244, v40 row_newbcast:10 row_mask:0xf bank_mask:0xf
	v_fmac_f32_dpp v225, v245, v41 row_newbcast:10 row_mask:0xf bank_mask:0xf
	v_fmac_f32_dpp v224, v246, v42 row_newbcast:10 row_mask:0xf bank_mask:0xf
	v_fmac_f32_dpp v225, v247, v43 row_newbcast:10 row_mask:0xf bank_mask:0xf
	v_fmac_f32_dpp v224, v244, v44 row_newbcast:11 row_mask:0xf bank_mask:0xf
	v_fmac_f32_dpp v225, v245, v45 row_newbcast:11 row_mask:0xf bank_mask:0xf
	v_fmac_f32_dpp v224, v246, v46 row_newbcast:11 row_mask:0xf bank_mask:0xf
	v_fmac_f32_dpp v225, v247, v47 row_newbcast:11 row_mask:0xf bank_mask:0xf
	v_fmac_f32_dpp v224, v244, v48 row_newbcast:12 row_mask:0xf bank_mask:0xf
	v_fmac_f32_dpp v225, v245, v49 row_newbcast:12 row_mask:0xf bank_mask:0xf
	v_fmac_f32_dpp v224, v246, v50 row_newbcast:12 row_mask:0xf bank_mask:0xf
	v_fmac_f32_dpp v225, v247, v51 row_newbcast:12 row_mask:0xf bank_mask:0xf
	v_fmac_f32_dpp v224, v244, v52 row_newbcast:13 row_mask:0xf bank_mask:0xf
	v_fmac_f32_dpp v225, v245, v53 row_newbcast:13 row_mask:0xf bank_mask:0xf
	v_fmac_f32_dpp v224, v246, v54 row_newbcast:13 row_mask:0xf bank_mask:0xf
	v_fmac_f32_dpp v225, v247, v55 row_newbcast:13 row_mask:0xf bank_mask:0xf
	v_fmac_f32_dpp v224, v244, v56 row_newbcast:14 row_mask:0xf bank_mask:0xf
	v_fmac_f32_dpp v225, v245, v57 row_newbcast:14 row_mask:0xf bank_mask:0xf
	v_fmac_f32_dpp v224, v246, v58 row_newbcast:14 row_mask:0xf bank_mask:0xf
	v_fmac_f32_dpp v225, v247, v59 row_newbcast:14 row_mask:0xf bank_mask:0xf
	v_fmac_f32_dpp v224, v244, v60 row_newbcast:15 row_mask:0xf bank_mask:0xf
	v_fmac_f32_dpp v225, v245, v61 row_newbcast:15 row_mask:0xf bank_mask:0xf
	v_fmac_f32_dpp v224, v246, v62 row_newbcast:15 row_mask:0xf bank_mask:0xf
	v_fmac_f32_dpp v225, v247, v63 row_newbcast:15 row_mask:0xf bank_mask:0xf
	v_mul_f32_dpp v228, v244, v64 row_newbcast:0 row_mask:0xf bank_mask:0xf
	v_mul_f32_dpp v229, v245, v65 row_newbcast:0 row_mask:0xf bank_mask:0xf
	v_fmac_f32_dpp v228, v246, v66 row_newbcast:0 row_mask:0xf bank_mask:0xf
	v_fmac_f32_dpp v229, v247, v67 row_newbcast:0 row_mask:0xf bank_mask:0xf
	v_fmac_f32_dpp v228, v244, v68 row_newbcast:1 row_mask:0xf bank_mask:0xf
	v_fmac_f32_dpp v229, v245, v69 row_newbcast:1 row_mask:0xf bank_mask:0xf
	v_fmac_f32_dpp v228, v246, v70 row_newbcast:1 row_mask:0xf bank_mask:0xf
	v_fmac_f32_dpp v229, v247, v71 row_newbcast:1 row_mask:0xf bank_mask:0xf
	v_fmac_f32_dpp v228, v244, v72 row_newbcast:2 row_mask:0xf bank_mask:0xf
	v_fmac_f32_dpp v229, v245, v73 row_newbcast:2 row_mask:0xf bank_mask:0xf
	v_fmac_f32_dpp v228, v246, v74 row_newbcast:2 row_mask:0xf bank_mask:0xf
	v_fmac_f32_dpp v229, v247, v75 row_newbcast:2 row_mask:0xf bank_mask:0xf
	v_fmac_f32_dpp v228, v244, v76 row_newbcast:3 row_mask:0xf bank_mask:0xf
	v_fmac_f32_dpp v229, v245, v77 row_newbcast:3 row_mask:0xf bank_mask:0xf
	v_fmac_f32_dpp v228, v246, v78 row_newbcast:3 row_mask:0xf bank_mask:0xf
	v_fmac_f32_dpp v229, v247, v79 row_newbcast:3 row_mask:0xf bank_mask:0xf
	v_fmac_f32_dpp v228, v244, v80 row_newbcast:4 row_mask:0xf bank_mask:0xf
	v_fmac_f32_dpp v229, v245, v81 row_newbcast:4 row_mask:0xf bank_mask:0xf
	v_fmac_f32_dpp v228, v246, v82 row_newbcast:4 row_mask:0xf bank_mask:0xf
	v_fmac_f32_dpp v229, v247, v83 row_newbcast:4 row_mask:0xf bank_mask:0xf
	v_fmac_f32_dpp v228, v244, v84 row_newbcast:5 row_mask:0xf bank_mask:0xf
	v_fmac_f32_dpp v229, v245, v85 row_newbcast:5 row_mask:0xf bank_mask:0xf
	v_fmac_f32_dpp v228, v246, v86 row_newbcast:5 row_mask:0xf bank_mask:0xf
;     static __device__ __forceinline__ void updS(float (&S)[64], const In1& in, float sa, float vv) {
;         float t0, t1, t2, t3;
;         asm volatile("v_mul_f32_dpp %0, %8, %21 row_newbcast:%22" DPPM "v_mul_f32_dpp %1, %9, %21 row_newbcast:%22" DPPM "v_mul_f32_dpp %2, %10, %21 row_newbcast:%22" DPPM "v_mul_f32_dpp %3, %11, %21 row_newbcast:%22" DPPM
;                      "v_fmac_f32_dpp %0, %12, %4 row_newbcast:%22" DPPM "v_fmac_f32_dpp %1, %13, %5 row_newbcast:%22" DPPM "v_fmac_f32_dpp %2, %14, %6 row_newbcast:%22" DPPM "v_fmac_f32_dpp %3, %15, %7 row_newbcast:%22" DPPM
;                      "v_fmac_f32_dpp %0, %16, %20 row_newbcast:%22" DPPM "v_fmac_f32_dpp %1, %17, %20 row_newbcast:%22" DPPM "v_fmac_f32_dpp %2, %18, %20 row_newbcast:%22" DPPM "v_fmac_f32_dpp %3, %19, %20 row_newbcast:%22" DPPM
;                      : "=&v"(t0), "=&v"(t1), "=&v"(t2), "=&v"(t3)
;                      : "v"(S[K]), "v"(S[K + 1]), "v"(S[K + 2]), "v"(S[K + 3]), "v"(in.kd[0]), "v"(in.kd[1]), "v"(in.kd[2]), "v"(in.kd[3]), "v"(in.w[0]), "v"(in.w[1]), "v"(in.w[2]), "v"(in.w[3]),
;                        "v"(in.b[0]), "v"(in.b[1]), "v"(in.b[2]), "v"(in.b[3]), "v"(sa), "v"(vv), "n"(N0));
;         S[K] = t0; S[K + 1] = t1; S[K + 2] = t2; S[K + 3] = t3;
;         if constexpr (K + 4 < 64) ScanK<K + 4>::updS(S, in, sa, vv);
;     }
;     static __device__ __forceinline__ void updP(float (&P)[64], const In1& in, float sa) {
;         float u0, u1, u2, u3;
;         asm volatile("v_mul_f32_dpp %0, %8, %4 row_newbcast:%17" DPPM "v_mul_f32_dpp %1, %9, %5 row_newbcast:%17" DPPM "v_mul_f32_dpp %2, %10, %6 row_newbcast:%17" DPPM "v_mul_f32_dpp %3, %11, %7 row_newbcast:%17" DPPM
;                      "v_fmac_f32_dpp %0, %12, %16 row_newbcast:%17" DPPM "v_fmac_f32_dpp %1, %13, %16 row_newbcast:%17" DPPM "v_fmac_f32_dpp %2, %14, %16 row_newbcast:%17" DPPM "v_fmac_f32_dpp %3, %15, %16 row_newbcast:%17" DPPM
;                      : "=&v"(u0), "=&v"(u1), "=&v"(u2), "=&v"(u3)
;                      : "v"(P[K]), "v"(P[K + 1]), "v"(P[K + 2]), "v"(P[K + 3]), "v"(in.w[0]), "v"(in.w[1]), "v"(in.w[2]), "v"(in.w[3]), "v"(in.b[0]), "v"(in.b[1]), "v"(in.b[2]), "v"(in.b[3]), "v"(sa), "n"(N0));
;         P[K] = u0; P[K + 1] = u1; P[K + 2] = u2; P[K + 3] = u3;
;         if constexpr (K + 4 < 64) ScanK<K + 4>::updP(P, in, sa);
;     }
	v_fmac_f32_dpp v229, v247, v87 row_newbcast:5 row_mask:0xf bank_mask:0xf
	v_fmac_f32_dpp v228, v244, v88 row_newbcast:6 row_mask:0xf bank_mask:0xf
	v_fmac_f32_dpp v229, v245, v89 row_newbcast:6 row_mask:0xf bank_mask:0xf
	v_fmac_f32_dpp v228, v246, v90 row_newbcast:6 row_mask:0xf bank_mask:0xf
	v_fmac_f32_dpp v229, v247, v91 row_newbcast:6 row_mask:0xf bank_mask:0xf
	v_fmac_f32_dpp v228, v244, v92 row_newbcast:7 row_mask:0xf bank_mask:0xf
	v_fmac_f32_dpp v229, v245, v93 row_newbcast:7 row_mask:0xf bank_mask:0xf
	v_fmac_f32_dpp v228, v246, v94 row_newbcast:7 row_mask:0xf bank_mask:0xf
	v_fmac_f32_dpp v229, v247, v95 row_newbcast:7 row_mask:0xf bank_mask:0xf
	v_fmac_f32_dpp v228, v244, v96 row_newbcast:8 row_mask:0xf bank_mask:0xf
	v_fmac_f32_dpp v229, v245, v97 row_newbcast:8 row_mask:0xf bank_mask:0xf
	v_fmac_f32_dpp v228, v246, v98 row_newbcast:8 row_mask:0xf bank_mask:0xf
	v_fmac_f32_dpp v229, v247, v99 row_newbcast:8 row_mask:0xf bank_mask:0xf
	v_fmac_f32_dpp v228, v244, v100 row_newbcast:9 row_mask:0xf bank_mask:0xf
	v_fmac_f32_dpp v229, v245, v101 row_newbcast:9 row_mask:0xf bank_mask:0xf
	v_fmac_f32_dpp v228, v246, v102 row_newbcast:9 row_mask:0xf bank_mask:0xf
	v_fmac_f32_dpp v229, v247, v103 row_newbcast:9 row_mask:0xf bank_mask:0xf
	v_fmac_f32_dpp v228, v244, v104 row_newbcast:10 row_mask:0xf bank_mask:0xf
	v_fmac_f32_dpp v229, v245, v105 row_newbcast:10 row_mask:0xf bank_mask:0xf
	v_fmac_f32_dpp v228, v246, v106 row_newbcast:10 row_mask:0xf bank_mask:0xf
	v_fmac_f32_dpp v229, v247, v107 row_newbcast:10 row_mask:0xf bank_mask:0xf
	v_fmac_f32_dpp v228, v244, v108 row_newbcast:11 row_mask:0xf bank_mask:0xf
	v_fmac_f32_dpp v229, v245, v109 row_newbcast:11 row_mask:0xf bank_mask:0xf
	v_fmac_f32_dpp v228, v246, v110 row_newbcast:11 row_mask:0xf bank_mask:0xf
	v_fmac_f32_dpp v229, v247, v111 row_newbcast:11 row_mask:0xf bank_mask:0xf
	v_fmac_f32_dpp v228, v244, v112 row_newbcast:12 row_mask:0xf bank_mask:0xf
	v_fmac_f32_dpp v229, v245, v113 row_newbcast:12 row_mask:0xf bank_mask:0xf
	v_fmac_f32_dpp v228, v246, v114 row_newbcast:12 row_mask:0xf bank_mask:0xf
	v_fmac_f32_dpp v229, v247, v115 row_newbcast:12 row_mask:0xf bank_mask:0xf
	v_fmac_f32_dpp v228, v244, v116 row_newbcast:13 row_mask:0xf bank_mask:0xf
	v_fmac_f32_dpp v229, v245, v117 row_newbcast:13 row_mask:0xf bank_mask:0xf
	v_fmac_f32_dpp v228, v246, v118 row_newbcast:13 row_mask:0xf bank_mask:0xf
	v_fmac_f32_dpp v229, v247, v119 row_newbcast:13 row_mask:0xf bank_mask:0xf
	v_fmac_f32_dpp v228, v244, v120 row_newbcast:14 row_mask:0xf bank_mask:0xf
	v_fmac_f32_dpp v229, v245, v121 row_newbcast:14 row_mask:0xf bank_mask:0xf
	v_fmac_f32_dpp v228, v246, v122 row_newbcast:14 row_mask:0xf bank_mask:0xf
	v_fmac_f32_dpp v229, v247, v123 row_newbcast:14 row_mask:0xf bank_mask:0xf
	v_fmac_f32_dpp v228, v244, v124 row_newbcast:15 row_mask:0xf bank_mask:0xf
	v_fmac_f32_dpp v229, v245, v125 row_newbcast:15 row_mask:0xf bank_mask:0xf
	v_fmac_f32_dpp v228, v246, v126 row_newbcast:15 row_mask:0xf bank_mask:0xf
	v_fmac_f32_dpp v229, v247, v127 row_newbcast:15 row_mask:0xf bank_mask:0xf
	v_sub_f32_e64 v232, -v224, v225
	v_sub_f32_e64 v233, -v228, v229
	s_waitcnt lgkmcnt(0)
	v_mfma_f32_4x4x1_16b_f32 v[0:3], v128, v232, v[0:3]
	v_mfma_f32_4x4x1_16b_f32 v[4:7], v129, v232, v[4:7]
	v_mfma_f32_4x4x1_16b_f32 v[8:11], v130, v232, v[8:11]
	v_mfma_f32_4x4x1_16b_f32 v[12:15], v131, v232, v[12:15]
	v_mfma_f32_4x4x1_16b_f32 v[16:19], v132, v232, v[16:19]
	v_mfma_f32_4x4x1_16b_f32 v[20:23], v133, v232, v[20:23]
	v_mfma_f32_4x4x1_16b_f32 v[24:27], v134, v232, v[24:27]
	v_mfma_f32_4x4x1_16b_f32 v[28:31], v135, v232, v[28:31]
	v_mfma_f32_4x4x1_16b_f32 v[32:35], v136, v232, v[32:35]
	v_mfma_f32_4x4x1_16b_f32 v[36:39], v137, v232, v[36:39]
	v_mfma_f32_4x4x1_16b_f32 v[40:43], v138, v232, v[40:43]
	v_mfma_f32_4x4x1_16b_f32 v[44:47], v139, v232, v[44:47]
	v_mfma_f32_4x4x1_16b_f32 v[48:51], v140, v232, v[48:51]
	v_mfma_f32_4x4x1_16b_f32 v[52:55], v141, v232, v[52:55]
	v_mfma_f32_4x4x1_16b_f32 v[56:59], v142, v232, v[56:59]
	v_mfma_f32_4x4x1_16b_f32 v[60:63], v143, v232, v[60:63]
	v_mfma_f32_4x4x1_16b_f32 v[0:3], v144, v174, v[0:3]
	v_mfma_f32_4x4x1_16b_f32 v[4:7], v145, v174, v[4:7]
	v_mfma_f32_4x4x1_16b_f32 v[8:11], v146, v174, v[8:11]
	v_mfma_f32_4x4x1_16b_f32 v[12:15], v147, v174, v[12:15]
	v_mfma_f32_4x4x1_16b_f32 v[16:19], v148, v174, v[16:19]
	v_mfma_f32_4x4x1_16b_f32 v[20:23], v149, v174, v[20:23]
	v_mfma_f32_4x4x1_16b_f32 v[24:27], v150, v174, v[24:27]
	v_mfma_f32_4x4x1_16b_f32 v[28:31], v151, v174, v[28:31]
	v_mfma_f32_4x4x1_16b_f32 v[32:35], v152, v174, v[32:35]
	v_mfma_f32_4x4x1_16b_f32 v[36:39], v153, v174, v[36:39]
	v_mfma_f32_4x4x1_16b_f32 v[40:43], v154, v174, v[40:43]
	v_mfma_f32_4x4x1_16b_f32 v[44:47], v155, v174, v[44:47]
	v_mfma_f32_4x4x1_16b_f32 v[48:51], v156, v174, v[48:51]
	v_mfma_f32_4x4x1_16b_f32 v[52:55], v157, v174, v[52:55]
	v_mfma_f32_4x4x1_16b_f32 v[56:59], v158, v174, v[56:59]
	v_mfma_f32_4x4x1_16b_f32 v[60:63], v159, v174, v[60:63]
	v_mfma_f32_4x4x1_16b_f32 v[64:67], v128, v233, v[64:67]
	v_mfma_f32_4x4x1_16b_f32 v[68:71], v129, v233, v[68:71]
	v_mfma_f32_4x4x1_16b_f32 v[72:75], v130, v233, v[72:75]
	v_mfma_f32_4x4x1_16b_f32 v[76:79], v131, v233, v[76:79]
	v_mfma_f32_4x4x1_16b_f32 v[80:83], v132, v233, v[80:83]
	v_mfma_f32_4x4x1_16b_f32 v[84:87], v133, v233, v[84:87]
	v_mfma_f32_4x4x1_16b_f32 v[88:91], v134, v233, v[88:91]
	v_mfma_f32_4x4x1_16b_f32 v[92:95], v135, v233, v[92:95]
	v_mfma_f32_4x4x1_16b_f32 v[96:99], v136, v233, v[96:99]
	v_mfma_f32_4x4x1_16b_f32 v[100:103], v137, v233, v[100:103]
	v_mfma_f32_4x4x1_16b_f32 v[104:107], v138, v233, v[104:107]
;     static __device__ __forceinline__ void updS(float (&S)[64], const In1& in, float sa, float vv) {
;         float t0, t1, t2, t3;
;         asm volatile("v_mul_f32_dpp %0, %8, %21 row_newbcast:%22" DPPM "v_mul_f32_dpp %1, %9, %21 row_newbcast:%22" DPPM "v_mul_f32_dpp %2, %10, %21 row_newbcast:%22" DPPM "v_mul_f32_dpp %3, %11, %21 row_newbcast:%22" DPPM
;                      "v_fmac_f32_dpp %0, %12, %4 row_newbcast:%22" DPPM "v_fmac_f32_dpp %1, %13, %5 row_newbcast:%22" DPPM "v_fmac_f32_dpp %2, %14, %6 row_newbcast:%22" DPPM "v_fmac_f32_dpp %3, %15, %7 row_newbcast:%22" DPPM
;                      "v_fmac_f32_dpp %0, %16, %20 row_newbcast:%22" DPPM "v_fmac_f32_dpp %1, %17, %20 row_newbcast:%22" DPPM "v_fmac_f32_dpp %2, %18, %20 row_newbcast:%22" DPPM "v_fmac_f32_dpp %3, %19, %20 row_newbcast:%22" DPPM
;                      : "=&v"(t0), "=&v"(t1), "=&v"(t2), "=&v"(t3)
;                      : "v"(S[K]), "v"(S[K + 1]), "v"(S[K + 2]), "v"(S[K + 3]), "v"(in.kd[0]), "v"(in.kd[1]), "v"(in.kd[2]), "v"(in.kd[3]), "v"(in.w[0]), "v"(in.w[1]), "v"(in.w[2]), "v"(in.w[3]),
;                        "v"(in.b[0]), "v"(in.b[1]), "v"(in.b[2]), "v"(in.b[3]), "v"(sa), "v"(vv), "n"(N0));
;         S[K] = t0; S[K + 1] = t1; S[K + 2] = t2; S[K + 3] = t3;
;         if constexpr (K + 4 < 64) ScanK<K + 4>::updS(S, in, sa, vv);
;     }
;     static __device__ __forceinline__ void updP(float (&P)[64], const In1& in, float sa) {
;         float u0, u1, u2, u3;
;         asm volatile("v_mul_f32_dpp %0, %8, %4 row_newbcast:%17" DPPM "v_mul_f32_dpp %1, %9, %5 row_newbcast:%17" DPPM "v_mul_f32_dpp %2, %10, %6 row_newbcast:%17" DPPM "v_mul_f32_dpp %3, %11, %7 row_newbcast:%17" DPPM
;                      "v_fmac_f32_dpp %0, %12, %16 row_newbcast:%17" DPPM "v_fmac_f32_dpp %1, %13, %16 row_newbcast:%17" DPPM "v_fmac_f32_dpp %2, %14, %16 row_newbcast:%17" DPPM "v_fmac_f32_dpp %3, %15, %16 row_newbcast:%17" DPPM
;                      : "=&v"(u0), "=&v"(u1), "=&v"(u2), "=&v"(u3)
;                      : "v"(P[K]), "v"(P[K + 1]), "v"(P[K + 2]), "v"(P[K + 3]), "v"(in.w[0]), "v"(in.w[1]), "v"(in.w[2]), "v"(in.w[3]), "v"(in.b[0]), "v"(in.b[1]), "v"(in.b[2]), "v"(in.b[3]), "v"(sa), "n"(N0));
;         P[K] = u0; P[K + 1] = u1; P[K + 2] = u2; P[K + 3] = u3;
;         if constexpr (K + 4 < 64) ScanK<K + 4>::updP(P, in, sa);
;     }
	v_mfma_f32_4x4x1_16b_f32 v[108:111], v139, v233, v[108:111]
	v_mfma_f32_4x4x1_16b_f32 v[112:115], v140, v233, v[112:115]
	v_mfma_f32_4x4x1_16b_f32 v[116:119], v141, v233, v[116:119]
	v_mfma_f32_4x4x1_16b_f32 v[120:123], v142, v233, v[120:123]
	v_mfma_f32_4x4x1_16b_f32 v[124:127], v143, v233, v[124:127]
	v_mul_f32_dpp v0, v236, v0 row_newbcast:0 row_mask:0xf bank_mask:0xf
	v_mul_f32_dpp v1, v237, v1 row_newbcast:0 row_mask:0xf bank_mask:0xf
	v_mul_f32_dpp v2, v238, v2 row_newbcast:0 row_mask:0xf bank_mask:0xf
	v_mul_f32_dpp v3, v239, v3 row_newbcast:0 row_mask:0xf bank_mask:0xf
	v_mul_f32_dpp v4, v236, v4 row_newbcast:1 row_mask:0xf bank_mask:0xf
	v_mul_f32_dpp v5, v237, v5 row_newbcast:1 row_mask:0xf bank_mask:0xf
	v_mul_f32_dpp v6, v238, v6 row_newbcast:1 row_mask:0xf bank_mask:0xf
	v_mul_f32_dpp v7, v239, v7 row_newbcast:1 row_mask:0xf bank_mask:0xf
	v_mul_f32_dpp v8, v236, v8 row_newbcast:2 row_mask:0xf bank_mask:0xf
	v_mul_f32_dpp v9, v237, v9 row_newbcast:2 row_mask:0xf bank_mask:0xf
	v_mul_f32_dpp v10, v238, v10 row_newbcast:2 row_mask:0xf bank_mask:0xf
	v_mul_f32_dpp v11, v239, v11 row_newbcast:2 row_mask:0xf bank_mask:0xf
	v_mul_f32_dpp v12, v236, v12 row_newbcast:3 row_mask:0xf bank_mask:0xf
	v_mul_f32_dpp v13, v237, v13 row_newbcast:3 row_mask:0xf bank_mask:0xf
	v_mul_f32_dpp v14, v238, v14 row_newbcast:3 row_mask:0xf bank_mask:0xf
	v_mul_f32_dpp v15, v239, v15 row_newbcast:3 row_mask:0xf bank_mask:0xf
	v_mul_f32_dpp v16, v236, v16 row_newbcast:4 row_mask:0xf bank_mask:0xf
	v_mul_f32_dpp v17, v237, v17 row_newbcast:4 row_mask:0xf bank_mask:0xf
	v_mul_f32_dpp v18, v238, v18 row_newbcast:4 row_mask:0xf bank_mask:0xf
	v_mul_f32_dpp v19, v239, v19 row_newbcast:4 row_mask:0xf bank_mask:0xf
	v_mul_f32_dpp v20, v236, v20 row_newbcast:5 row_mask:0xf bank_mask:0xf
	v_mul_f32_dpp v21, v237, v21 row_newbcast:5 row_mask:0xf bank_mask:0xf
	v_mul_f32_dpp v22, v238, v22 row_newbcast:5 row_mask:0xf bank_mask:0xf
	v_mul_f32_dpp v23, v239, v23 row_newbcast:5 row_mask:0xf bank_mask:0xf
	v_mul_f32_dpp v24, v236, v24 row_newbcast:6 row_mask:0xf bank_mask:0xf
	v_mul_f32_dpp v25, v237, v25 row_newbcast:6 row_mask:0xf bank_mask:0xf
	v_mul_f32_dpp v26, v238, v26 row_newbcast:6 row_mask:0xf bank_mask:0xf
	v_mul_f32_dpp v27, v239, v27 row_newbcast:6 row_mask:0xf bank_mask:0xf
	v_mul_f32_dpp v28, v236, v28 row_newbcast:7 row_mask:0xf bank_mask:0xf
	v_mul_f32_dpp v29, v237, v29 row_newbcast:7 row_mask:0xf bank_mask:0xf
	v_mul_f32_dpp v30, v238, v30 row_newbcast:7 row_mask:0xf bank_mask:0xf
	v_mul_f32_dpp v31, v239, v31 row_newbcast:7 row_mask:0xf bank_mask:0xf
	v_mul_f32_dpp v32, v236, v32 row_newbcast:8 row_mask:0xf bank_mask:0xf
	v_mul_f32_dpp v33, v237, v33 row_newbcast:8 row_mask:0xf bank_mask:0xf
	v_mul_f32_dpp v34, v238, v34 row_newbcast:8 row_mask:0xf bank_mask:0xf
	v_mul_f32_dpp v35, v239, v35 row_newbcast:8 row_mask:0xf bank_mask:0xf
	v_mul_f32_dpp v36, v236, v36 row_newbcast:9 row_mask:0xf bank_mask:0xf
	v_mul_f32_dpp v37, v237, v37 row_newbcast:9 row_mask:0xf bank_mask:0xf
	v_mul_f32_dpp v38, v238, v38 row_newbcast:9 row_mask:0xf bank_mask:0xf
	v_mul_f32_dpp v39, v239, v39 row_newbcast:9 row_mask:0xf bank_mask:0xf
	v_mul_f32_dpp v40, v236, v40 row_newbcast:10 row_mask:0xf bank_mask:0xf
	v_mul_f32_dpp v41, v237, v41 row_newbcast:10 row_mask:0xf bank_mask:0xf
	v_mul_f32_dpp v42, v238, v42 row_newbcast:10 row_mask:0xf bank_mask:0xf
	v_mul_f32_dpp v43, v239, v43 row_newbcast:10 row_mask:0xf bank_mask:0xf
	v_mul_f32_dpp v44, v236, v44 row_newbcast:11 row_mask:0xf bank_mask:0xf
	v_mul_f32_dpp v45, v237, v45 row_newbcast:11 row_mask:0xf bank_mask:0xf
	v_mul_f32_dpp v46, v238, v46 row_newbcast:11 row_mask:0xf bank_mask:0xf
	v_mul_f32_dpp v47, v239, v47 row_newbcast:11 row_mask:0xf bank_mask:0xf
	v_mul_f32_dpp v48, v236, v48 row_newbcast:12 row_mask:0xf bank_mask:0xf
	v_mul_f32_dpp v49, v237, v49 row_newbcast:12 row_mask:0xf bank_mask:0xf
	v_mul_f32_dpp v50, v238, v50 row_newbcast:12 row_mask:0xf bank_mask:0xf
	v_mul_f32_dpp v51, v239, v51 row_newbcast:12 row_mask:0xf bank_mask:0xf
	v_mul_f32_dpp v52, v236, v52 row_newbcast:13 row_mask:0xf bank_mask:0xf
	v_mul_f32_dpp v53, v237, v53 row_newbcast:13 row_mask:0xf bank_mask:0xf
	v_mul_f32_dpp v54, v238, v54 row_newbcast:13 row_mask:0xf bank_mask:0xf
	v_mul_f32_dpp v55, v239, v55 row_newbcast:13 row_mask:0xf bank_mask:0xf
	v_mul_f32_dpp v56, v236, v56 row_newbcast:14 row_mask:0xf bank_mask:0xf
	v_mul_f32_dpp v57, v237, v57 row_newbcast:14 row_mask:0xf bank_mask:0xf
	v_mul_f32_dpp v58, v238, v58 row_newbcast:14 row_mask:0xf bank_mask:0xf
	v_mul_f32_dpp v59, v239, v59 row_newbcast:14 row_mask:0xf bank_mask:0xf
	v_mul_f32_dpp v60, v236, v60 row_newbcast:15 row_mask:0xf bank_mask:0xf
	v_mul_f32_dpp v61, v237, v61 row_newbcast:15 row_mask:0xf bank_mask:0xf
	v_mul_f32_dpp v62, v238, v62 row_newbcast:15 row_mask:0xf bank_mask:0xf
	v_mul_f32_dpp v63, v239, v63 row_newbcast:15 row_mask:0xf bank_mask:0xf
	v_mul_f32_dpp v64, v236, v64 row_newbcast:0 row_mask:0xf bank_mask:0xf
	v_mul_f32_dpp v65, v237, v65 row_newbcast:0 row_mask:0xf bank_mask:0xf
	v_mul_f32_dpp v66, v238, v66 row_newbcast:0 row_mask:0xf bank_mask:0xf
	v_mul_f32_dpp v67, v239, v67 row_newbcast:0 row_mask:0xf bank_mask:0xf
	v_mul_f32_dpp v68, v236, v68 row_newbcast:1 row_mask:0xf bank_mask:0xf
	v_mul_f32_dpp v69, v237, v69 row_newbcast:1 row_mask:0xf bank_mask:0xf
	v_mul_f32_dpp v70, v238, v70 row_newbcast:1 row_mask:0xf bank_mask:0xf
	v_mul_f32_dpp v71, v239, v71 row_newbcast:1 row_mask:0xf bank_mask:0xf
	v_mul_f32_dpp v72, v236, v72 row_newbcast:2 row_mask:0xf bank_mask:0xf
	v_mul_f32_dpp v73, v237, v73 row_newbcast:2 row_mask:0xf bank_mask:0xf
;     static __device__ __forceinline__ void updS(float (&S)[64], const In1& in, float sa, float vv) {
;         float t0, t1, t2, t3;
;         asm volatile("v_mul_f32_dpp %0, %8, %21 row_newbcast:%22" DPPM "v_mul_f32_dpp %1, %9, %21 row_newbcast:%22" DPPM "v_mul_f32_dpp %2, %10, %21 row_newbcast:%22" DPPM "v_mul_f32_dpp %3, %11, %21 row_newbcast:%22" DPPM
;                      "v_fmac_f32_dpp %0, %12, %4 row_newbcast:%22" DPPM "v_fmac_f32_dpp %1, %13, %5 row_newbcast:%22" DPPM "v_fmac_f32_dpp %2, %14, %6 row_newbcast:%22" DPPM "v_fmac_f32_dpp %3, %15, %7 row_newbcast:%22" DPPM
;                      "v_fmac_f32_dpp %0, %16, %20 row_newbcast:%22" DPPM "v_fmac_f32_dpp %1, %17, %20 row_newbcast:%22" DPPM "v_fmac_f32_dpp %2, %18, %20 row_newbcast:%22" DPPM "v_fmac_f32_dpp %3, %19, %20 row_newbcast:%22" DPPM
;                      : "=&v"(t0), "=&v"(t1), "=&v"(t2), "=&v"(t3)
;                      : "v"(S[K]), "v"(S[K + 1]), "v"(S[K + 2]), "v"(S[K + 3]), "v"(in.kd[0]), "v"(in.kd[1]), "v"(in.kd[2]), "v"(in.kd[3]), "v"(in.w[0]), "v"(in.w[1]), "v"(in.w[2]), "v"(in.w[3]),
;                        "v"(in.b[0]), "v"(in.b[1]), "v"(in.b[2]), "v"(in.b[3]), "v"(sa), "v"(vv), "n"(N0));
;         S[K] = t0; S[K + 1] = t1; S[K + 2] = t2; S[K + 3] = t3;
;         if constexpr (K + 4 < 64) ScanK<K + 4>::updS(S, in, sa, vv);
;     }
;     static __device__ __forceinline__ void updP(float (&P)[64], const In1& in, float sa) {
;         float u0, u1, u2, u3;
;         asm volatile("v_mul_f32_dpp %0, %8, %4 row_newbcast:%17" DPPM "v_mul_f32_dpp %1, %9, %5 row_newbcast:%17" DPPM "v_mul_f32_dpp %2, %10, %6 row_newbcast:%17" DPPM "v_mul_f32_dpp %3, %11, %7 row_newbcast:%17" DPPM
;                      "v_fmac_f32_dpp %0, %12, %16 row_newbcast:%17" DPPM "v_fmac_f32_dpp %1, %13, %16 row_newbcast:%17" DPPM "v_fmac_f32_dpp %2, %14, %16 row_newbcast:%17" DPPM "v_fmac_f32_dpp %3, %15, %16 row_newbcast:%17" DPPM
;                      : "=&v"(u0), "=&v"(u1), "=&v"(u2), "=&v"(u3)
;                      : "v"(P[K]), "v"(P[K + 1]), "v"(P[K + 2]), "v"(P[K + 3]), "v"(in.w[0]), "v"(in.w[1]), "v"(in.w[2]), "v"(in.w[3]), "v"(in.b[0]), "v"(in.b[1]), "v"(in.b[2]), "v"(in.b[3]), "v"(sa), "n"(N0));
;         P[K] = u0; P[K + 1] = u1; P[K + 2] = u2; P[K + 3] = u3;
;         if constexpr (K + 4 < 64) ScanK<K + 4>::updP(P, in, sa);
;     }
	v_mul_f32_dpp v74, v238, v74 row_newbcast:2 row_mask:0xf bank_mask:0xf
	v_mul_f32_dpp v75, v239, v75 row_newbcast:2 row_mask:0xf bank_mask:0xf
	v_mul_f32_dpp v76, v236, v76 row_newbcast:3 row_mask:0xf bank_mask:0xf
	v_mul_f32_dpp v77, v237, v77 row_newbcast:3 row_mask:0xf bank_mask:0xf
	v_mul_f32_dpp v78, v238, v78 row_newbcast:3 row_mask:0xf bank_mask:0xf
	v_mul_f32_dpp v79, v239, v79 row_newbcast:3 row_mask:0xf bank_mask:0xf
	v_mul_f32_dpp v80, v236, v80 row_newbcast:4 row_mask:0xf bank_mask:0xf
	v_mul_f32_dpp v81, v237, v81 row_newbcast:4 row_mask:0xf bank_mask:0xf
	v_mul_f32_dpp v82, v238, v82 row_newbcast:4 row_mask:0xf bank_mask:0xf
	v_mul_f32_dpp v83, v239, v83 row_newbcast:4 row_mask:0xf bank_mask:0xf
	v_mul_f32_dpp v84, v236, v84 row_newbcast:5 row_mask:0xf bank_mask:0xf
	v_mul_f32_dpp v85, v237, v85 row_newbcast:5 row_mask:0xf bank_mask:0xf
	v_mul_f32_dpp v86, v238, v86 row_newbcast:5 row_mask:0xf bank_mask:0xf
	v_mul_f32_dpp v87, v239, v87 row_newbcast:5 row_mask:0xf bank_mask:0xf
	v_mul_f32_dpp v88, v236, v88 row_newbcast:6 row_mask:0xf bank_mask:0xf
	v_mul_f32_dpp v89, v237, v89 row_newbcast:6 row_mask:0xf bank_mask:0xf
	v_mul_f32_dpp v90, v238, v90 row_newbcast:6 row_mask:0xf bank_mask:0xf
	v_mul_f32_dpp v91, v239, v91 row_newbcast:6 row_mask:0xf bank_mask:0xf
	v_mul_f32_dpp v92, v236, v92 row_newbcast:7 row_mask:0xf bank_mask:0xf
	v_mul_f32_dpp v93, v237, v93 row_newbcast:7 row_mask:0xf bank_mask:0xf
	v_mul_f32_dpp v94, v238, v94 row_newbcast:7 row_mask:0xf bank_mask:0xf
	v_mul_f32_dpp v95, v239, v95 row_newbcast:7 row_mask:0xf bank_mask:0xf
	v_mul_f32_dpp v96, v236, v96 row_newbcast:8 row_mask:0xf bank_mask:0xf
	v_mul_f32_dpp v97, v237, v97 row_newbcast:8 row_mask:0xf bank_mask:0xf
	v_mul_f32_dpp v98, v238, v98 row_newbcast:8 row_mask:0xf bank_mask:0xf
	v_mul_f32_dpp v99, v239, v99 row_newbcast:8 row_mask:0xf bank_mask:0xf
	v_mul_f32_dpp v100, v236, v100 row_newbcast:9 row_mask:0xf bank_mask:0xf
	v_mul_f32_dpp v101, v237, v101 row_newbcast:9 row_mask:0xf bank_mask:0xf
	v_mul_f32_dpp v102, v238, v102 row_newbcast:9 row_mask:0xf bank_mask:0xf
	v_mul_f32_dpp v103, v239, v103 row_newbcast:9 row_mask:0xf bank_mask:0xf
	v_mul_f32_dpp v104, v236, v104 row_newbcast:10 row_mask:0xf bank_mask:0xf
	v_mul_f32_dpp v105, v237, v105 row_newbcast:10 row_mask:0xf bank_mask:0xf
	v_mul_f32_dpp v106, v238, v106 row_newbcast:10 row_mask:0xf bank_mask:0xf
	v_mul_f32_dpp v107, v239, v107 row_newbcast:10 row_mask:0xf bank_mask:0xf
	v_mul_f32_dpp v108, v236, v108 row_newbcast:11 row_mask:0xf bank_mask:0xf
	v_mul_f32_dpp v109, v237, v109 row_newbcast:11 row_mask:0xf bank_mask:0xf
	v_mul_f32_dpp v110, v238, v110 row_newbcast:11 row_mask:0xf bank_mask:0xf
	v_mul_f32_dpp v111, v239, v111 row_newbcast:11 row_mask:0xf bank_mask:0xf
	v_mul_f32_dpp v112, v236, v112 row_newbcast:12 row_mask:0xf bank_mask:0xf
	v_mul_f32_dpp v113, v237, v113 row_newbcast:12 row_mask:0xf bank_mask:0xf
	v_mul_f32_dpp v114, v238, v114 row_newbcast:12 row_mask:0xf bank_mask:0xf
	v_mul_f32_dpp v115, v239, v115 row_newbcast:12 row_mask:0xf bank_mask:0xf
	v_mul_f32_dpp v116, v236, v116 row_newbcast:13 row_mask:0xf bank_mask:0xf
	v_mul_f32_dpp v117, v237, v117 row_newbcast:13 row_mask:0xf bank_mask:0xf
	v_mul_f32_dpp v118, v238, v118 row_newbcast:13 row_mask:0xf bank_mask:0xf
	v_mul_f32_dpp v119, v239, v119 row_newbcast:13 row_mask:0xf bank_mask:0xf
	v_mul_f32_dpp v120, v236, v120 row_newbcast:14 row_mask:0xf bank_mask:0xf
	v_mul_f32_dpp v121, v237, v121 row_newbcast:14 row_mask:0xf bank_mask:0xf
	v_mul_f32_dpp v122, v238, v122 row_newbcast:14 row_mask:0xf bank_mask:0xf
	v_mul_f32_dpp v123, v239, v123 row_newbcast:14 row_mask:0xf bank_mask:0xf
	v_mul_f32_dpp v124, v236, v124 row_newbcast:15 row_mask:0xf bank_mask:0xf
	v_mul_f32_dpp v125, v237, v125 row_newbcast:15 row_mask:0xf bank_mask:0xf
	v_mul_f32_dpp v126, v238, v126 row_newbcast:15 row_mask:0xf bank_mask:0xf
	v_mul_f32_dpp v127, v239, v127 row_newbcast:15 row_mask:0xf bank_mask:0xf
	v_mov_b32_e32 v236, 1.0
	v_mov_b32_e32 v237, 1.0
	v_mov_b32_e32 v238, 1.0
	v_mov_b32_e32 v239, 1.0
	s_waitcnt vmcnt(0)
; #define NEXT_ITEM() (MIX ? (int)__builtin_amdgcn_readfirstlane(lane == 0 ? __hip_atomic_fetch_add(qctr, 1u, __ATOMIC_RELAXED, __HIP_MEMORY_SCOPE_AGENT) : 0u) : item + (int)gridDim.x * 8)
; template <bool MIX> __device__ __forceinline__ void scan_pass1(const Params& p, int d, float* ldsf) {
;     ...
;     for (int item = MIX ? NEXT_ITEM() : (int)(blockIdx.x * 8 + wid); item < 2 * NS; item = NEXT_ITEM()) {
;     ...
;         float* po = (isP ? PT : SLT) + ((size_t)(bh * NC + c)) * 4096 + lane * 64;
; #pragma unroll
;         for (int i = 0; i < 16; ++i) *(f32x4*)(po + 4 * i) = (f32x4){S[4 * i], S[4 * i + 1], S[4 * i + 2], S[4 * i + 3]};
	s_nop 1
	v_and_b32_e32 v128, 63, v254
	v_lshlrev_b32_e32 v129, 8, v128
	v_lshlrev_b32_e32 v130, 2, v128
	global_store_dwordx4 v129, v[0:3], s[90:91] offset:0
	global_store_dwordx4 v129, v[4:7], s[90:91] offset:16
	global_store_dwordx4 v129, v[8:11], s[90:91] offset:32
	global_store_dwordx4 v129, v[12:15], s[90:91] offset:48
	global_store_dwordx4 v129, v[16:19], s[90:91] offset:64
	global_store_dwordx4 v129, v[20:23], s[90:91] offset:80
	global_store_dwordx4 v129, v[24:27], s[90:91] offset:96
	global_store_dwordx4 v129, v[28:31], s[90:91] offset:112
	global_store_dwordx4 v129, v[32:35], s[90:91] offset:128
	global_store_dwordx4 v129, v[36:39], s[90:91] offset:144
	global_store_dwordx4 v129, v[40:43], s[90:91] offset:160
	global_store_dwordx4 v129, v[44:47], s[90:91] offset:176
	global_store_dwordx4 v129, v[48:51], s[90:91] offset:192
	global_store_dwordx4 v129, v[52:55], s[90:91] offset:208
	global_store_dwordx4 v129, v[56:59], s[90:91] offset:224
	global_store_dwordx4 v129, v[60:63], s[90:91] offset:240
	global_store_dword v130, v64, s[92:93] offset:0
	global_store_dword v130, v65, s[92:93] offset:256
	global_store_dword v130, v66, s[92:93] offset:512
	global_store_dword v130, v67, s[92:93] offset:768
	global_store_dword v130, v68, s[92:93] offset:1024
	global_store_dword v130, v69, s[92:93] offset:1280
	global_store_dword v130, v70, s[92:93] offset:1536
	global_store_dword v130, v71, s[92:93] offset:1792
	global_store_dword v130, v72, s[92:93] offset:2048
	global_store_dword v130, v73, s[92:93] offset:2304
	global_store_dword v130, v74, s[92:93] offset:2560
	global_store_dword v130, v75, s[92:93] offset:2816
	global_store_dword v130, v76, s[92:93] offset:3072
	global_store_dword v130, v77, s[92:93] offset:3328
	global_store_dword v130, v78, s[92:93] offset:3584
	global_store_dword v130, v79, s[92:93] offset:3840
	s_add_u32 s92, s92, 0x1000
	s_addc_u32 s93, s93, 0
	global_store_dword v130, v80, s[92:93] offset:0
	global_store_dword v130, v81, s[92:93] offset:256
	global_store_dword v130, v82, s[92:93] offset:512
	global_store_dword v130, v83, s[92:93] offset:768
	global_store_dword v130, v84, s[92:93] offset:1024
	global_store_dword v130, v85, s[92:93] offset:1280
	global_store_dword v130, v86, s[92:93] offset:1536
	global_store_dword v130, v87, s[92:93] offset:1792
	global_store_dword v130, v88, s[92:93] offset:2048
	global_store_dword v130, v89, s[92:93] offset:2304
	global_store_dword v130, v90, s[92:93] offset:2560
	global_store_dword v130, v91, s[92:93] offset:2816
	global_store_dword v130, v92, s[92:93] offset:3072
	global_store_dword v130, v93, s[92:93] offset:3328
	global_store_dword v130, v94, s[92:93] offset:3584
	global_store_dword v130, v95, s[92:93] offset:3840
	s_add_u32 s92, s92, 0x1000
	s_addc_u32 s93, s93, 0
	global_store_dword v130, v96, s[92:93] offset:0
	global_store_dword v130, v97, s[92:93] offset:256
	global_store_dword v130, v98, s[92:93] offset:512
	global_store_dword v130, v99, s[92:93] offset:768
	global_store_dword v130, v100, s[92:93] offset:1024
	global_store_dword v130, v101, s[92:93] offset:1280
	global_store_dword v130, v102, s[92:93] offset:1536
	global_store_dword v130, v103, s[92:93] offset:1792
	global_store_dword v130, v104, s[92:93] offset:2048
	global_store_dword v130, v105, s[92:93] offset:2304
	global_store_dword v130, v106, s[92:93] offset:2560
	global_store_dword v130, v107, s[92:93] offset:2816
	global_store_dword v130, v108, s[92:93] offset:3072
	global_store_dword v130, v109, s[92:93] offset:3328
	global_store_dword v130, v110, s[92:93] offset:3584
	global_store_dword v130, v111, s[92:93] offset:3840
	s_add_u32 s92, s92, 0x1000
	s_addc_u32 s93, s93, 0
	global_store_dword v130, v112, s[92:93] offset:0
	global_store_dword v130, v113, s[92:93] offset:256
	global_store_dword v130, v114, s[92:93] offset:512
	global_store_dword v130, v115, s[92:93] offset:768
	global_store_dword v130, v116, s[92:93] offset:1024
	global_store_dword v130, v117, s[92:93] offset:1280
	global_store_dword v130, v118, s[92:93] offset:1536
	global_store_dword v130, v119, s[92:93] offset:1792
	global_store_dword v130, v120, s[92:93] offset:2048
	global_store_dword v130, v121, s[92:93] offset:2304
	global_store_dword v130, v122, s[92:93] offset:2560
	global_store_dword v130, v123, s[92:93] offset:2816
	global_store_dword v130, v124, s[92:93] offset:3072
	global_store_dword v130, v125, s[92:93] offset:3328
	global_store_dword v130, v126, s[92:93] offset:3584
	global_store_dword v130, v127, s[92:93] offset:3840
	s_nop 1
	s_lshl_b32 s6, s96, 3
	s_add_i32 s0, s0, s6
	s_branch .Lmy_p1d1_item
